# code placement: the five GEMM K-loops whose MFMAs sat at 0 mod 8 (P3, P8 proj_a, P9, P10, P13) shifted by 4 bytes to the phase the other three already have; P5 step loop shifted too (v_p5al)
# speedup vs baseline: 1.0040x; 1.0040x over previous
; #define PG8_STAGE(bufoff, gbase, voff) do { _Pragma("unroll") for (int _i = 0; _i < 2; ++_i) \
;         __builtin_amdgcn_global_load_lds((const unsigned*)((const char*)(gbase) + (voff)[_i]), (PG8_LAS unsigned*)(lds + (bufoff) + ldsw + _i * 8192), 16, 0, 0); } while (0)
; #define PG8_LDA(dst, b, h) do { _Pragma("unroll") for (int m = 0; m < 4; ++m) _Pragma("unroll") for (int k = 0; k < 2; ++k) dst[m][k] = *(const PG8_LAS bf16x8*)(lds + PG8_SA(b, h) + aoff + m * 2048 + k * 1024); } while (0)
; #define PG8_LDB(dst, b, h) do { _Pragma("unroll") for (int n = 0; n < 2; ++n) _Pragma("unroll") for (int k = 0; k < 2; ++k) dst[n][k] = *(const PG8_LAS bf16x8*)(lds + PG8_SB(b, h) + boff + n * 2048 + k * 1024); } while (0)
; #define PG8_MMA(ai, bj, At, Bt) do { __builtin_amdgcn_s_setprio(1); _Pragma("unroll") for (int m = 0; m < 4; ++m) _Pragma("unroll") for (int n = 0; n < 2; ++n) _Pragma("unroll") for (int k = 0; k < 2; ++k) \
;         acc[ai][bj][m][n] = __builtin_amdgcn_mfma_f32_16x16x32_bf16(Bt[n][k], At[m][k], acc[ai][bj][m][n], 0, 0, 0); __builtin_amdgcn_s_setprio(0); } while (0)
; #define PG8_WAIT_V(n) asm volatile("s_waitcnt vmcnt(" #n ")" ::: "memory")
; #define PG8_WAIT_L(n) asm volatile("s_waitcnt lgkmcnt(" #n ")" ::: "memory")
; #define PG8_BAR __builtin_amdgcn_s_barrier()
; #define PG8_SCHED __builtin_amdgcn_sched_barrier(0)
; template <class Epi, class Sched, bool ALIGN_EPI = false, bool SP2 = false>
; __device__ __forceinline__ void gemm_phase(PG8_LAS unsigned char* lds, const Gemm g, const Sched& S, const Epi& E) {
;     ...
;             PG8_LDB(B0, 0, 0); PG8_LDB(B1, 0, 1); PG8_SCHED; PG8_LDA(At, 0, 0); PG8_STAGE(PG8_SA(1, 1), a1 + hstep, voffA);
;             PG8_WAIT_V(8); PG8_WAIT_L(0); PG8_BAR; PG8_MMA(0, 0, At, B0); PG8_MMA(0, 1, At, B1); PG8_BAR; PG8_SCHED;
;     ...
; #pragma unroll
;         for (int a = 0; a < 2; ++a)
; #pragma unroll
;             for (int b = 0; b < 2; ++b)
; #pragma unroll
;                 for (int m = 0; m < 4; ++m)
; #pragma unroll
;                     for (int n = 0; n < 2; ++n) acc[a][b][m][n] = (f32x4){0.f, 0.f, 0.f, 0.f};
;         cur = nxt; cA = nA; cB = nB; ++ui;
;         if constexpr (ALIGN_EPI) { if (wr == 1) PG8_BAR; }
.LBB0_917:
	v_mov_b32_e32 v123, 0
	s_andn2_b64 vcc, exec, s[66:67]
	v_mov_b32_e32 v122, v123
	v_mov_b32_e32 v121, v123
	v_mov_b32_e32 v120, v123
	v_mov_b32_e32 v127, v123
	v_mov_b32_e32 v126, v123
	v_mov_b32_e32 v125, v123
	v_mov_b32_e32 v124, v123
	v_mov_b32_e32 v111, v123
	v_mov_b32_e32 v110, v123
	v_mov_b32_e32 v109, v123
	v_mov_b32_e32 v108, v123
	v_mov_b32_e32 v107, v123
	v_mov_b32_e32 v106, v123
	v_mov_b32_e32 v105, v123
	v_mov_b32_e32 v104, v123
	v_mov_b32_e32 v95, v123
	v_mov_b32_e32 v94, v123
	v_mov_b32_e32 v93, v123
	v_mov_b32_e32 v92, v123
	v_mov_b32_e32 v91, v123
	v_mov_b32_e32 v90, v123
	v_mov_b32_e32 v89, v123
	v_mov_b32_e32 v88, v123
	v_mov_b32_e32 v79, v123
	v_mov_b32_e32 v78, v123
	v_mov_b32_e32 v77, v123
	v_mov_b32_e32 v76, v123
	v_mov_b32_e32 v75, v123
	v_mov_b32_e32 v74, v123
	v_mov_b32_e32 v73, v123
	v_mov_b32_e32 v72, v123
	v_mov_b32_e32 v119, v123
	v_mov_b32_e32 v118, v123
	v_mov_b32_e32 v117, v123
	v_mov_b32_e32 v116, v123
	v_mov_b32_e32 v115, v123
	v_mov_b32_e32 v114, v123
	v_mov_b32_e32 v113, v123
	v_mov_b32_e32 v112, v123
	v_mov_b32_e32 v103, v123
	v_mov_b32_e32 v102, v123
	v_mov_b32_e32 v101, v123
	v_mov_b32_e32 v100, v123
	v_mov_b32_e32 v99, v123
	v_mov_b32_e32 v98, v123
	v_mov_b32_e32 v97, v123
	v_mov_b32_e32 v96, v123
	v_mov_b32_e32 v87, v123
	v_mov_b32_e32 v86, v123
	v_mov_b32_e32 v85, v123
	v_mov_b32_e32 v84, v123
	v_mov_b32_e32 v83, v123
	v_mov_b32_e32 v82, v123
	v_mov_b32_e32 v81, v123
	v_mov_b32_e32 v80, v123
	v_mov_b32_e32 v71, v123
	v_mov_b32_e32 v70, v123
	v_mov_b32_e32 v69, v123
	v_mov_b32_e32 v68, v123
	v_mov_b32_e32 v67, v123
	v_mov_b32_e32 v66, v123
	v_mov_b32_e32 v65, v123
	v_mov_b32_e32 v64, v123
	v_mov_b32_e32 v63, v123
	v_mov_b32_e32 v62, v123
	v_mov_b32_e32 v61, v123
	v_mov_b32_e32 v60, v123
	v_mov_b32_e32 v59, v123
	v_mov_b32_e32 v58, v123
	v_mov_b32_e32 v57, v123
	v_mov_b32_e32 v56, v123
	v_mov_b32_e32 v47, v123
	v_mov_b32_e32 v46, v123
	v_mov_b32_e32 v45, v123
	v_mov_b32_e32 v44, v123
	v_mov_b32_e32 v43, v123
	v_mov_b32_e32 v42, v123
	v_mov_b32_e32 v41, v123
	v_mov_b32_e32 v40, v123
	v_mov_b32_e32 v31, v123
	v_mov_b32_e32 v30, v123
	v_mov_b32_e32 v29, v123
	v_mov_b32_e32 v28, v123
	v_mov_b32_e32 v27, v123
	v_mov_b32_e32 v26, v123
	v_mov_b32_e32 v25, v123
	v_mov_b32_e32 v24, v123
	v_mov_b32_e32 v15, v123
	v_mov_b32_e32 v14, v123
	v_mov_b32_e32 v13, v123
	v_mov_b32_e32 v12, v123
	v_mov_b32_e32 v11, v123
	v_mov_b32_e32 v10, v123
	v_mov_b32_e32 v9, v123
	v_mov_b32_e32 v8, v123
	v_mov_b32_e32 v55, v123
	v_mov_b32_e32 v54, v123
	v_mov_b32_e32 v53, v123
	v_mov_b32_e32 v52, v123
	v_mov_b32_e32 v51, v123
	v_mov_b32_e32 v50, v123
	v_mov_b32_e32 v49, v123
	v_mov_b32_e32 v48, v123
	v_mov_b32_e32 v39, v123
	v_mov_b32_e32 v38, v123
	v_mov_b32_e32 v37, v123
	v_mov_b32_e32 v36, v123
	v_mov_b32_e32 v35, v123
	v_mov_b32_e32 v34, v123
	v_mov_b32_e32 v33, v123
	v_mov_b32_e32 v32, v123
	v_mov_b32_e32 v23, v123
	v_mov_b32_e32 v22, v123
	v_mov_b32_e32 v21, v123
	v_mov_b32_e32 v20, v123
	v_mov_b32_e32 v19, v123
	v_mov_b32_e32 v18, v123
	v_mov_b32_e32 v17, v123
	v_mov_b32_e32 v16, v123
	v_mov_b32_e32 v7, v123
	v_mov_b32_e32 v6, v123
	v_mov_b32_e32 v5, v123
	v_mov_b32_e32 v4, v123
	v_mov_b32_e32 v3, v123
	v_mov_b32_e32 v2, v123
	v_mov_b32_e32 v1, v123
	v_mov_b32_e32 v0, v123
	s_cbranch_vccnz .LBB0_920
	s_add_u32 s0, s0, 0x80
	s_addc_u32 s1, s1, 0
	s_add_u32 s44, s72, 0x100
	s_addc_u32 s45, s73, 0
	s_mov_b32 s6, 0
	s_nop 0
	ds_read_b128 v[128:131], v187
	ds_read_b128 v[132:135], v187 offset:1024
	ds_read_b128 v[154:157], v187 offset:2048
	ds_read_b128 v[158:161], v187 offset:3072
	ds_read_b128 v[162:165], v188
	ds_read_b128 v[166:169], v188 offset:1024
	ds_read_b128 v[170:173], v188 offset:2048
	ds_read_b128 v[174:177], v188 offset:3072
	s_add_i32 s46, s6, 2
	s_add_u32 s47, s0, 0x80
	s_addc_u32 s7, s1, 0
	s_cmp_eq_u32 s93, s6
	s_cselect_b32 s6, s16, s47
	s_cselect_b32 s7, s17, s7
	s_cselect_b32 s49, s19, s45
	s_cselect_b32 s48, s18, s44
	v_lshl_add_u64 v[182:183], s[0:1], 0, v[146:147]
	s_add_i32 m0, s85, 0xc000
	ds_read_b128 v[178:181], v189
	ds_read_b128 v[192:195], v189 offset:1024
	ds_read_b128 v[196:199], v189 offset:2048
	ds_read_b128 v[200:203], v189 offset:3072
	ds_read_b128 v[204:207], v189 offset:4096
	ds_read_b128 v[208:211], v189 offset:5120
	ds_read_b128 v[212:215], v189 offset:6144
	ds_read_b128 v[216:219], v189 offset:7168
	global_load_lds_dwordx4 v[182:183], off
	v_lshl_add_u64 v[182:183], s[0:1], 0, v[148:149]
	s_add_i32 m0, s85, 0xe000
	s_nop 0
	global_load_lds_dwordx4 v[182:183], off
	s_waitcnt vmcnt(8)
	s_waitcnt lgkmcnt(0)
	s_barrier
; #define PG8_STAGE(bufoff, gbase, voff) do { _Pragma("unroll") for (int _i = 0; _i < 2; ++_i) \
;         __builtin_amdgcn_global_load_lds((const unsigned*)((const char*)(gbase) + (voff)[_i]), (PG8_LAS unsigned*)(lds + (bufoff) + ldsw + _i * 8192), 16, 0, 0); } while (0)
; #define PG8_LDA(dst, b, h) do { _Pragma("unroll") for (int m = 0; m < 4; ++m) _Pragma("unroll") for (int k = 0; k < 2; ++k) dst[m][k] = *(const PG8_LAS bf16x8*)(lds + PG8_SA(b, h) + aoff + m * 2048 + k * 1024); } while (0)
; #define PG8_MMA(ai, bj, At, Bt) do { __builtin_amdgcn_s_setprio(1); _Pragma("unroll") for (int m = 0; m < 4; ++m) _Pragma("unroll") for (int n = 0; n < 2; ++n) _Pragma("unroll") for (int k = 0; k < 2; ++k) \
;         acc[ai][bj][m][n] = __builtin_amdgcn_mfma_f32_16x16x32_bf16(Bt[n][k], At[m][k], acc[ai][bj][m][n], 0, 0, 0); __builtin_amdgcn_s_setprio(0); } while (0)
; #define PG8_WAIT_V(n) asm volatile("s_waitcnt vmcnt(" #n ")" ::: "memory")
; #define PG8_WAIT_L(n) asm volatile("s_waitcnt lgkmcnt(" #n ")" ::: "memory")
; #define PG8_BAR __builtin_amdgcn_s_barrier()
; #define PG8_SCHED __builtin_amdgcn_sched_barrier(0)
; template <class Epi, class Sched, bool ALIGN_EPI = false, bool SP2 = false>
; __device__ __forceinline__ void gemm_phase(PG8_LAS unsigned char* lds, const Gemm g, const Sched& S, const Epi& E) {
;     ...
;             PG8_WAIT_V(8); PG8_WAIT_L(0); PG8_BAR; PG8_MMA(0, 0, At, B0); PG8_MMA(0, 1, At, B1); PG8_BAR; PG8_SCHED;
;             PG8_LDA(At, 0, 1); PG8_STAGE(PG8_SB(0, 0), b2, voffB); PG8_STAGE(PG8_SB(0, 1), b2 + hstep, voffB); PG8_STAGE(PG8_SA(0, 0), a2, voffA);
;             PG8_WAIT_V(8); PG8_WAIT_L(0); PG8_BAR; PG8_MMA(1, 0, At, B0); PG8_MMA(1, 1, At, B1); PG8_BAR; PG8_SCHED;
	s_setprio 1
	v_mfma_f32_16x16x32_bf16 v[120:123], v[128:131], v[178:181], 0
	v_mfma_f32_16x16x32_bf16 v[124:127], v[154:157], v[178:181], 0
	v_mfma_f32_16x16x32_bf16 v[108:111], v[128:131], v[196:199], 0
	v_mfma_f32_16x16x32_bf16 v[104:107], v[154:157], v[196:199], 0
	v_mfma_f32_16x16x32_bf16 v[92:95], v[128:131], v[204:207], 0
	v_mfma_f32_16x16x32_bf16 v[88:91], v[154:157], v[204:207], 0
	v_mfma_f32_16x16x32_bf16 v[76:79], v[128:131], v[212:215], 0
	v_mfma_f32_16x16x32_bf16 v[72:75], v[154:157], v[212:215], 0
	v_mfma_f32_16x16x32_bf16 v[120:123], v[132:135], v[192:195], v[120:123]
	v_mfma_f32_16x16x32_bf16 v[124:127], v[158:161], v[192:195], v[124:127]
	v_mfma_f32_16x16x32_bf16 v[108:111], v[132:135], v[200:203], v[108:111]
	v_mfma_f32_16x16x32_bf16 v[104:107], v[158:161], v[200:203], v[104:107]
	v_mfma_f32_16x16x32_bf16 v[92:95], v[132:135], v[208:211], v[92:95]
	v_mfma_f32_16x16x32_bf16 v[88:91], v[158:161], v[208:211], v[88:91]
	v_mfma_f32_16x16x32_bf16 v[76:79], v[132:135], v[216:219], v[76:79]
	v_mfma_f32_16x16x32_bf16 v[72:75], v[158:161], v[216:219], v[72:75]
	s_setprio 0
	s_setprio 1
	v_mfma_f32_16x16x32_bf16 v[116:119], v[162:165], v[178:181], 0
	v_mfma_f32_16x16x32_bf16 v[112:115], v[170:173], v[178:181], 0
	v_mfma_f32_16x16x32_bf16 v[100:103], v[162:165], v[196:199], 0
	v_mfma_f32_16x16x32_bf16 v[96:99], v[170:173], v[196:199], 0
	v_mfma_f32_16x16x32_bf16 v[84:87], v[162:165], v[204:207], 0
	v_mfma_f32_16x16x32_bf16 v[80:83], v[170:173], v[204:207], 0
	v_mfma_f32_16x16x32_bf16 v[68:71], v[162:165], v[212:215], 0
	v_mfma_f32_16x16x32_bf16 v[64:67], v[170:173], v[212:215], 0
	v_mfma_f32_16x16x32_bf16 v[116:119], v[166:169], v[192:195], v[116:119]
	v_mfma_f32_16x16x32_bf16 v[112:115], v[174:177], v[192:195], v[112:115]
	v_mfma_f32_16x16x32_bf16 v[100:103], v[166:169], v[200:203], v[100:103]
	v_mfma_f32_16x16x32_bf16 v[96:99], v[174:177], v[200:203], v[96:99]
	v_mfma_f32_16x16x32_bf16 v[84:87], v[166:169], v[208:211], v[84:87]
	v_mfma_f32_16x16x32_bf16 v[80:83], v[174:177], v[208:211], v[80:83]
	v_mfma_f32_16x16x32_bf16 v[68:71], v[166:169], v[216:219], v[68:71]
	v_mfma_f32_16x16x32_bf16 v[64:67], v[174:177], v[216:219], v[64:67]
	s_setprio 0
	s_barrier
	s_add_i32 s47, s3, s84
	v_lshl_add_u64 v[182:183], s[48:49], 0, v[138:139]
	s_mov_b32 m0, s47
	ds_read_b128 v[178:181], v189 offset:16384
	ds_read_b128 v[192:195], v189 offset:17408
	ds_read_b128 v[196:199], v189 offset:18432
	ds_read_b128 v[200:203], v189 offset:19456
	ds_read_b128 v[204:207], v189 offset:20480
	ds_read_b128 v[208:211], v189 offset:21504
	ds_read_b128 v[212:215], v189 offset:22528
	ds_read_b128 v[216:219], v189 offset:23552
	global_load_lds_dwordx4 v[182:183], off
	s_add_i32 m0, s47, 0x2000
	v_lshl_add_u64 v[220:221], s[48:49], 0, v[142:143]
	s_add_u32 s48, s48, s10
	s_addc_u32 s49, s49, s11
	s_add_i32 s47, s8, s84
	global_load_lds_dwordx4 v[220:221], off
	v_lshl_add_u64 v[222:223], s[48:49], 0, v[138:139]
	s_mov_b32 m0, s47
	v_lshl_add_u64 v[224:225], s[48:49], 0, v[142:143]
	global_load_lds_dwordx4 v[222:223], off
	s_add_i32 m0, s47, 0x2000
	v_lshl_add_u64 v[226:227], s[6:7], 0, v[136:137]
	global_load_lds_dwordx4 v[224:225], off
	s_mov_b32 m0, s85
	v_lshl_add_u64 v[228:229], s[6:7], 0, v[140:141]
	global_load_lds_dwordx4 v[226:227], off
	s_mov_b32 m0, s86
	s_nop 0
	global_load_lds_dwordx4 v[228:229], off
	s_waitcnt vmcnt(8)
	s_waitcnt lgkmcnt(0)
	s_barrier
	s_setprio 1
	v_mfma_f32_16x16x32_bf16 v[60:63], v[128:131], v[178:181], 0
	v_mfma_f32_16x16x32_bf16 v[56:59], v[154:157], v[178:181], 0
	v_mfma_f32_16x16x32_bf16 v[44:47], v[128:131], v[196:199], 0
	v_mfma_f32_16x16x32_bf16 v[40:43], v[154:157], v[196:199], 0
	v_mfma_f32_16x16x32_bf16 v[28:31], v[128:131], v[204:207], 0
	v_mfma_f32_16x16x32_bf16 v[24:27], v[154:157], v[204:207], 0
	v_mfma_f32_16x16x32_bf16 v[12:15], v[128:131], v[212:215], 0
	v_mfma_f32_16x16x32_bf16 v[8:11], v[154:157], v[212:215], 0
	v_mfma_f32_16x16x32_bf16 v[60:63], v[132:135], v[192:195], v[60:63]
	v_mfma_f32_16x16x32_bf16 v[56:59], v[158:161], v[192:195], v[56:59]
	v_mfma_f32_16x16x32_bf16 v[44:47], v[132:135], v[200:203], v[44:47]
	v_mfma_f32_16x16x32_bf16 v[40:43], v[158:161], v[200:203], v[40:43]
	v_mfma_f32_16x16x32_bf16 v[28:31], v[132:135], v[208:211], v[28:31]
	v_mfma_f32_16x16x32_bf16 v[24:27], v[158:161], v[208:211], v[24:27]
	v_mfma_f32_16x16x32_bf16 v[12:15], v[132:135], v[216:219], v[12:15]
	v_mfma_f32_16x16x32_bf16 v[8:11], v[158:161], v[216:219], v[8:11]
	s_setprio 0
	s_setprio 1
	v_mfma_f32_16x16x32_bf16 v[52:55], v[162:165], v[178:181], 0
	v_mfma_f32_16x16x32_bf16 v[48:51], v[170:173], v[178:181], 0
	v_mfma_f32_16x16x32_bf16 v[36:39], v[162:165], v[196:199], 0
	v_mfma_f32_16x16x32_bf16 v[32:35], v[170:173], v[196:199], 0
	v_mfma_f32_16x16x32_bf16 v[20:23], v[162:165], v[204:207], 0
	v_mfma_f32_16x16x32_bf16 v[16:19], v[170:173], v[204:207], 0
	v_mfma_f32_16x16x32_bf16 v[4:7], v[162:165], v[212:215], 0
	v_mfma_f32_16x16x32_bf16 v[0:3], v[170:173], v[212:215], 0
	v_mfma_f32_16x16x32_bf16 v[52:55], v[166:169], v[192:195], v[52:55]
	v_mfma_f32_16x16x32_bf16 v[48:51], v[174:177], v[192:195], v[48:51]
	v_mfma_f32_16x16x32_bf16 v[36:39], v[166:169], v[200:203], v[36:39]
	v_mfma_f32_16x16x32_bf16 v[32:35], v[174:177], v[200:203], v[32:35]
	v_mfma_f32_16x16x32_bf16 v[20:23], v[166:169], v[208:211], v[20:23]
	v_mfma_f32_16x16x32_bf16 v[16:19], v[174:177], v[208:211], v[16:19]
	v_mfma_f32_16x16x32_bf16 v[4:7], v[166:169], v[216:219], v[4:7]
	v_mfma_f32_16x16x32_bf16 v[0:3], v[174:177], v[216:219], v[0:3]
	s_setprio 0
	s_barrier
; #define PG8_STAGE(bufoff, gbase, voff) do { _Pragma("unroll") for (int _i = 0; _i < 2; ++_i) \
;         __builtin_amdgcn_global_load_lds((const unsigned*)((const char*)(gbase) + (voff)[_i]), (PG8_LAS unsigned*)(lds + (bufoff) + ldsw + _i * 8192), 16, 0, 0); } while (0)
; #define PG8_LDA(dst, b, h) do { _Pragma("unroll") for (int m = 0; m < 4; ++m) _Pragma("unroll") for (int k = 0; k < 2; ++k) dst[m][k] = *(const PG8_LAS bf16x8*)(lds + PG8_SA(b, h) + aoff + m * 2048 + k * 1024); } while (0)
; #define PG8_LDB(dst, b, h) do { _Pragma("unroll") for (int n = 0; n < 2; ++n) _Pragma("unroll") for (int k = 0; k < 2; ++k) dst[n][k] = *(const PG8_LAS bf16x8*)(lds + PG8_SB(b, h) + boff + n * 2048 + k * 1024); } while (0)
; #define PG8_MMA(ai, bj, At, Bt) do { __builtin_amdgcn_s_setprio(1); _Pragma("unroll") for (int m = 0; m < 4; ++m) _Pragma("unroll") for (int n = 0; n < 2; ++n) _Pragma("unroll") for (int k = 0; k < 2; ++k) \
;         acc[ai][bj][m][n] = __builtin_amdgcn_mfma_f32_16x16x32_bf16(Bt[n][k], At[m][k], acc[ai][bj][m][n], 0, 0, 0); __builtin_amdgcn_s_setprio(0); } while (0)
; #define PG8_WAIT_V(n) asm volatile("s_waitcnt vmcnt(" #n ")" ::: "memory")
; #define PG8_WAIT_L(n) asm volatile("s_waitcnt lgkmcnt(" #n ")" ::: "memory")
; #define PG8_BAR __builtin_amdgcn_s_barrier()
; #define PG8_SCHED __builtin_amdgcn_sched_barrier(0)
; template <class Epi, class Sched, bool ALIGN_EPI = false, bool SP2 = false>
; __device__ __forceinline__ void gemm_phase(PG8_LAS unsigned char* lds, const Gemm g, const Sched& S, const Epi& E) {
;     ...
;             PG8_LDB(B0, 1, 0); PG8_LDB(B1, 1, 1); PG8_SCHED; PG8_LDA(At, 1, 0); PG8_STAGE(PG8_SA(0, 1), a2 + hstep, voffA);
;             PG8_WAIT_V(8); PG8_WAIT_L(0); PG8_BAR; PG8_MMA(0, 0, At, B0); PG8_MMA(0, 1, At, B1); PG8_BAR; PG8_SCHED;
;             PG8_LDA(At, 1, 1); PG8_STAGE(PG8_SB(1, 0), b3, voffB); PG8_STAGE(PG8_SB(1, 1), b3 + hstep, voffB); PG8_STAGE(PG8_SA(1, 0), a3, voffA);
;             PG8_WAIT_V(8); PG8_WAIT_L(0); PG8_BAR; PG8_MMA(1, 0, At, B0); PG8_MMA(1, 1, At, B1); PG8_BAR; PG8_SCHED;
	s_add_i32 s47, 0, 0x18000
	s_add_i32 s48, 0, 0x1c000
	v_add_u32_e32 v158, s47, v186
	v_add_u32_e32 v174, s48, v186
	ds_read_b128 v[128:131], v158
	ds_read_b128 v[132:135], v158 offset:1024
	ds_read_b128 v[154:157], v158 offset:2048
	ds_read_b128 v[158:161], v158 offset:3072
	ds_read_b128 v[162:165], v174
	ds_read_b128 v[166:169], v174 offset:1024
	ds_read_b128 v[170:173], v174 offset:2048
	ds_read_b128 v[174:177], v174 offset:3072
	s_add_u32 s6, s6, s10
	s_addc_u32 s7, s7, s11
	s_mov_b32 m0, s87
	v_lshl_add_u64 v[230:231], s[6:7], 0, v[136:137]
	ds_read_b128 v[178:181], v189 offset:32768
	ds_read_b128 v[192:195], v189 offset:33792
	ds_read_b128 v[196:199], v189 offset:34816
	ds_read_b128 v[200:203], v189 offset:35840
	ds_read_b128 v[204:207], v189 offset:36864
	ds_read_b128 v[208:211], v189 offset:37888
	ds_read_b128 v[212:215], v189 offset:38912
	ds_read_b128 v[216:219], v189 offset:39936
	global_load_lds_dwordx4 v[230:231], off
	v_lshl_add_u64 v[230:231], s[6:7], 0, v[140:141]
	s_mov_b32 m0, s88
	s_nop 0
	global_load_lds_dwordx4 v[230:231], off
	s_waitcnt vmcnt(8)
	s_waitcnt lgkmcnt(0)
	s_barrier
	s_setprio 1
	v_mfma_f32_16x16x32_bf16 v[120:123], v[128:131], v[178:181], v[120:123]
	v_mfma_f32_16x16x32_bf16 v[124:127], v[154:157], v[178:181], v[124:127]
	v_mfma_f32_16x16x32_bf16 v[108:111], v[128:131], v[196:199], v[108:111]
	v_mfma_f32_16x16x32_bf16 v[104:107], v[154:157], v[196:199], v[104:107]
	v_mfma_f32_16x16x32_bf16 v[92:95], v[128:131], v[204:207], v[92:95]
	v_mfma_f32_16x16x32_bf16 v[88:91], v[154:157], v[204:207], v[88:91]
	v_mfma_f32_16x16x32_bf16 v[76:79], v[128:131], v[212:215], v[76:79]
	v_mfma_f32_16x16x32_bf16 v[72:75], v[154:157], v[212:215], v[72:75]
	v_mfma_f32_16x16x32_bf16 v[120:123], v[132:135], v[192:195], v[120:123]
	v_mfma_f32_16x16x32_bf16 v[124:127], v[158:161], v[192:195], v[124:127]
	v_mfma_f32_16x16x32_bf16 v[108:111], v[132:135], v[200:203], v[108:111]
	v_mfma_f32_16x16x32_bf16 v[104:107], v[158:161], v[200:203], v[104:107]
	v_mfma_f32_16x16x32_bf16 v[92:95], v[132:135], v[208:211], v[92:95]
	v_mfma_f32_16x16x32_bf16 v[88:91], v[158:161], v[208:211], v[88:91]
	v_mfma_f32_16x16x32_bf16 v[76:79], v[132:135], v[216:219], v[76:79]
	v_mfma_f32_16x16x32_bf16 v[72:75], v[158:161], v[216:219], v[72:75]
	s_setprio 0
	s_setprio 1
	v_mfma_f32_16x16x32_bf16 v[116:119], v[162:165], v[178:181], v[116:119]
	v_mfma_f32_16x16x32_bf16 v[112:115], v[170:173], v[178:181], v[112:115]
	v_mfma_f32_16x16x32_bf16 v[100:103], v[162:165], v[196:199], v[100:103]
	v_mfma_f32_16x16x32_bf16 v[96:99], v[170:173], v[196:199], v[96:99]
	v_mfma_f32_16x16x32_bf16 v[84:87], v[162:165], v[204:207], v[84:87]
	v_mfma_f32_16x16x32_bf16 v[80:83], v[170:173], v[204:207], v[80:83]
	v_mfma_f32_16x16x32_bf16 v[68:71], v[162:165], v[212:215], v[68:71]
	v_mfma_f32_16x16x32_bf16 v[64:67], v[170:173], v[212:215], v[64:67]
	v_mfma_f32_16x16x32_bf16 v[116:119], v[166:169], v[192:195], v[116:119]
	v_mfma_f32_16x16x32_bf16 v[112:115], v[174:177], v[192:195], v[112:115]
	v_mfma_f32_16x16x32_bf16 v[100:103], v[166:169], v[200:203], v[100:103]
	v_mfma_f32_16x16x32_bf16 v[96:99], v[174:177], v[200:203], v[96:99]
	v_mfma_f32_16x16x32_bf16 v[84:87], v[166:169], v[208:211], v[84:87]
	v_mfma_f32_16x16x32_bf16 v[80:83], v[174:177], v[208:211], v[80:83]
	v_mfma_f32_16x16x32_bf16 v[68:71], v[166:169], v[216:219], v[68:71]
	v_mfma_f32_16x16x32_bf16 v[64:67], v[174:177], v[216:219], v[64:67]
	s_setprio 0
	s_barrier
	s_add_i32 s6, s47, s84
	v_lshl_add_u64 v[182:183], v[182:183], 0, s[64:65]
	s_mov_b32 m0, s6
	ds_read_b128 v[178:181], v189 offset:49152
	ds_read_b128 v[192:195], v189 offset:50176
	ds_read_b128 v[196:199], v189 offset:51200
	ds_read_b128 v[200:203], v189 offset:52224
	ds_read_b128 v[204:207], v189 offset:53248
	ds_read_b128 v[208:211], v189 offset:54272
	ds_read_b128 v[212:215], v189 offset:55296
	ds_read_b128 v[216:219], v189 offset:56320
	global_load_lds_dwordx4 v[182:183], off
	v_lshl_add_u64 v[182:183], v[220:221], 0, s[64:65]
	s_add_i32 m0, s6, 0x2000
	s_add_i32 s6, s48, s84
	global_load_lds_dwordx4 v[182:183], off
	v_lshl_add_u64 v[182:183], v[222:223], 0, s[64:65]
	s_mov_b32 m0, s6
	s_nop 0
	global_load_lds_dwordx4 v[182:183], off
	v_lshl_add_u64 v[182:183], v[224:225], 0, s[64:65]
	s_add_i32 m0, s6, 0x2000
	s_nop 0
	global_load_lds_dwordx4 v[182:183], off
	v_lshl_add_u64 v[182:183], v[226:227], 0, s[64:65]
	s_mov_b32 m0, s96
	s_nop 0
	global_load_lds_dwordx4 v[182:183], off
	v_lshl_add_u64 v[182:183], v[228:229], 0, s[64:65]
	s_mov_b32 m0, s97
	s_nop 0
	global_load_lds_dwordx4 v[182:183], off
	s_waitcnt vmcnt(8)
	s_waitcnt lgkmcnt(0)
	s_barrier
	s_setprio 1
	v_mfma_f32_16x16x32_bf16 v[60:63], v[128:131], v[178:181], v[60:63]
	v_mfma_f32_16x16x32_bf16 v[56:59], v[154:157], v[178:181], v[56:59]
	v_mfma_f32_16x16x32_bf16 v[44:47], v[128:131], v[196:199], v[44:47]
	v_mfma_f32_16x16x32_bf16 v[40:43], v[154:157], v[196:199], v[40:43]
	v_mfma_f32_16x16x32_bf16 v[28:31], v[128:131], v[204:207], v[28:31]
	v_mfma_f32_16x16x32_bf16 v[24:27], v[154:157], v[204:207], v[24:27]
	v_mfma_f32_16x16x32_bf16 v[12:15], v[128:131], v[212:215], v[12:15]
	v_mfma_f32_16x16x32_bf16 v[8:11], v[154:157], v[212:215], v[8:11]
	v_mfma_f32_16x16x32_bf16 v[60:63], v[132:135], v[192:195], v[60:63]
	v_mfma_f32_16x16x32_bf16 v[56:59], v[158:161], v[192:195], v[56:59]
	v_mfma_f32_16x16x32_bf16 v[44:47], v[132:135], v[200:203], v[44:47]
	v_mfma_f32_16x16x32_bf16 v[40:43], v[158:161], v[200:203], v[40:43]
	v_mfma_f32_16x16x32_bf16 v[28:31], v[132:135], v[208:211], v[28:31]
	v_mfma_f32_16x16x32_bf16 v[24:27], v[158:161], v[208:211], v[24:27]
	v_mfma_f32_16x16x32_bf16 v[12:15], v[132:135], v[216:219], v[12:15]
	v_mfma_f32_16x16x32_bf16 v[8:11], v[158:161], v[216:219], v[8:11]
	s_setprio 0
	s_setprio 1
	v_mfma_f32_16x16x32_bf16 v[52:55], v[162:165], v[178:181], v[52:55]
	v_mfma_f32_16x16x32_bf16 v[48:51], v[170:173], v[178:181], v[48:51]
	v_mfma_f32_16x16x32_bf16 v[36:39], v[162:165], v[196:199], v[36:39]
	v_mfma_f32_16x16x32_bf16 v[32:35], v[170:173], v[196:199], v[32:35]
	v_mfma_f32_16x16x32_bf16 v[20:23], v[162:165], v[204:207], v[20:23]
	v_mfma_f32_16x16x32_bf16 v[16:19], v[170:173], v[204:207], v[16:19]
	v_mfma_f32_16x16x32_bf16 v[4:7], v[162:165], v[212:215], v[4:7]
	v_mfma_f32_16x16x32_bf16 v[0:3], v[170:173], v[212:215], v[0:3]
	v_mfma_f32_16x16x32_bf16 v[52:55], v[166:169], v[192:195], v[52:55]
	v_mfma_f32_16x16x32_bf16 v[48:51], v[174:177], v[192:195], v[48:51]
	v_mfma_f32_16x16x32_bf16 v[36:39], v[166:169], v[200:203], v[36:39]
	v_mfma_f32_16x16x32_bf16 v[32:35], v[174:177], v[200:203], v[32:35]
	v_mfma_f32_16x16x32_bf16 v[20:23], v[166:169], v[208:211], v[20:23]
	v_mfma_f32_16x16x32_bf16 v[16:19], v[174:177], v[208:211], v[16:19]
	v_mfma_f32_16x16x32_bf16 v[4:7], v[166:169], v[216:219], v[4:7]
	v_mfma_f32_16x16x32_bf16 v[0:3], v[174:177], v[216:219], v[0:3]
	s_setprio 0
	s_barrier
	s_add_u32 s0, s0, 0x100
	s_addc_u32 s1, s1, 0
	s_add_u32 s44, s44, 0x100
	s_addc_u32 s45, s45, 0
	s_cmp_ge_i32 s46, s33
	s_mov_b32 s6, s46
; #define PG8_STAGE(bufoff, gbase, voff) do { _Pragma("unroll") for (int _i = 0; _i < 2; ++_i) \
;         __builtin_amdgcn_global_load_lds((const unsigned*)((const char*)(gbase) + (voff)[_i]), (PG8_LAS unsigned*)(lds + (bufoff) + ldsw + _i * 8192), 16, 0, 0); } while (0)
; #define PG8_LDA(dst, b, h) do { _Pragma("unroll") for (int m = 0; m < 4; ++m) _Pragma("unroll") for (int k = 0; k < 2; ++k) dst[m][k] = *(const PG8_LAS bf16x8*)(lds + PG8_SA(b, h) + aoff + m * 2048 + k * 1024); } while (0)
; #define PG8_LDB(dst, b, h) do { _Pragma("unroll") for (int n = 0; n < 2; ++n) _Pragma("unroll") for (int k = 0; k < 2; ++k) dst[n][k] = *(const PG8_LAS bf16x8*)(lds + PG8_SB(b, h) + boff + n * 2048 + k * 1024); } while (0)
; #define PG8_MMA(ai, bj, At, Bt) do { __builtin_amdgcn_s_setprio(1); _Pragma("unroll") for (int m = 0; m < 4; ++m) _Pragma("unroll") for (int n = 0; n < 2; ++n) _Pragma("unroll") for (int k = 0; k < 2; ++k) \
;         acc[ai][bj][m][n] = __builtin_amdgcn_mfma_f32_16x16x32_bf16(Bt[n][k], At[m][k], acc[ai][bj][m][n], 0, 0, 0); __builtin_amdgcn_s_setprio(0); } while (0)
; #define PG8_WAIT_V(n) asm volatile("s_waitcnt vmcnt(" #n ")" ::: "memory")
; #define PG8_WAIT_L(n) asm volatile("s_waitcnt lgkmcnt(" #n ")" ::: "memory")
; #define PG8_BAR __builtin_amdgcn_s_barrier()
; #define PG8_SCHED __builtin_amdgcn_sched_barrier(0)
; template <class Epi, class Sched, bool ALIGN_EPI = false, bool SP2 = false>
; __device__ __forceinline__ void gemm_phase(PG8_LAS unsigned char* lds, const Gemm g, const Sched& S, const Epi& E) {
;     ...
;         for (int t = 0; t < nt; t += 2) {
;             const bool last = (t == nt - 2);
;             const char* a1 = cA + (size_t)(t + 1) * kstep;
;             const char* a2 = last ? nA : cA + (size_t)(t + 2) * kstep; const char* b2 = last ? nB : cB + (size_t)(t + 2) * kstep;
;             const char* a3 = a2 + kstep; const char* b3 = b2 + kstep;
;             if (last && has_next) S.a_ready(nxt);
;             if constexpr (SP2) {
;             PG8_LDB(B0, 0, 0); PG8_LDB(B1, 0, 1); PG8_SCHED; PG8_LDA(At, 0, 0); PG8_STAGE(PG8_SA(1, 1), a1 + hstep, voffA);
;             PG8_WAIT_V(8); PG8_WAIT_L(0); PG8_BAR; PG8_MMA(0, 0, At, B0); PG8_MMA(0, 1, At, B1); PG8_BAR; PG8_SCHED;
.LBB0_919:
	ds_read_b128 v[128:131], v187
	ds_read_b128 v[132:135], v187 offset:1024
	ds_read_b128 v[154:157], v187 offset:2048
	ds_read_b128 v[158:161], v187 offset:3072
	ds_read_b128 v[162:165], v188
	ds_read_b128 v[166:169], v188 offset:1024
	ds_read_b128 v[170:173], v188 offset:2048
	ds_read_b128 v[174:177], v188 offset:3072
	s_add_i32 s46, s6, 2
	s_add_u32 s47, s0, 0x80
	s_addc_u32 s7, s1, 0
	s_cmp_eq_u32 s93, s6
	s_cselect_b32 s6, s16, s47
	s_cselect_b32 s7, s17, s7
	s_cselect_b32 s49, s19, s45
	s_cselect_b32 s48, s18, s44
	v_lshl_add_u64 v[182:183], s[0:1], 0, v[146:147]
	s_add_i32 m0, s85, 0xc000
	ds_read_b128 v[178:181], v189
	ds_read_b128 v[192:195], v189 offset:1024
	ds_read_b128 v[196:199], v189 offset:2048
	ds_read_b128 v[200:203], v189 offset:3072
	ds_read_b128 v[204:207], v189 offset:4096
	ds_read_b128 v[208:211], v189 offset:5120
	ds_read_b128 v[212:215], v189 offset:6144
	ds_read_b128 v[216:219], v189 offset:7168
	global_load_lds_dwordx4 v[182:183], off
	v_lshl_add_u64 v[182:183], s[0:1], 0, v[148:149]
	s_add_i32 m0, s85, 0xe000
	s_nop 0
	global_load_lds_dwordx4 v[182:183], off
	s_waitcnt vmcnt(8)
	s_waitcnt lgkmcnt(0)
	s_barrier
	s_setprio 1
	v_mfma_f32_16x16x32_bf16 v[120:123], v[128:131], v[178:181], v[120:123]
	v_mfma_f32_16x16x32_bf16 v[124:127], v[154:157], v[178:181], v[124:127]
	v_mfma_f32_16x16x32_bf16 v[108:111], v[128:131], v[196:199], v[108:111]
	v_mfma_f32_16x16x32_bf16 v[104:107], v[154:157], v[196:199], v[104:107]
	v_mfma_f32_16x16x32_bf16 v[92:95], v[128:131], v[204:207], v[92:95]
	v_mfma_f32_16x16x32_bf16 v[88:91], v[154:157], v[204:207], v[88:91]
	v_mfma_f32_16x16x32_bf16 v[76:79], v[128:131], v[212:215], v[76:79]
	v_mfma_f32_16x16x32_bf16 v[72:75], v[154:157], v[212:215], v[72:75]
	v_mfma_f32_16x16x32_bf16 v[120:123], v[132:135], v[192:195], v[120:123]
	v_mfma_f32_16x16x32_bf16 v[124:127], v[158:161], v[192:195], v[124:127]
	v_mfma_f32_16x16x32_bf16 v[108:111], v[132:135], v[200:203], v[108:111]
	v_mfma_f32_16x16x32_bf16 v[104:107], v[158:161], v[200:203], v[104:107]
	v_mfma_f32_16x16x32_bf16 v[92:95], v[132:135], v[208:211], v[92:95]
	v_mfma_f32_16x16x32_bf16 v[88:91], v[158:161], v[208:211], v[88:91]
	v_mfma_f32_16x16x32_bf16 v[76:79], v[132:135], v[216:219], v[76:79]
	v_mfma_f32_16x16x32_bf16 v[72:75], v[158:161], v[216:219], v[72:75]
	s_setprio 0
	s_setprio 1
	v_mfma_f32_16x16x32_bf16 v[116:119], v[162:165], v[178:181], v[116:119]
	v_mfma_f32_16x16x32_bf16 v[112:115], v[170:173], v[178:181], v[112:115]
	v_mfma_f32_16x16x32_bf16 v[100:103], v[162:165], v[196:199], v[100:103]
	v_mfma_f32_16x16x32_bf16 v[96:99], v[170:173], v[196:199], v[96:99]
	v_mfma_f32_16x16x32_bf16 v[84:87], v[162:165], v[204:207], v[84:87]
	v_mfma_f32_16x16x32_bf16 v[80:83], v[170:173], v[204:207], v[80:83]
	v_mfma_f32_16x16x32_bf16 v[68:71], v[162:165], v[212:215], v[68:71]
	v_mfma_f32_16x16x32_bf16 v[64:67], v[170:173], v[212:215], v[64:67]
	v_mfma_f32_16x16x32_bf16 v[116:119], v[166:169], v[192:195], v[116:119]
	v_mfma_f32_16x16x32_bf16 v[112:115], v[174:177], v[192:195], v[112:115]
	v_mfma_f32_16x16x32_bf16 v[100:103], v[166:169], v[200:203], v[100:103]
	v_mfma_f32_16x16x32_bf16 v[96:99], v[174:177], v[200:203], v[96:99]
	v_mfma_f32_16x16x32_bf16 v[84:87], v[166:169], v[208:211], v[84:87]
	v_mfma_f32_16x16x32_bf16 v[80:83], v[174:177], v[208:211], v[80:83]
	v_mfma_f32_16x16x32_bf16 v[68:71], v[166:169], v[216:219], v[68:71]
	v_mfma_f32_16x16x32_bf16 v[64:67], v[174:177], v[216:219], v[64:67]
	s_setprio 0
	s_barrier
	s_add_i32 s47, s3, s84
	v_lshl_add_u64 v[182:183], s[48:49], 0, v[138:139]
	s_mov_b32 m0, s47
	ds_read_b128 v[178:181], v189 offset:16384
	ds_read_b128 v[192:195], v189 offset:17408
	ds_read_b128 v[196:199], v189 offset:18432
	ds_read_b128 v[200:203], v189 offset:19456
	ds_read_b128 v[204:207], v189 offset:20480
	ds_read_b128 v[208:211], v189 offset:21504
	ds_read_b128 v[212:215], v189 offset:22528
	ds_read_b128 v[216:219], v189 offset:23552
	global_load_lds_dwordx4 v[182:183], off
	s_add_i32 m0, s47, 0x2000
	v_lshl_add_u64 v[220:221], s[48:49], 0, v[142:143]
	s_add_u32 s48, s48, s10
	s_addc_u32 s49, s49, s11
	s_add_i32 s47, s8, s84
	global_load_lds_dwordx4 v[220:221], off
	v_lshl_add_u64 v[222:223], s[48:49], 0, v[138:139]
	s_mov_b32 m0, s47
	v_lshl_add_u64 v[224:225], s[48:49], 0, v[142:143]
	global_load_lds_dwordx4 v[222:223], off
	s_add_i32 m0, s47, 0x2000
	v_lshl_add_u64 v[226:227], s[6:7], 0, v[136:137]
	global_load_lds_dwordx4 v[224:225], off
	s_mov_b32 m0, s85
	v_lshl_add_u64 v[228:229], s[6:7], 0, v[140:141]
	global_load_lds_dwordx4 v[226:227], off
	s_mov_b32 m0, s86
	s_nop 0
	global_load_lds_dwordx4 v[228:229], off
	s_waitcnt vmcnt(8)
	s_waitcnt lgkmcnt(0)
	s_barrier
; #define PG8_STAGE(bufoff, gbase, voff) do { _Pragma("unroll") for (int _i = 0; _i < 2; ++_i) \
;         __builtin_amdgcn_global_load_lds((const unsigned*)((const char*)(gbase) + (voff)[_i]), (PG8_LAS unsigned*)(lds + (bufoff) + ldsw + _i * 8192), 16, 0, 0); } while (0)
; #define PG8_LDA(dst, b, h) do { _Pragma("unroll") for (int m = 0; m < 4; ++m) _Pragma("unroll") for (int k = 0; k < 2; ++k) dst[m][k] = *(const PG8_LAS bf16x8*)(lds + PG8_SA(b, h) + aoff + m * 2048 + k * 1024); } while (0)
; #define PG8_LDB(dst, b, h) do { _Pragma("unroll") for (int n = 0; n < 2; ++n) _Pragma("unroll") for (int k = 0; k < 2; ++k) dst[n][k] = *(const PG8_LAS bf16x8*)(lds + PG8_SB(b, h) + boff + n * 2048 + k * 1024); } while (0)
; #define PG8_MMA(ai, bj, At, Bt) do { __builtin_amdgcn_s_setprio(1); _Pragma("unroll") for (int m = 0; m < 4; ++m) _Pragma("unroll") for (int n = 0; n < 2; ++n) _Pragma("unroll") for (int k = 0; k < 2; ++k) \
;         acc[ai][bj][m][n] = __builtin_amdgcn_mfma_f32_16x16x32_bf16(Bt[n][k], At[m][k], acc[ai][bj][m][n], 0, 0, 0); __builtin_amdgcn_s_setprio(0); } while (0)
; #define PG8_WAIT_V(n) asm volatile("s_waitcnt vmcnt(" #n ")" ::: "memory")
; #define PG8_WAIT_L(n) asm volatile("s_waitcnt lgkmcnt(" #n ")" ::: "memory")
; #define PG8_BAR __builtin_amdgcn_s_barrier()
; #define PG8_SCHED __builtin_amdgcn_sched_barrier(0)
; template <class Epi, class Sched, bool ALIGN_EPI = false, bool SP2 = false>
; __device__ __forceinline__ void gemm_phase(PG8_LAS unsigned char* lds, const Gemm g, const Sched& S, const Epi& E) {
;     ...
;             PG8_WAIT_V(8); PG8_WAIT_L(0); PG8_BAR; PG8_MMA(1, 0, At, B0); PG8_MMA(1, 1, At, B1); PG8_BAR; PG8_SCHED;
;             PG8_LDB(B0, 1, 0); PG8_LDB(B1, 1, 1); PG8_SCHED; PG8_LDA(At, 1, 0); PG8_STAGE(PG8_SA(0, 1), a2 + hstep, voffA);
;             PG8_WAIT_V(8); PG8_WAIT_L(0); PG8_BAR; PG8_MMA(0, 0, At, B0); PG8_MMA(0, 1, At, B1); PG8_BAR; PG8_SCHED;
	s_setprio 1
	v_mfma_f32_16x16x32_bf16 v[60:63], v[128:131], v[178:181], v[60:63]
	v_mfma_f32_16x16x32_bf16 v[56:59], v[154:157], v[178:181], v[56:59]
	v_mfma_f32_16x16x32_bf16 v[44:47], v[128:131], v[196:199], v[44:47]
	v_mfma_f32_16x16x32_bf16 v[40:43], v[154:157], v[196:199], v[40:43]
	v_mfma_f32_16x16x32_bf16 v[28:31], v[128:131], v[204:207], v[28:31]
	v_mfma_f32_16x16x32_bf16 v[24:27], v[154:157], v[204:207], v[24:27]
	v_mfma_f32_16x16x32_bf16 v[12:15], v[128:131], v[212:215], v[12:15]
	v_mfma_f32_16x16x32_bf16 v[8:11], v[154:157], v[212:215], v[8:11]
	v_mfma_f32_16x16x32_bf16 v[60:63], v[132:135], v[192:195], v[60:63]
	v_mfma_f32_16x16x32_bf16 v[56:59], v[158:161], v[192:195], v[56:59]
	v_mfma_f32_16x16x32_bf16 v[44:47], v[132:135], v[200:203], v[44:47]
	v_mfma_f32_16x16x32_bf16 v[40:43], v[158:161], v[200:203], v[40:43]
	v_mfma_f32_16x16x32_bf16 v[28:31], v[132:135], v[208:211], v[28:31]
	v_mfma_f32_16x16x32_bf16 v[24:27], v[158:161], v[208:211], v[24:27]
	v_mfma_f32_16x16x32_bf16 v[12:15], v[132:135], v[216:219], v[12:15]
	v_mfma_f32_16x16x32_bf16 v[8:11], v[158:161], v[216:219], v[8:11]
	s_setprio 0
	s_setprio 1
	v_mfma_f32_16x16x32_bf16 v[52:55], v[162:165], v[178:181], v[52:55]
	v_mfma_f32_16x16x32_bf16 v[48:51], v[170:173], v[178:181], v[48:51]
	v_mfma_f32_16x16x32_bf16 v[36:39], v[162:165], v[196:199], v[36:39]
	v_mfma_f32_16x16x32_bf16 v[32:35], v[170:173], v[196:199], v[32:35]
	v_mfma_f32_16x16x32_bf16 v[20:23], v[162:165], v[204:207], v[20:23]
	v_mfma_f32_16x16x32_bf16 v[16:19], v[170:173], v[204:207], v[16:19]
	v_mfma_f32_16x16x32_bf16 v[4:7], v[162:165], v[212:215], v[4:7]
	v_mfma_f32_16x16x32_bf16 v[0:3], v[170:173], v[212:215], v[0:3]
	v_mfma_f32_16x16x32_bf16 v[52:55], v[166:169], v[192:195], v[52:55]
	v_mfma_f32_16x16x32_bf16 v[48:51], v[174:177], v[192:195], v[48:51]
	v_mfma_f32_16x16x32_bf16 v[36:39], v[166:169], v[200:203], v[36:39]
	v_mfma_f32_16x16x32_bf16 v[32:35], v[174:177], v[200:203], v[32:35]
	v_mfma_f32_16x16x32_bf16 v[20:23], v[166:169], v[208:211], v[20:23]
	v_mfma_f32_16x16x32_bf16 v[16:19], v[174:177], v[208:211], v[16:19]
	v_mfma_f32_16x16x32_bf16 v[4:7], v[166:169], v[216:219], v[4:7]
	v_mfma_f32_16x16x32_bf16 v[0:3], v[174:177], v[216:219], v[0:3]
	s_setprio 0
	s_barrier
	s_add_i32 s47, 0, 0x18000
	s_add_i32 s48, 0, 0x1c000
	v_add_u32_e32 v158, s47, v186
	v_add_u32_e32 v174, s48, v186
	ds_read_b128 v[128:131], v158
	ds_read_b128 v[132:135], v158 offset:1024
	ds_read_b128 v[154:157], v158 offset:2048
	ds_read_b128 v[158:161], v158 offset:3072
	ds_read_b128 v[162:165], v174
	ds_read_b128 v[166:169], v174 offset:1024
	ds_read_b128 v[170:173], v174 offset:2048
	ds_read_b128 v[174:177], v174 offset:3072
	s_add_u32 s6, s6, s10
	s_addc_u32 s7, s7, s11
	s_mov_b32 m0, s87
	v_lshl_add_u64 v[230:231], s[6:7], 0, v[136:137]
	ds_read_b128 v[178:181], v189 offset:32768
	ds_read_b128 v[192:195], v189 offset:33792
	ds_read_b128 v[196:199], v189 offset:34816
	ds_read_b128 v[200:203], v189 offset:35840
	ds_read_b128 v[204:207], v189 offset:36864
	ds_read_b128 v[208:211], v189 offset:37888
	ds_read_b128 v[212:215], v189 offset:38912
	ds_read_b128 v[216:219], v189 offset:39936
	global_load_lds_dwordx4 v[230:231], off
	v_lshl_add_u64 v[230:231], s[6:7], 0, v[140:141]
	s_mov_b32 m0, s88
	s_nop 0
	global_load_lds_dwordx4 v[230:231], off
	s_waitcnt vmcnt(8)
	s_waitcnt lgkmcnt(0)
	s_barrier
	s_setprio 1
	v_mfma_f32_16x16x32_bf16 v[120:123], v[128:131], v[178:181], v[120:123]
	v_mfma_f32_16x16x32_bf16 v[124:127], v[154:157], v[178:181], v[124:127]
	v_mfma_f32_16x16x32_bf16 v[108:111], v[128:131], v[196:199], v[108:111]
	v_mfma_f32_16x16x32_bf16 v[104:107], v[154:157], v[196:199], v[104:107]
	v_mfma_f32_16x16x32_bf16 v[92:95], v[128:131], v[204:207], v[92:95]
	v_mfma_f32_16x16x32_bf16 v[88:91], v[154:157], v[204:207], v[88:91]
	v_mfma_f32_16x16x32_bf16 v[76:79], v[128:131], v[212:215], v[76:79]
	v_mfma_f32_16x16x32_bf16 v[72:75], v[154:157], v[212:215], v[72:75]
	v_mfma_f32_16x16x32_bf16 v[120:123], v[132:135], v[192:195], v[120:123]
	v_mfma_f32_16x16x32_bf16 v[124:127], v[158:161], v[192:195], v[124:127]
	v_mfma_f32_16x16x32_bf16 v[108:111], v[132:135], v[200:203], v[108:111]
	v_mfma_f32_16x16x32_bf16 v[104:107], v[158:161], v[200:203], v[104:107]
	v_mfma_f32_16x16x32_bf16 v[92:95], v[132:135], v[208:211], v[92:95]
	v_mfma_f32_16x16x32_bf16 v[88:91], v[158:161], v[208:211], v[88:91]
	v_mfma_f32_16x16x32_bf16 v[76:79], v[132:135], v[216:219], v[76:79]
	v_mfma_f32_16x16x32_bf16 v[72:75], v[158:161], v[216:219], v[72:75]
	s_setprio 0
	s_setprio 1
	v_mfma_f32_16x16x32_bf16 v[116:119], v[162:165], v[178:181], v[116:119]
	v_mfma_f32_16x16x32_bf16 v[112:115], v[170:173], v[178:181], v[112:115]
	v_mfma_f32_16x16x32_bf16 v[100:103], v[162:165], v[196:199], v[100:103]
	v_mfma_f32_16x16x32_bf16 v[96:99], v[170:173], v[196:199], v[96:99]
	v_mfma_f32_16x16x32_bf16 v[84:87], v[162:165], v[204:207], v[84:87]
	v_mfma_f32_16x16x32_bf16 v[80:83], v[170:173], v[204:207], v[80:83]
	v_mfma_f32_16x16x32_bf16 v[68:71], v[162:165], v[212:215], v[68:71]
	v_mfma_f32_16x16x32_bf16 v[64:67], v[170:173], v[212:215], v[64:67]
	v_mfma_f32_16x16x32_bf16 v[116:119], v[166:169], v[192:195], v[116:119]
	v_mfma_f32_16x16x32_bf16 v[112:115], v[174:177], v[192:195], v[112:115]
	v_mfma_f32_16x16x32_bf16 v[100:103], v[166:169], v[200:203], v[100:103]
	v_mfma_f32_16x16x32_bf16 v[96:99], v[174:177], v[200:203], v[96:99]
	v_mfma_f32_16x16x32_bf16 v[84:87], v[166:169], v[208:211], v[84:87]
	v_mfma_f32_16x16x32_bf16 v[80:83], v[174:177], v[208:211], v[80:83]
	v_mfma_f32_16x16x32_bf16 v[68:71], v[166:169], v[216:219], v[68:71]
	v_mfma_f32_16x16x32_bf16 v[64:67], v[174:177], v[216:219], v[64:67]
	s_setprio 0
	s_barrier
; #define PG8_STAGE(bufoff, gbase, voff) do { _Pragma("unroll") for (int _i = 0; _i < 2; ++_i) \
;         __builtin_amdgcn_global_load_lds((const unsigned*)((const char*)(gbase) + (voff)[_i]), (PG8_LAS unsigned*)(lds + (bufoff) + ldsw + _i * 8192), 16, 0, 0); } while (0)
; #define PG8_LDA(dst, b, h) do { _Pragma("unroll") for (int m = 0; m < 4; ++m) _Pragma("unroll") for (int k = 0; k < 2; ++k) dst[m][k] = *(const PG8_LAS bf16x8*)(lds + PG8_SA(b, h) + aoff + m * 2048 + k * 1024); } while (0)
; #define PG8_MMA(ai, bj, At, Bt) do { __builtin_amdgcn_s_setprio(1); _Pragma("unroll") for (int m = 0; m < 4; ++m) _Pragma("unroll") for (int n = 0; n < 2; ++n) _Pragma("unroll") for (int k = 0; k < 2; ++k) \
;         acc[ai][bj][m][n] = __builtin_amdgcn_mfma_f32_16x16x32_bf16(Bt[n][k], At[m][k], acc[ai][bj][m][n], 0, 0, 0); __builtin_amdgcn_s_setprio(0); } while (0)
; #define PG8_WAIT_V(n) asm volatile("s_waitcnt vmcnt(" #n ")" ::: "memory")
; #define PG8_WAIT_L(n) asm volatile("s_waitcnt lgkmcnt(" #n ")" ::: "memory")
; #define PG8_BAR __builtin_amdgcn_s_barrier()
; #define PG8_SCHED __builtin_amdgcn_sched_barrier(0)
; template <class Epi, class Sched, bool ALIGN_EPI = false, bool SP2 = false>
; __device__ __forceinline__ void gemm_phase(PG8_LAS unsigned char* lds, const Gemm g, const Sched& S, const Epi& E) {
;     ...
;         for (int t = 0; t < nt; t += 2) {
;     ...
;             PG8_WAIT_V(8); PG8_WAIT_L(0); PG8_BAR; PG8_MMA(0, 0, At, B0); PG8_MMA(0, 1, At, B1); PG8_BAR; PG8_SCHED;
;             PG8_LDA(At, 1, 1); PG8_STAGE(PG8_SB(1, 0), b3, voffB); PG8_STAGE(PG8_SB(1, 1), b3 + hstep, voffB); PG8_STAGE(PG8_SA(1, 0), a3, voffA);
;             PG8_WAIT_V(8); PG8_WAIT_L(0); PG8_BAR; PG8_MMA(1, 0, At, B0); PG8_MMA(1, 1, At, B1); PG8_BAR; PG8_SCHED;
	s_add_i32 s6, s47, s84
	v_lshl_add_u64 v[182:183], v[182:183], 0, s[64:65]
	s_mov_b32 m0, s6
	ds_read_b128 v[178:181], v189 offset:49152
	ds_read_b128 v[192:195], v189 offset:50176
	ds_read_b128 v[196:199], v189 offset:51200
	ds_read_b128 v[200:203], v189 offset:52224
	ds_read_b128 v[204:207], v189 offset:53248
	ds_read_b128 v[208:211], v189 offset:54272
	ds_read_b128 v[212:215], v189 offset:55296
	ds_read_b128 v[216:219], v189 offset:56320
	global_load_lds_dwordx4 v[182:183], off
	v_lshl_add_u64 v[182:183], v[220:221], 0, s[64:65]
	s_add_i32 m0, s6, 0x2000
	s_add_i32 s6, s48, s84
	global_load_lds_dwordx4 v[182:183], off
	v_lshl_add_u64 v[182:183], v[222:223], 0, s[64:65]
	s_mov_b32 m0, s6
	s_nop 0
	global_load_lds_dwordx4 v[182:183], off
	v_lshl_add_u64 v[182:183], v[224:225], 0, s[64:65]
	s_add_i32 m0, s6, 0x2000
	s_nop 0
	global_load_lds_dwordx4 v[182:183], off
	v_lshl_add_u64 v[182:183], v[226:227], 0, s[64:65]
	s_mov_b32 m0, s96
	s_nop 0
	global_load_lds_dwordx4 v[182:183], off
	v_lshl_add_u64 v[182:183], v[228:229], 0, s[64:65]
	s_mov_b32 m0, s97
	s_nop 0
	global_load_lds_dwordx4 v[182:183], off
	s_waitcnt vmcnt(8)
	s_waitcnt lgkmcnt(0)
	s_barrier
	s_setprio 1
	v_mfma_f32_16x16x32_bf16 v[60:63], v[128:131], v[178:181], v[60:63]
	v_mfma_f32_16x16x32_bf16 v[56:59], v[154:157], v[178:181], v[56:59]
	v_mfma_f32_16x16x32_bf16 v[44:47], v[128:131], v[196:199], v[44:47]
	v_mfma_f32_16x16x32_bf16 v[40:43], v[154:157], v[196:199], v[40:43]
	v_mfma_f32_16x16x32_bf16 v[28:31], v[128:131], v[204:207], v[28:31]
	v_mfma_f32_16x16x32_bf16 v[24:27], v[154:157], v[204:207], v[24:27]
	v_mfma_f32_16x16x32_bf16 v[12:15], v[128:131], v[212:215], v[12:15]
	v_mfma_f32_16x16x32_bf16 v[8:11], v[154:157], v[212:215], v[8:11]
	v_mfma_f32_16x16x32_bf16 v[60:63], v[132:135], v[192:195], v[60:63]
	v_mfma_f32_16x16x32_bf16 v[56:59], v[158:161], v[192:195], v[56:59]
	v_mfma_f32_16x16x32_bf16 v[44:47], v[132:135], v[200:203], v[44:47]
	v_mfma_f32_16x16x32_bf16 v[40:43], v[158:161], v[200:203], v[40:43]
	v_mfma_f32_16x16x32_bf16 v[28:31], v[132:135], v[208:211], v[28:31]
	v_mfma_f32_16x16x32_bf16 v[24:27], v[158:161], v[208:211], v[24:27]
	v_mfma_f32_16x16x32_bf16 v[12:15], v[132:135], v[216:219], v[12:15]
	v_mfma_f32_16x16x32_bf16 v[8:11], v[158:161], v[216:219], v[8:11]
	s_setprio 0
	s_setprio 1
	v_mfma_f32_16x16x32_bf16 v[52:55], v[162:165], v[178:181], v[52:55]
	v_mfma_f32_16x16x32_bf16 v[48:51], v[170:173], v[178:181], v[48:51]
	v_mfma_f32_16x16x32_bf16 v[36:39], v[162:165], v[196:199], v[36:39]
	v_mfma_f32_16x16x32_bf16 v[32:35], v[170:173], v[196:199], v[32:35]
	v_mfma_f32_16x16x32_bf16 v[20:23], v[162:165], v[204:207], v[20:23]
	v_mfma_f32_16x16x32_bf16 v[16:19], v[170:173], v[204:207], v[16:19]
	v_mfma_f32_16x16x32_bf16 v[4:7], v[162:165], v[212:215], v[4:7]
	v_mfma_f32_16x16x32_bf16 v[0:3], v[170:173], v[212:215], v[0:3]
	v_mfma_f32_16x16x32_bf16 v[52:55], v[166:169], v[192:195], v[52:55]
	v_mfma_f32_16x16x32_bf16 v[48:51], v[174:177], v[192:195], v[48:51]
	v_mfma_f32_16x16x32_bf16 v[36:39], v[166:169], v[200:203], v[36:39]
	v_mfma_f32_16x16x32_bf16 v[32:35], v[174:177], v[200:203], v[32:35]
	v_mfma_f32_16x16x32_bf16 v[20:23], v[166:169], v[208:211], v[20:23]
	v_mfma_f32_16x16x32_bf16 v[16:19], v[174:177], v[208:211], v[16:19]
	v_mfma_f32_16x16x32_bf16 v[4:7], v[166:169], v[216:219], v[4:7]
	v_mfma_f32_16x16x32_bf16 v[0:3], v[174:177], v[216:219], v[0:3]
	s_setprio 0
	s_barrier
	s_add_u32 s0, s0, 0x100
	s_addc_u32 s1, s1, 0
	s_add_u32 s44, s44, 0x100
	s_addc_u32 s45, s45, 0
	s_cmp_ge_i32 s46, s33
	s_mov_b32 s6, s46
	s_cbranch_scc0 .LBB0_919
	s_nop 0

; #define PG8_STAGE(bufoff, gbase, voff) do { _Pragma("unroll") for (int _i = 0; _i < 2; ++_i) \
;         __builtin_amdgcn_global_load_lds((const unsigned*)((const char*)(gbase) + (voff)[_i]), (PG8_LAS unsigned*)(lds + (bufoff) + ldsw + _i * 8192), 16, 0, 0); } while (0)
; #define PG8_LDA(dst, b, h) do { _Pragma("unroll") for (int m = 0; m < 4; ++m) _Pragma("unroll") for (int k = 0; k < 2; ++k) dst[m][k] = *(const PG8_LAS bf16x8*)(lds + PG8_SA(b, h) + aoff + m * 2048 + k * 1024); } while (0)
; #define PG8_LDB(dst, b, h) do { _Pragma("unroll") for (int n = 0; n < 2; ++n) _Pragma("unroll") for (int k = 0; k < 2; ++k) dst[n][k] = *(const PG8_LAS bf16x8*)(lds + PG8_SB(b, h) + boff + n * 2048 + k * 1024); } while (0)
; #define PG8_MMA(ai, bj, At, Bt) do { __builtin_amdgcn_s_setprio(1); _Pragma("unroll") for (int m = 0; m < 4; ++m) _Pragma("unroll") for (int n = 0; n < 2; ++n) _Pragma("unroll") for (int k = 0; k < 2; ++k) \
;         acc[ai][bj][m][n] = __builtin_amdgcn_mfma_f32_16x16x32_bf16(Bt[n][k], At[m][k], acc[ai][bj][m][n], 0, 0, 0); __builtin_amdgcn_s_setprio(0); } while (0)
; #define PG8_WAIT_V(n) asm volatile("s_waitcnt vmcnt(" #n ")" ::: "memory")
; #define PG8_WAIT_L(n) asm volatile("s_waitcnt lgkmcnt(" #n ")" ::: "memory")
; #define PG8_BAR __builtin_amdgcn_s_barrier()
; template <class Epi, class Sched, bool ALIGN_EPI = false, bool SP2 = false>
; __device__ __forceinline__ void gemm_phase(PG8_LAS unsigned char* lds, const Gemm g, const Sched& S, const Epi& E) {
;     ...
;         const bool has_next = S.next(ui + 1, nxt);
;         const char* nA = has_next ? (const char*)g.A + (size_t)nxt.pm * tstep : cA; const char* nB = has_next ? (const char*)g.Bt + (size_t)nxt.pn * tstep : cB;
;         for (int t = 0; t < nt; t += 2) {
;             const bool last = (t == nt - 2);
;             const char* a1 = cA + (size_t)(t + 1) * kstep;
;             const char* a2 = last ? nA : cA + (size_t)(t + 2) * kstep; const char* b2 = last ? nB : cB + (size_t)(t + 2) * kstep;
;             const char* a3 = a2 + kstep; const char* b3 = b2 + kstep;
;             if (last && has_next) S.a_ready(nxt);
;             if constexpr (SP2) {
;             PG8_LDB(B0, 0, 0); PG8_LDB(B1, 0, 1); PG8_SCHED; PG8_LDA(At, 0, 0); PG8_STAGE(PG8_SA(1, 1), a1 + hstep, voffA);
;             PG8_WAIT_V(8); PG8_WAIT_L(0); PG8_BAR; PG8_MMA(0, 0, At, B0); PG8_MMA(0, 1, At, B1); PG8_BAR; PG8_SCHED;
.LBB0_1459:
	s_ashr_i32 s47, s46, 31
	s_lshl_b64 s[48:49], s[46:47], 19
	s_add_u32 s48, s61, s48
	s_addc_u32 s49, s62, s49
	s_and_b64 s[52:53], s[4:5], exec
	s_cselect_b32 s47, s49, s55
	s_cselect_b32 s81, s48, s54
	s_ashr_i32 s45, s44, 31
	s_lshl_b64 s[52:53], s[44:45], 19
	s_add_u32 s52, s63, s52
	s_addc_u32 s53, s64, s53
	s_and_b64 s[58:59], s[4:5], exec
	s_cselect_b32 s45, s53, s57
	s_cselect_b32 s82, s52, s56
	s_add_u32 s54, s54, 0x40080
	s_addc_u32 s55, s55, 0
	s_add_u32 s83, s56, 0x100
	s_addc_u32 s84, s57, 0
	s_mov_b32 s85, -2
	s_nop 0
	ds_read_b128 v[152:155], v147
	ds_read_b128 v[156:159], v147 offset:1024
	ds_read_b128 v[160:163], v147 offset:2048
	ds_read_b128 v[164:167], v147 offset:3072
	ds_read_b128 v[168:171], v148
	ds_read_b128 v[172:175], v148 offset:1024
	ds_read_b128 v[176:179], v148 offset:2048
	ds_read_b128 v[180:183], v148 offset:3072
	s_add_u32 s56, s54, 0xfffc0080
	s_addc_u32 s57, s55, -1
	s_cmp_eq_u32 s85, 12
	s_cselect_b32 s59, s47, s57
	s_cselect_b32 s58, s81, s56
	s_cselect_b32 s57, s45, s84
	s_cselect_b32 s56, s82, s83
	v_lshl_add_u64 v[216:217], s[54:55], 0, v[136:137]
	s_add_i32 m0, s43, 0xc000
	ds_read_b128 v[184:187], v149
	ds_read_b128 v[188:191], v149 offset:1024
	ds_read_b128 v[192:195], v149 offset:2048
	ds_read_b128 v[196:199], v149 offset:3072
	ds_read_b128 v[200:203], v149 offset:4096
	ds_read_b128 v[204:207], v149 offset:5120
	ds_read_b128 v[208:211], v149 offset:6144
	ds_read_b128 v[212:215], v149 offset:7168
	global_load_lds_dwordx4 v[216:217], off
	v_lshl_add_u64 v[216:217], s[54:55], 0, v[138:139]
	s_add_i32 m0, s43, 0xe000
	s_nop 0
	global_load_lds_dwordx4 v[216:217], off
	s_waitcnt vmcnt(8)
	s_waitcnt lgkmcnt(0)
	s_barrier
	s_setprio 1
	v_mfma_f32_16x16x32_bf16 v[124:127], v[152:155], v[184:187], 0
	v_mfma_f32_16x16x32_bf16 v[120:123], v[160:163], v[184:187], 0
	v_mfma_f32_16x16x32_bf16 v[116:119], v[152:155], v[192:195], 0
	v_mfma_f32_16x16x32_bf16 v[112:115], v[160:163], v[192:195], 0
	v_mfma_f32_16x16x32_bf16 v[100:103], v[152:155], v[200:203], 0
	v_mfma_f32_16x16x32_bf16 v[96:99], v[160:163], v[200:203], 0
	v_mfma_f32_16x16x32_bf16 v[84:87], v[152:155], v[208:211], 0
	v_mfma_f32_16x16x32_bf16 v[80:83], v[160:163], v[208:211], 0
	v_mfma_f32_16x16x32_bf16 v[124:127], v[156:159], v[188:191], v[124:127]
	v_mfma_f32_16x16x32_bf16 v[120:123], v[164:167], v[188:191], v[120:123]
	v_mfma_f32_16x16x32_bf16 v[116:119], v[156:159], v[196:199], v[116:119]
	v_mfma_f32_16x16x32_bf16 v[112:115], v[164:167], v[196:199], v[112:115]
	v_mfma_f32_16x16x32_bf16 v[100:103], v[156:159], v[204:207], v[100:103]
	v_mfma_f32_16x16x32_bf16 v[96:99], v[164:167], v[204:207], v[96:99]
	v_mfma_f32_16x16x32_bf16 v[84:87], v[156:159], v[212:215], v[84:87]
	v_mfma_f32_16x16x32_bf16 v[80:83], v[164:167], v[212:215], v[80:83]
	s_setprio 0
	s_setprio 1
	v_mfma_f32_16x16x32_bf16 v[108:111], v[168:171], v[184:187], 0
	v_mfma_f32_16x16x32_bf16 v[104:107], v[176:179], v[184:187], 0
	v_mfma_f32_16x16x32_bf16 v[92:95], v[168:171], v[192:195], 0
	v_mfma_f32_16x16x32_bf16 v[88:91], v[176:179], v[192:195], 0
	v_mfma_f32_16x16x32_bf16 v[76:79], v[168:171], v[200:203], 0
	v_mfma_f32_16x16x32_bf16 v[72:75], v[176:179], v[200:203], 0
	v_mfma_f32_16x16x32_bf16 v[68:71], v[168:171], v[208:211], 0
	v_mfma_f32_16x16x32_bf16 v[64:67], v[176:179], v[208:211], 0
	v_mfma_f32_16x16x32_bf16 v[108:111], v[172:175], v[188:191], v[108:111]
	v_mfma_f32_16x16x32_bf16 v[104:107], v[180:183], v[188:191], v[104:107]
	v_mfma_f32_16x16x32_bf16 v[92:95], v[172:175], v[196:199], v[92:95]
	v_mfma_f32_16x16x32_bf16 v[88:91], v[180:183], v[196:199], v[88:91]
	v_mfma_f32_16x16x32_bf16 v[76:79], v[172:175], v[204:207], v[76:79]
	v_mfma_f32_16x16x32_bf16 v[72:75], v[180:183], v[204:207], v[72:75]
	v_mfma_f32_16x16x32_bf16 v[68:71], v[172:175], v[212:215], v[68:71]
	v_mfma_f32_16x16x32_bf16 v[64:67], v[180:183], v[212:215], v[64:67]
	s_setprio 0
	s_barrier
	s_add_i32 s86, s72, s60
	v_lshl_add_u64 v[216:217], s[56:57], 0, v[130:131]
	s_mov_b32 m0, s86
	ds_read_b128 v[184:187], v149 offset:16384
	ds_read_b128 v[188:191], v149 offset:17408
	ds_read_b128 v[192:195], v149 offset:18432
	ds_read_b128 v[196:199], v149 offset:19456
	ds_read_b128 v[200:203], v149 offset:20480
	ds_read_b128 v[204:207], v149 offset:21504
	ds_read_b128 v[208:211], v149 offset:22528
	ds_read_b128 v[212:215], v149 offset:23552
	global_load_lds_dwordx4 v[216:217], off
	s_add_i32 m0, s86, 0x2000
	s_add_u32 s86, s56, 0x40000
	v_lshl_add_u64 v[218:219], s[56:57], 0, v[134:135]
	s_addc_u32 s87, s57, 0
	s_add_i32 s88, s73, s60
	global_load_lds_dwordx4 v[218:219], off
	v_lshl_add_u64 v[220:221], s[86:87], 0, v[130:131]
	s_mov_b32 m0, s88
	v_lshl_add_u64 v[222:223], s[58:59], 0, v[132:133]
	global_load_lds_dwordx4 v[220:221], off
	v_lshl_add_u64 v[220:221], s[86:87], 0, v[134:135]
	s_add_i32 m0, s88, 0x2000
	s_nop 0
	global_load_lds_dwordx4 v[220:221], off
	v_lshl_add_u64 v[220:221], s[58:59], 0, v[128:129]
	s_mov_b32 m0, s43
	s_nop 0
	global_load_lds_dwordx4 v[220:221], off
	s_mov_b32 m0, s50
	s_nop 0
	global_load_lds_dwordx4 v[222:223], off
	s_waitcnt vmcnt(8)
	s_waitcnt lgkmcnt(0)
	s_barrier
; #define PG8_STAGE(bufoff, gbase, voff) do { _Pragma("unroll") for (int _i = 0; _i < 2; ++_i) \
;         __builtin_amdgcn_global_load_lds((const unsigned*)((const char*)(gbase) + (voff)[_i]), (PG8_LAS unsigned*)(lds + (bufoff) + ldsw + _i * 8192), 16, 0, 0); } while (0)
; #define PG8_LDA(dst, b, h) do { _Pragma("unroll") for (int m = 0; m < 4; ++m) _Pragma("unroll") for (int k = 0; k < 2; ++k) dst[m][k] = *(const PG8_LAS bf16x8*)(lds + PG8_SA(b, h) + aoff + m * 2048 + k * 1024); } while (0)
; #define PG8_LDB(dst, b, h) do { _Pragma("unroll") for (int n = 0; n < 2; ++n) _Pragma("unroll") for (int k = 0; k < 2; ++k) dst[n][k] = *(const PG8_LAS bf16x8*)(lds + PG8_SB(b, h) + boff + n * 2048 + k * 1024); } while (0)
; #define PG8_MMA(ai, bj, At, Bt) do { __builtin_amdgcn_s_setprio(1); _Pragma("unroll") for (int m = 0; m < 4; ++m) _Pragma("unroll") for (int n = 0; n < 2; ++n) _Pragma("unroll") for (int k = 0; k < 2; ++k) \
;         acc[ai][bj][m][n] = __builtin_amdgcn_mfma_f32_16x16x32_bf16(Bt[n][k], At[m][k], acc[ai][bj][m][n], 0, 0, 0); __builtin_amdgcn_s_setprio(0); } while (0)
; #define PG8_WAIT_V(n) asm volatile("s_waitcnt vmcnt(" #n ")" ::: "memory")
; #define PG8_WAIT_L(n) asm volatile("s_waitcnt lgkmcnt(" #n ")" ::: "memory")
; #define PG8_BAR __builtin_amdgcn_s_barrier()
; #define PG8_SCHED __builtin_amdgcn_sched_barrier(0)
; template <class Epi, class Sched, bool ALIGN_EPI = false, bool SP2 = false>
; __device__ __forceinline__ void gemm_phase(PG8_LAS unsigned char* lds, const Gemm g, const Sched& S, const Epi& E) {
;     ...
;             PG8_WAIT_V(8); PG8_WAIT_L(0); PG8_BAR; PG8_MMA(1, 0, At, B0); PG8_MMA(1, 1, At, B1); PG8_BAR; PG8_SCHED;
;             PG8_LDB(B0, 1, 0); PG8_LDB(B1, 1, 1); PG8_SCHED; PG8_LDA(At, 1, 0); PG8_STAGE(PG8_SA(0, 1), a2 + hstep, voffA);
;             PG8_WAIT_V(8); PG8_WAIT_L(0); PG8_BAR; PG8_MMA(0, 0, At, B0); PG8_MMA(0, 1, At, B1); PG8_BAR; PG8_SCHED;
	s_setprio 1
	v_mfma_f32_16x16x32_bf16 v[60:63], v[152:155], v[184:187], 0
	v_mfma_f32_16x16x32_bf16 v[56:59], v[160:163], v[184:187], 0
	v_mfma_f32_16x16x32_bf16 v[52:55], v[152:155], v[192:195], 0
	v_mfma_f32_16x16x32_bf16 v[48:51], v[160:163], v[192:195], 0
	v_mfma_f32_16x16x32_bf16 v[36:39], v[152:155], v[200:203], 0
	v_mfma_f32_16x16x32_bf16 v[32:35], v[160:163], v[200:203], 0
	v_mfma_f32_16x16x32_bf16 v[20:23], v[152:155], v[208:211], 0
	v_mfma_f32_16x16x32_bf16 v[16:19], v[160:163], v[208:211], 0
	v_mfma_f32_16x16x32_bf16 v[60:63], v[156:159], v[188:191], v[60:63]
	v_mfma_f32_16x16x32_bf16 v[56:59], v[164:167], v[188:191], v[56:59]
	v_mfma_f32_16x16x32_bf16 v[52:55], v[156:159], v[196:199], v[52:55]
	v_mfma_f32_16x16x32_bf16 v[48:51], v[164:167], v[196:199], v[48:51]
	v_mfma_f32_16x16x32_bf16 v[36:39], v[156:159], v[204:207], v[36:39]
	v_mfma_f32_16x16x32_bf16 v[32:35], v[164:167], v[204:207], v[32:35]
	v_mfma_f32_16x16x32_bf16 v[20:23], v[156:159], v[212:215], v[20:23]
	v_mfma_f32_16x16x32_bf16 v[16:19], v[164:167], v[212:215], v[16:19]
	s_setprio 0
	s_setprio 1
	v_mfma_f32_16x16x32_bf16 v[44:47], v[168:171], v[184:187], 0
	v_mfma_f32_16x16x32_bf16 v[40:43], v[176:179], v[184:187], 0
	v_mfma_f32_16x16x32_bf16 v[28:31], v[168:171], v[192:195], 0
	v_mfma_f32_16x16x32_bf16 v[24:27], v[176:179], v[192:195], 0
	v_mfma_f32_16x16x32_bf16 v[12:15], v[168:171], v[200:203], 0
	v_mfma_f32_16x16x32_bf16 v[8:11], v[176:179], v[200:203], 0
	v_mfma_f32_16x16x32_bf16 v[4:7], v[168:171], v[208:211], 0
	v_mfma_f32_16x16x32_bf16 v[0:3], v[176:179], v[208:211], 0
	v_mfma_f32_16x16x32_bf16 v[44:47], v[172:175], v[188:191], v[44:47]
	v_mfma_f32_16x16x32_bf16 v[40:43], v[180:183], v[188:191], v[40:43]
	v_mfma_f32_16x16x32_bf16 v[28:31], v[172:175], v[196:199], v[28:31]
	v_mfma_f32_16x16x32_bf16 v[24:27], v[180:183], v[196:199], v[24:27]
	v_mfma_f32_16x16x32_bf16 v[12:15], v[172:175], v[204:207], v[12:15]
	v_mfma_f32_16x16x32_bf16 v[8:11], v[180:183], v[204:207], v[8:11]
	v_mfma_f32_16x16x32_bf16 v[4:7], v[172:175], v[212:215], v[4:7]
	v_mfma_f32_16x16x32_bf16 v[0:3], v[180:183], v[212:215], v[0:3]
	s_setprio 0
	s_barrier
	s_add_i32 s86, 0, 0x18000
	s_add_i32 s87, 0, 0x1c000
	v_add_u32_e32 v164, s86, v146
	v_add_u32_e32 v180, s87, v146
	ds_read_b128 v[152:155], v164
	ds_read_b128 v[156:159], v164 offset:1024
	ds_read_b128 v[160:163], v164 offset:2048
	ds_read_b128 v[164:167], v164 offset:3072
	ds_read_b128 v[168:171], v180
	ds_read_b128 v[172:175], v180 offset:1024
	ds_read_b128 v[176:179], v180 offset:2048
	ds_read_b128 v[180:183], v180 offset:3072
	s_add_u32 s58, s58, 0x40000
	s_addc_u32 s59, s59, 0
	s_mov_b32 m0, s51
	v_lshl_add_u64 v[224:225], s[58:59], 0, v[128:129]
	ds_read_b128 v[184:187], v149 offset:32768
	ds_read_b128 v[188:191], v149 offset:33792
	ds_read_b128 v[192:195], v149 offset:34816
	ds_read_b128 v[196:199], v149 offset:35840
	ds_read_b128 v[200:203], v149 offset:36864
	ds_read_b128 v[204:207], v149 offset:37888
	ds_read_b128 v[208:211], v149 offset:38912
	ds_read_b128 v[212:215], v149 offset:39936
	global_load_lds_dwordx4 v[224:225], off
	v_lshl_add_u64 v[224:225], s[58:59], 0, v[132:133]
	s_mov_b32 m0, s65
	s_nop 0
	global_load_lds_dwordx4 v[224:225], off
	s_waitcnt vmcnt(8)
	s_waitcnt lgkmcnt(0)
	s_barrier
	s_setprio 1
	v_mfma_f32_16x16x32_bf16 v[124:127], v[152:155], v[184:187], v[124:127]
	v_mfma_f32_16x16x32_bf16 v[120:123], v[160:163], v[184:187], v[120:123]
	v_mfma_f32_16x16x32_bf16 v[116:119], v[152:155], v[192:195], v[116:119]
	v_mfma_f32_16x16x32_bf16 v[112:115], v[160:163], v[192:195], v[112:115]
	v_mfma_f32_16x16x32_bf16 v[100:103], v[152:155], v[200:203], v[100:103]
	v_mfma_f32_16x16x32_bf16 v[96:99], v[160:163], v[200:203], v[96:99]
	v_mfma_f32_16x16x32_bf16 v[84:87], v[152:155], v[208:211], v[84:87]
	v_mfma_f32_16x16x32_bf16 v[80:83], v[160:163], v[208:211], v[80:83]
	v_mfma_f32_16x16x32_bf16 v[124:127], v[156:159], v[188:191], v[124:127]
	v_mfma_f32_16x16x32_bf16 v[120:123], v[164:167], v[188:191], v[120:123]
	v_mfma_f32_16x16x32_bf16 v[116:119], v[156:159], v[196:199], v[116:119]
	v_mfma_f32_16x16x32_bf16 v[112:115], v[164:167], v[196:199], v[112:115]
	v_mfma_f32_16x16x32_bf16 v[100:103], v[156:159], v[204:207], v[100:103]
	v_mfma_f32_16x16x32_bf16 v[96:99], v[164:167], v[204:207], v[96:99]
	v_mfma_f32_16x16x32_bf16 v[84:87], v[156:159], v[212:215], v[84:87]
	v_mfma_f32_16x16x32_bf16 v[80:83], v[164:167], v[212:215], v[80:83]
	s_setprio 0
	s_setprio 1
	v_mfma_f32_16x16x32_bf16 v[108:111], v[168:171], v[184:187], v[108:111]
	v_mfma_f32_16x16x32_bf16 v[104:107], v[176:179], v[184:187], v[104:107]
	v_mfma_f32_16x16x32_bf16 v[92:95], v[168:171], v[192:195], v[92:95]
	v_mfma_f32_16x16x32_bf16 v[88:91], v[176:179], v[192:195], v[88:91]
	v_mfma_f32_16x16x32_bf16 v[76:79], v[168:171], v[200:203], v[76:79]
	v_mfma_f32_16x16x32_bf16 v[72:75], v[176:179], v[200:203], v[72:75]
	v_mfma_f32_16x16x32_bf16 v[68:71], v[168:171], v[208:211], v[68:71]
	v_mfma_f32_16x16x32_bf16 v[64:67], v[176:179], v[208:211], v[64:67]
	v_mfma_f32_16x16x32_bf16 v[108:111], v[172:175], v[188:191], v[108:111]
	v_mfma_f32_16x16x32_bf16 v[104:107], v[180:183], v[188:191], v[104:107]
	v_mfma_f32_16x16x32_bf16 v[92:95], v[172:175], v[196:199], v[92:95]
	v_mfma_f32_16x16x32_bf16 v[88:91], v[180:183], v[196:199], v[88:91]
	v_mfma_f32_16x16x32_bf16 v[76:79], v[172:175], v[204:207], v[76:79]
	v_mfma_f32_16x16x32_bf16 v[72:75], v[180:183], v[204:207], v[72:75]
	v_mfma_f32_16x16x32_bf16 v[68:71], v[172:175], v[212:215], v[68:71]
	v_mfma_f32_16x16x32_bf16 v[64:67], v[180:183], v[212:215], v[64:67]
	s_setprio 0
	s_barrier
; #define PG8_STAGE(bufoff, gbase, voff) do { _Pragma("unroll") for (int _i = 0; _i < 2; ++_i) \
;         __builtin_amdgcn_global_load_lds((const unsigned*)((const char*)(gbase) + (voff)[_i]), (PG8_LAS unsigned*)(lds + (bufoff) + ldsw + _i * 8192), 16, 0, 0); } while (0)
; #define PG8_LDA(dst, b, h) do { _Pragma("unroll") for (int m = 0; m < 4; ++m) _Pragma("unroll") for (int k = 0; k < 2; ++k) dst[m][k] = *(const PG8_LAS bf16x8*)(lds + PG8_SA(b, h) + aoff + m * 2048 + k * 1024); } while (0)
; #define PG8_LDB(dst, b, h) do { _Pragma("unroll") for (int n = 0; n < 2; ++n) _Pragma("unroll") for (int k = 0; k < 2; ++k) dst[n][k] = *(const PG8_LAS bf16x8*)(lds + PG8_SB(b, h) + boff + n * 2048 + k * 1024); } while (0)
; #define PG8_MMA(ai, bj, At, Bt) do { __builtin_amdgcn_s_setprio(1); _Pragma("unroll") for (int m = 0; m < 4; ++m) _Pragma("unroll") for (int n = 0; n < 2; ++n) _Pragma("unroll") for (int k = 0; k < 2; ++k) \
;         acc[ai][bj][m][n] = __builtin_amdgcn_mfma_f32_16x16x32_bf16(Bt[n][k], At[m][k], acc[ai][bj][m][n], 0, 0, 0); __builtin_amdgcn_s_setprio(0); } while (0)
; #define PG8_WAIT_V(n) asm volatile("s_waitcnt vmcnt(" #n ")" ::: "memory")
; #define PG8_WAIT_L(n) asm volatile("s_waitcnt lgkmcnt(" #n ")" ::: "memory")
; #define PG8_BAR __builtin_amdgcn_s_barrier()
; #define PG8_SCHED __builtin_amdgcn_sched_barrier(0)
; template <class Epi, class Sched, bool ALIGN_EPI = false, bool SP2 = false>
; __device__ __forceinline__ void gemm_phase(PG8_LAS unsigned char* lds, const Gemm g, const Sched& S, const Epi& E) {
;     ...
;             PG8_LDB(B0, 0, 0); PG8_LDB(B1, 0, 1); PG8_SCHED; PG8_LDA(At, 0, 0); PG8_STAGE(PG8_SA(1, 1), a1 + hstep, voffA);
;             PG8_WAIT_V(8); PG8_WAIT_L(0); PG8_BAR; PG8_MMA(0, 0, At, B0); PG8_MMA(0, 1, At, B1); PG8_BAR; PG8_SCHED;
;     ...
;             PG8_LDA(At, 1, 1); PG8_STAGE(PG8_SB(1, 0), b3, voffB); PG8_STAGE(PG8_SB(1, 1), b3 + hstep, voffB); PG8_STAGE(PG8_SA(1, 0), a3, voffA);
;             PG8_WAIT_V(8); PG8_WAIT_L(0); PG8_BAR; PG8_MMA(1, 0, At, B0); PG8_MMA(1, 1, At, B1); PG8_BAR; PG8_SCHED;
	s_add_i32 s58, s86, s60
	v_lshl_add_u64 v[216:217], v[216:217], 0, s[10:11]
	s_mov_b32 m0, s58
	ds_read_b128 v[184:187], v149 offset:49152
	ds_read_b128 v[188:191], v149 offset:50176
	ds_read_b128 v[192:195], v149 offset:51200
	ds_read_b128 v[196:199], v149 offset:52224
	ds_read_b128 v[200:203], v149 offset:53248
	ds_read_b128 v[204:207], v149 offset:54272
	ds_read_b128 v[208:211], v149 offset:55296
	ds_read_b128 v[212:215], v149 offset:56320
	global_load_lds_dwordx4 v[216:217], off
	s_add_i32 m0, s58, 0x2000
	s_add_u32 s56, s56, 0x40080
	v_lshl_add_u64 v[216:217], v[218:219], 0, s[10:11]
	s_addc_u32 s57, s57, 0
	s_add_i32 s58, s87, s60
	global_load_lds_dwordx4 v[216:217], off
	v_lshl_add_u64 v[216:217], s[56:57], 0, v[130:131]
	s_mov_b32 m0, s58
	s_nop 0
	global_load_lds_dwordx4 v[216:217], off
	v_lshl_add_u64 v[216:217], s[56:57], 0, v[134:135]
	s_add_i32 m0, s58, 0x2000
	s_nop 0
	global_load_lds_dwordx4 v[216:217], off
	v_lshl_add_u64 v[216:217], v[220:221], 0, s[10:11]
	s_mov_b32 m0, s70
	s_nop 0
	global_load_lds_dwordx4 v[216:217], off
	v_lshl_add_u64 v[216:217], v[222:223], 0, s[10:11]
	s_mov_b32 m0, s71
	s_nop 0
	global_load_lds_dwordx4 v[216:217], off
	s_waitcnt vmcnt(8)
	s_waitcnt lgkmcnt(0)
	s_barrier
	s_setprio 1
	v_mfma_f32_16x16x32_bf16 v[60:63], v[152:155], v[184:187], v[60:63]
	v_mfma_f32_16x16x32_bf16 v[56:59], v[160:163], v[184:187], v[56:59]
	v_mfma_f32_16x16x32_bf16 v[52:55], v[152:155], v[192:195], v[52:55]
	v_mfma_f32_16x16x32_bf16 v[48:51], v[160:163], v[192:195], v[48:51]
	v_mfma_f32_16x16x32_bf16 v[36:39], v[152:155], v[200:203], v[36:39]
	v_mfma_f32_16x16x32_bf16 v[32:35], v[160:163], v[200:203], v[32:35]
	v_mfma_f32_16x16x32_bf16 v[20:23], v[152:155], v[208:211], v[20:23]
	v_mfma_f32_16x16x32_bf16 v[16:19], v[160:163], v[208:211], v[16:19]
	v_mfma_f32_16x16x32_bf16 v[60:63], v[156:159], v[188:191], v[60:63]
	v_mfma_f32_16x16x32_bf16 v[56:59], v[164:167], v[188:191], v[56:59]
	v_mfma_f32_16x16x32_bf16 v[52:55], v[156:159], v[196:199], v[52:55]
	v_mfma_f32_16x16x32_bf16 v[48:51], v[164:167], v[196:199], v[48:51]
	v_mfma_f32_16x16x32_bf16 v[36:39], v[156:159], v[204:207], v[36:39]
	v_mfma_f32_16x16x32_bf16 v[32:35], v[164:167], v[204:207], v[32:35]
	v_mfma_f32_16x16x32_bf16 v[20:23], v[156:159], v[212:215], v[20:23]
	v_mfma_f32_16x16x32_bf16 v[16:19], v[164:167], v[212:215], v[16:19]
	s_setprio 0
	s_setprio 1
	v_mfma_f32_16x16x32_bf16 v[44:47], v[168:171], v[184:187], v[44:47]
	v_mfma_f32_16x16x32_bf16 v[40:43], v[176:179], v[184:187], v[40:43]
	v_mfma_f32_16x16x32_bf16 v[28:31], v[168:171], v[192:195], v[28:31]
	v_mfma_f32_16x16x32_bf16 v[24:27], v[176:179], v[192:195], v[24:27]
	v_mfma_f32_16x16x32_bf16 v[12:15], v[168:171], v[200:203], v[12:15]
	v_mfma_f32_16x16x32_bf16 v[8:11], v[176:179], v[200:203], v[8:11]
	v_mfma_f32_16x16x32_bf16 v[4:7], v[168:171], v[208:211], v[4:7]
	v_mfma_f32_16x16x32_bf16 v[0:3], v[176:179], v[208:211], v[0:3]
	v_mfma_f32_16x16x32_bf16 v[44:47], v[172:175], v[188:191], v[44:47]
	v_mfma_f32_16x16x32_bf16 v[40:43], v[180:183], v[188:191], v[40:43]
	v_mfma_f32_16x16x32_bf16 v[28:31], v[172:175], v[196:199], v[28:31]
	v_mfma_f32_16x16x32_bf16 v[24:27], v[180:183], v[196:199], v[24:27]
	v_mfma_f32_16x16x32_bf16 v[12:15], v[172:175], v[204:207], v[12:15]
	v_mfma_f32_16x16x32_bf16 v[8:11], v[180:183], v[204:207], v[8:11]
	v_mfma_f32_16x16x32_bf16 v[4:7], v[172:175], v[212:215], v[4:7]
	v_mfma_f32_16x16x32_bf16 v[0:3], v[180:183], v[212:215], v[0:3]
	s_setprio 0
	s_barrier
	s_add_i32 s85, s85, 2
	s_add_u32 s54, s54, 0x100
	s_addc_u32 s55, s55, 0
	s_add_u32 s83, s83, 0x100
	s_addc_u32 s84, s84, 0
	s_cmp_gt_u32 s85, 13
.LBB0_1460:
	ds_read_b128 v[152:155], v147
	ds_read_b128 v[156:159], v147 offset:1024
	ds_read_b128 v[160:163], v147 offset:2048
	ds_read_b128 v[164:167], v147 offset:3072
	ds_read_b128 v[168:171], v148
	ds_read_b128 v[172:175], v148 offset:1024
	ds_read_b128 v[176:179], v148 offset:2048
	ds_read_b128 v[180:183], v148 offset:3072
	s_add_u32 s56, s54, 0xfffc0080
	s_addc_u32 s57, s55, -1
	s_cmp_eq_u32 s85, 12
	s_cselect_b32 s59, s47, s57
	s_cselect_b32 s58, s81, s56
	s_cselect_b32 s57, s45, s84
	s_cselect_b32 s56, s82, s83
	v_lshl_add_u64 v[216:217], s[54:55], 0, v[136:137]
	s_add_i32 m0, s43, 0xc000
	ds_read_b128 v[184:187], v149
	ds_read_b128 v[188:191], v149 offset:1024
	ds_read_b128 v[192:195], v149 offset:2048
	ds_read_b128 v[196:199], v149 offset:3072
	ds_read_b128 v[200:203], v149 offset:4096
	ds_read_b128 v[204:207], v149 offset:5120
	ds_read_b128 v[208:211], v149 offset:6144
	ds_read_b128 v[212:215], v149 offset:7168
	global_load_lds_dwordx4 v[216:217], off
	v_lshl_add_u64 v[216:217], s[54:55], 0, v[138:139]
	s_add_i32 m0, s43, 0xe000
	s_nop 0
	global_load_lds_dwordx4 v[216:217], off
	s_waitcnt vmcnt(8)
	s_waitcnt lgkmcnt(0)
	s_barrier
; #define PG8_STAGE(bufoff, gbase, voff) do { _Pragma("unroll") for (int _i = 0; _i < 2; ++_i) \
;         __builtin_amdgcn_global_load_lds((const unsigned*)((const char*)(gbase) + (voff)[_i]), (PG8_LAS unsigned*)(lds + (bufoff) + ldsw + _i * 8192), 16, 0, 0); } while (0)
; #define PG8_LDA(dst, b, h) do { _Pragma("unroll") for (int m = 0; m < 4; ++m) _Pragma("unroll") for (int k = 0; k < 2; ++k) dst[m][k] = *(const PG8_LAS bf16x8*)(lds + PG8_SA(b, h) + aoff + m * 2048 + k * 1024); } while (0)
; #define PG8_MMA(ai, bj, At, Bt) do { __builtin_amdgcn_s_setprio(1); _Pragma("unroll") for (int m = 0; m < 4; ++m) _Pragma("unroll") for (int n = 0; n < 2; ++n) _Pragma("unroll") for (int k = 0; k < 2; ++k) \
;         acc[ai][bj][m][n] = __builtin_amdgcn_mfma_f32_16x16x32_bf16(Bt[n][k], At[m][k], acc[ai][bj][m][n], 0, 0, 0); __builtin_amdgcn_s_setprio(0); } while (0)
; #define PG8_WAIT_V(n) asm volatile("s_waitcnt vmcnt(" #n ")" ::: "memory")
; #define PG8_WAIT_L(n) asm volatile("s_waitcnt lgkmcnt(" #n ")" ::: "memory")
; #define PG8_BAR __builtin_amdgcn_s_barrier()
; #define PG8_SCHED __builtin_amdgcn_sched_barrier(0)
; template <class Epi, class Sched, bool ALIGN_EPI = false, bool SP2 = false>
; __device__ __forceinline__ void gemm_phase(PG8_LAS unsigned char* lds, const Gemm g, const Sched& S, const Epi& E) {
;     ...
;             PG8_WAIT_V(8); PG8_WAIT_L(0); PG8_BAR; PG8_MMA(0, 0, At, B0); PG8_MMA(0, 1, At, B1); PG8_BAR; PG8_SCHED;
;             PG8_LDA(At, 0, 1); PG8_STAGE(PG8_SB(0, 0), b2, voffB); PG8_STAGE(PG8_SB(0, 1), b2 + hstep, voffB); PG8_STAGE(PG8_SA(0, 0), a2, voffA);
;             PG8_WAIT_V(8); PG8_WAIT_L(0); PG8_BAR; PG8_MMA(1, 0, At, B0); PG8_MMA(1, 1, At, B1); PG8_BAR; PG8_SCHED;
	s_setprio 1
	v_mfma_f32_16x16x32_bf16 v[124:127], v[152:155], v[184:187], v[124:127]
	v_mfma_f32_16x16x32_bf16 v[120:123], v[160:163], v[184:187], v[120:123]
	v_mfma_f32_16x16x32_bf16 v[116:119], v[152:155], v[192:195], v[116:119]
	v_mfma_f32_16x16x32_bf16 v[112:115], v[160:163], v[192:195], v[112:115]
	v_mfma_f32_16x16x32_bf16 v[100:103], v[152:155], v[200:203], v[100:103]
	v_mfma_f32_16x16x32_bf16 v[96:99], v[160:163], v[200:203], v[96:99]
	v_mfma_f32_16x16x32_bf16 v[84:87], v[152:155], v[208:211], v[84:87]
	v_mfma_f32_16x16x32_bf16 v[80:83], v[160:163], v[208:211], v[80:83]
	v_mfma_f32_16x16x32_bf16 v[124:127], v[156:159], v[188:191], v[124:127]
	v_mfma_f32_16x16x32_bf16 v[120:123], v[164:167], v[188:191], v[120:123]
	v_mfma_f32_16x16x32_bf16 v[116:119], v[156:159], v[196:199], v[116:119]
	v_mfma_f32_16x16x32_bf16 v[112:115], v[164:167], v[196:199], v[112:115]
	v_mfma_f32_16x16x32_bf16 v[100:103], v[156:159], v[204:207], v[100:103]
	v_mfma_f32_16x16x32_bf16 v[96:99], v[164:167], v[204:207], v[96:99]
	v_mfma_f32_16x16x32_bf16 v[84:87], v[156:159], v[212:215], v[84:87]
	v_mfma_f32_16x16x32_bf16 v[80:83], v[164:167], v[212:215], v[80:83]
	s_setprio 0
	s_setprio 1
	v_mfma_f32_16x16x32_bf16 v[108:111], v[168:171], v[184:187], v[108:111]
	v_mfma_f32_16x16x32_bf16 v[104:107], v[176:179], v[184:187], v[104:107]
	v_mfma_f32_16x16x32_bf16 v[92:95], v[168:171], v[192:195], v[92:95]
	v_mfma_f32_16x16x32_bf16 v[88:91], v[176:179], v[192:195], v[88:91]
	v_mfma_f32_16x16x32_bf16 v[76:79], v[168:171], v[200:203], v[76:79]
	v_mfma_f32_16x16x32_bf16 v[72:75], v[176:179], v[200:203], v[72:75]
	v_mfma_f32_16x16x32_bf16 v[68:71], v[168:171], v[208:211], v[68:71]
	v_mfma_f32_16x16x32_bf16 v[64:67], v[176:179], v[208:211], v[64:67]
	v_mfma_f32_16x16x32_bf16 v[108:111], v[172:175], v[188:191], v[108:111]
	v_mfma_f32_16x16x32_bf16 v[104:107], v[180:183], v[188:191], v[104:107]
	v_mfma_f32_16x16x32_bf16 v[92:95], v[172:175], v[196:199], v[92:95]
	v_mfma_f32_16x16x32_bf16 v[88:91], v[180:183], v[196:199], v[88:91]
	v_mfma_f32_16x16x32_bf16 v[76:79], v[172:175], v[204:207], v[76:79]
	v_mfma_f32_16x16x32_bf16 v[72:75], v[180:183], v[204:207], v[72:75]
	v_mfma_f32_16x16x32_bf16 v[68:71], v[172:175], v[212:215], v[68:71]
	v_mfma_f32_16x16x32_bf16 v[64:67], v[180:183], v[212:215], v[64:67]
	s_setprio 0
	s_barrier
	s_add_i32 s86, s72, s60
	v_lshl_add_u64 v[216:217], s[56:57], 0, v[130:131]
	s_mov_b32 m0, s86
	ds_read_b128 v[184:187], v149 offset:16384
	ds_read_b128 v[188:191], v149 offset:17408
	ds_read_b128 v[192:195], v149 offset:18432
	ds_read_b128 v[196:199], v149 offset:19456
	ds_read_b128 v[200:203], v149 offset:20480
	ds_read_b128 v[204:207], v149 offset:21504
	ds_read_b128 v[208:211], v149 offset:22528
	ds_read_b128 v[212:215], v149 offset:23552
	global_load_lds_dwordx4 v[216:217], off
	s_add_i32 m0, s86, 0x2000
	s_add_u32 s86, s56, 0x40000
	v_lshl_add_u64 v[218:219], s[56:57], 0, v[134:135]
	s_addc_u32 s87, s57, 0
	s_add_i32 s88, s73, s60
	global_load_lds_dwordx4 v[218:219], off
	v_lshl_add_u64 v[220:221], s[86:87], 0, v[130:131]
	s_mov_b32 m0, s88
	v_lshl_add_u64 v[222:223], s[58:59], 0, v[132:133]
	global_load_lds_dwordx4 v[220:221], off
	v_lshl_add_u64 v[220:221], s[86:87], 0, v[134:135]
	s_add_i32 m0, s88, 0x2000
	s_nop 0
	global_load_lds_dwordx4 v[220:221], off
	v_lshl_add_u64 v[220:221], s[58:59], 0, v[128:129]
	s_mov_b32 m0, s43
	s_nop 0
	global_load_lds_dwordx4 v[220:221], off
	s_mov_b32 m0, s50
	s_nop 0
	global_load_lds_dwordx4 v[222:223], off
	s_waitcnt vmcnt(8)
	s_waitcnt lgkmcnt(0)
	s_barrier
	s_setprio 1
	v_mfma_f32_16x16x32_bf16 v[60:63], v[152:155], v[184:187], v[60:63]
	v_mfma_f32_16x16x32_bf16 v[56:59], v[160:163], v[184:187], v[56:59]
	v_mfma_f32_16x16x32_bf16 v[52:55], v[152:155], v[192:195], v[52:55]
	v_mfma_f32_16x16x32_bf16 v[48:51], v[160:163], v[192:195], v[48:51]
	v_mfma_f32_16x16x32_bf16 v[36:39], v[152:155], v[200:203], v[36:39]
	v_mfma_f32_16x16x32_bf16 v[32:35], v[160:163], v[200:203], v[32:35]
	v_mfma_f32_16x16x32_bf16 v[20:23], v[152:155], v[208:211], v[20:23]
	v_mfma_f32_16x16x32_bf16 v[16:19], v[160:163], v[208:211], v[16:19]
	v_mfma_f32_16x16x32_bf16 v[60:63], v[156:159], v[188:191], v[60:63]
	v_mfma_f32_16x16x32_bf16 v[56:59], v[164:167], v[188:191], v[56:59]
	v_mfma_f32_16x16x32_bf16 v[52:55], v[156:159], v[196:199], v[52:55]
	v_mfma_f32_16x16x32_bf16 v[48:51], v[164:167], v[196:199], v[48:51]
	v_mfma_f32_16x16x32_bf16 v[36:39], v[156:159], v[204:207], v[36:39]
	v_mfma_f32_16x16x32_bf16 v[32:35], v[164:167], v[204:207], v[32:35]
	v_mfma_f32_16x16x32_bf16 v[20:23], v[156:159], v[212:215], v[20:23]
	v_mfma_f32_16x16x32_bf16 v[16:19], v[164:167], v[212:215], v[16:19]
	s_setprio 0
	s_setprio 1
	v_mfma_f32_16x16x32_bf16 v[44:47], v[168:171], v[184:187], v[44:47]
	v_mfma_f32_16x16x32_bf16 v[40:43], v[176:179], v[184:187], v[40:43]
	v_mfma_f32_16x16x32_bf16 v[28:31], v[168:171], v[192:195], v[28:31]
	v_mfma_f32_16x16x32_bf16 v[24:27], v[176:179], v[192:195], v[24:27]
	v_mfma_f32_16x16x32_bf16 v[12:15], v[168:171], v[200:203], v[12:15]
	v_mfma_f32_16x16x32_bf16 v[8:11], v[176:179], v[200:203], v[8:11]
	v_mfma_f32_16x16x32_bf16 v[4:7], v[168:171], v[208:211], v[4:7]
	v_mfma_f32_16x16x32_bf16 v[0:3], v[176:179], v[208:211], v[0:3]
	v_mfma_f32_16x16x32_bf16 v[44:47], v[172:175], v[188:191], v[44:47]
	v_mfma_f32_16x16x32_bf16 v[40:43], v[180:183], v[188:191], v[40:43]
	v_mfma_f32_16x16x32_bf16 v[28:31], v[172:175], v[196:199], v[28:31]
	v_mfma_f32_16x16x32_bf16 v[24:27], v[180:183], v[196:199], v[24:27]
	v_mfma_f32_16x16x32_bf16 v[12:15], v[172:175], v[204:207], v[12:15]
	v_mfma_f32_16x16x32_bf16 v[8:11], v[180:183], v[204:207], v[8:11]
	v_mfma_f32_16x16x32_bf16 v[4:7], v[172:175], v[212:215], v[4:7]
	v_mfma_f32_16x16x32_bf16 v[0:3], v[180:183], v[212:215], v[0:3]
	s_setprio 0
	s_barrier
; #define PG8_STAGE(bufoff, gbase, voff) do { _Pragma("unroll") for (int _i = 0; _i < 2; ++_i) \
;         __builtin_amdgcn_global_load_lds((const unsigned*)((const char*)(gbase) + (voff)[_i]), (PG8_LAS unsigned*)(lds + (bufoff) + ldsw + _i * 8192), 16, 0, 0); } while (0)
; #define PG8_LDA(dst, b, h) do { _Pragma("unroll") for (int m = 0; m < 4; ++m) _Pragma("unroll") for (int k = 0; k < 2; ++k) dst[m][k] = *(const PG8_LAS bf16x8*)(lds + PG8_SA(b, h) + aoff + m * 2048 + k * 1024); } while (0)
; #define PG8_LDB(dst, b, h) do { _Pragma("unroll") for (int n = 0; n < 2; ++n) _Pragma("unroll") for (int k = 0; k < 2; ++k) dst[n][k] = *(const PG8_LAS bf16x8*)(lds + PG8_SB(b, h) + boff + n * 2048 + k * 1024); } while (0)
; #define PG8_MMA(ai, bj, At, Bt) do { __builtin_amdgcn_s_setprio(1); _Pragma("unroll") for (int m = 0; m < 4; ++m) _Pragma("unroll") for (int n = 0; n < 2; ++n) _Pragma("unroll") for (int k = 0; k < 2; ++k) \
;         acc[ai][bj][m][n] = __builtin_amdgcn_mfma_f32_16x16x32_bf16(Bt[n][k], At[m][k], acc[ai][bj][m][n], 0, 0, 0); __builtin_amdgcn_s_setprio(0); } while (0)
; #define PG8_WAIT_V(n) asm volatile("s_waitcnt vmcnt(" #n ")" ::: "memory")
; #define PG8_WAIT_L(n) asm volatile("s_waitcnt lgkmcnt(" #n ")" ::: "memory")
; #define PG8_BAR __builtin_amdgcn_s_barrier()
; #define PG8_SCHED __builtin_amdgcn_sched_barrier(0)
; template <class Epi, class Sched, bool ALIGN_EPI = false, bool SP2 = false>
; __device__ __forceinline__ void gemm_phase(PG8_LAS unsigned char* lds, const Gemm g, const Sched& S, const Epi& E) {
;     ...
;             PG8_LDB(B0, 1, 0); PG8_LDB(B1, 1, 1); PG8_SCHED; PG8_LDA(At, 1, 0); PG8_STAGE(PG8_SA(0, 1), a2 + hstep, voffA);
;             PG8_WAIT_V(8); PG8_WAIT_L(0); PG8_BAR; PG8_MMA(0, 0, At, B0); PG8_MMA(0, 1, At, B1); PG8_BAR; PG8_SCHED;
	s_add_i32 s86, 0, 0x18000
	s_add_i32 s87, 0, 0x1c000
	v_add_u32_e32 v164, s86, v146
	v_add_u32_e32 v180, s87, v146
	ds_read_b128 v[152:155], v164
	ds_read_b128 v[156:159], v164 offset:1024
	ds_read_b128 v[160:163], v164 offset:2048
	ds_read_b128 v[164:167], v164 offset:3072
	ds_read_b128 v[168:171], v180
	ds_read_b128 v[172:175], v180 offset:1024
	ds_read_b128 v[176:179], v180 offset:2048
	ds_read_b128 v[180:183], v180 offset:3072
	s_add_u32 s58, s58, 0x40000
	s_addc_u32 s59, s59, 0
	s_mov_b32 m0, s51
	v_lshl_add_u64 v[224:225], s[58:59], 0, v[128:129]
	ds_read_b128 v[184:187], v149 offset:32768
	ds_read_b128 v[188:191], v149 offset:33792
	ds_read_b128 v[192:195], v149 offset:34816
	ds_read_b128 v[196:199], v149 offset:35840
	ds_read_b128 v[200:203], v149 offset:36864
	ds_read_b128 v[204:207], v149 offset:37888
	ds_read_b128 v[208:211], v149 offset:38912
	ds_read_b128 v[212:215], v149 offset:39936
	global_load_lds_dwordx4 v[224:225], off
	v_lshl_add_u64 v[224:225], s[58:59], 0, v[132:133]
	s_mov_b32 m0, s65
	s_nop 0
	global_load_lds_dwordx4 v[224:225], off
	s_waitcnt vmcnt(8)
	s_waitcnt lgkmcnt(0)
	s_barrier
	s_setprio 1
	v_mfma_f32_16x16x32_bf16 v[124:127], v[152:155], v[184:187], v[124:127]
	v_mfma_f32_16x16x32_bf16 v[120:123], v[160:163], v[184:187], v[120:123]
	v_mfma_f32_16x16x32_bf16 v[116:119], v[152:155], v[192:195], v[116:119]
	v_mfma_f32_16x16x32_bf16 v[112:115], v[160:163], v[192:195], v[112:115]
	v_mfma_f32_16x16x32_bf16 v[100:103], v[152:155], v[200:203], v[100:103]
	v_mfma_f32_16x16x32_bf16 v[96:99], v[160:163], v[200:203], v[96:99]
	v_mfma_f32_16x16x32_bf16 v[84:87], v[152:155], v[208:211], v[84:87]
	v_mfma_f32_16x16x32_bf16 v[80:83], v[160:163], v[208:211], v[80:83]
	v_mfma_f32_16x16x32_bf16 v[124:127], v[156:159], v[188:191], v[124:127]
	v_mfma_f32_16x16x32_bf16 v[120:123], v[164:167], v[188:191], v[120:123]
	v_mfma_f32_16x16x32_bf16 v[116:119], v[156:159], v[196:199], v[116:119]
	v_mfma_f32_16x16x32_bf16 v[112:115], v[164:167], v[196:199], v[112:115]
	v_mfma_f32_16x16x32_bf16 v[100:103], v[156:159], v[204:207], v[100:103]
	v_mfma_f32_16x16x32_bf16 v[96:99], v[164:167], v[204:207], v[96:99]
	v_mfma_f32_16x16x32_bf16 v[84:87], v[156:159], v[212:215], v[84:87]
	v_mfma_f32_16x16x32_bf16 v[80:83], v[164:167], v[212:215], v[80:83]
	s_setprio 0
	s_setprio 1
	v_mfma_f32_16x16x32_bf16 v[108:111], v[168:171], v[184:187], v[108:111]
	v_mfma_f32_16x16x32_bf16 v[104:107], v[176:179], v[184:187], v[104:107]
	v_mfma_f32_16x16x32_bf16 v[92:95], v[168:171], v[192:195], v[92:95]
	v_mfma_f32_16x16x32_bf16 v[88:91], v[176:179], v[192:195], v[88:91]
	v_mfma_f32_16x16x32_bf16 v[76:79], v[168:171], v[200:203], v[76:79]
	v_mfma_f32_16x16x32_bf16 v[72:75], v[176:179], v[200:203], v[72:75]
	v_mfma_f32_16x16x32_bf16 v[68:71], v[168:171], v[208:211], v[68:71]
	v_mfma_f32_16x16x32_bf16 v[64:67], v[176:179], v[208:211], v[64:67]
	v_mfma_f32_16x16x32_bf16 v[108:111], v[172:175], v[188:191], v[108:111]
	v_mfma_f32_16x16x32_bf16 v[104:107], v[180:183], v[188:191], v[104:107]
	v_mfma_f32_16x16x32_bf16 v[92:95], v[172:175], v[196:199], v[92:95]
	v_mfma_f32_16x16x32_bf16 v[88:91], v[180:183], v[196:199], v[88:91]
	v_mfma_f32_16x16x32_bf16 v[76:79], v[172:175], v[204:207], v[76:79]
	v_mfma_f32_16x16x32_bf16 v[72:75], v[180:183], v[204:207], v[72:75]
	v_mfma_f32_16x16x32_bf16 v[68:71], v[172:175], v[212:215], v[68:71]
	v_mfma_f32_16x16x32_bf16 v[64:67], v[180:183], v[212:215], v[64:67]
	s_setprio 0
	s_barrier
; #define PG8_STAGE(bufoff, gbase, voff) do { _Pragma("unroll") for (int _i = 0; _i < 2; ++_i) \
;         __builtin_amdgcn_global_load_lds((const unsigned*)((const char*)(gbase) + (voff)[_i]), (PG8_LAS unsigned*)(lds + (bufoff) + ldsw + _i * 8192), 16, 0, 0); } while (0)
; #define PG8_LDA(dst, b, h) do { _Pragma("unroll") for (int m = 0; m < 4; ++m) _Pragma("unroll") for (int k = 0; k < 2; ++k) dst[m][k] = *(const PG8_LAS bf16x8*)(lds + PG8_SA(b, h) + aoff + m * 2048 + k * 1024); } while (0)
; #define PG8_MMA(ai, bj, At, Bt) do { __builtin_amdgcn_s_setprio(1); _Pragma("unroll") for (int m = 0; m < 4; ++m) _Pragma("unroll") for (int n = 0; n < 2; ++n) _Pragma("unroll") for (int k = 0; k < 2; ++k) \
;         acc[ai][bj][m][n] = __builtin_amdgcn_mfma_f32_16x16x32_bf16(Bt[n][k], At[m][k], acc[ai][bj][m][n], 0, 0, 0); __builtin_amdgcn_s_setprio(0); } while (0)
; #define PG8_WAIT_V(n) asm volatile("s_waitcnt vmcnt(" #n ")" ::: "memory")
; #define PG8_WAIT_L(n) asm volatile("s_waitcnt lgkmcnt(" #n ")" ::: "memory")
; #define PG8_BAR __builtin_amdgcn_s_barrier()
; #define PG8_SCHED __builtin_amdgcn_sched_barrier(0)
; template <class Epi, class Sched, bool ALIGN_EPI = false, bool SP2 = false>
; __device__ __forceinline__ void gemm_phase(PG8_LAS unsigned char* lds, const Gemm g, const Sched& S, const Epi& E) {
;     ...
;             PG8_LDA(At, 1, 1); PG8_STAGE(PG8_SB(1, 0), b3, voffB); PG8_STAGE(PG8_SB(1, 1), b3 + hstep, voffB); PG8_STAGE(PG8_SA(1, 0), a3, voffA);
;             PG8_WAIT_V(8); PG8_WAIT_L(0); PG8_BAR; PG8_MMA(1, 0, At, B0); PG8_MMA(1, 1, At, B1); PG8_BAR; PG8_SCHED;
;     ...
;         if constexpr (ALIGN_EPI) { if (wr == 0) PG8_BAR; }
	s_add_i32 s58, s86, s60
	v_lshl_add_u64 v[216:217], v[216:217], 0, s[10:11]
	s_mov_b32 m0, s58
	ds_read_b128 v[184:187], v149 offset:49152
	ds_read_b128 v[188:191], v149 offset:50176
	ds_read_b128 v[192:195], v149 offset:51200
	ds_read_b128 v[196:199], v149 offset:52224
	ds_read_b128 v[200:203], v149 offset:53248
	ds_read_b128 v[204:207], v149 offset:54272
	ds_read_b128 v[208:211], v149 offset:55296
	ds_read_b128 v[212:215], v149 offset:56320
	global_load_lds_dwordx4 v[216:217], off
	s_add_i32 m0, s58, 0x2000
	s_add_u32 s56, s56, 0x40080
	v_lshl_add_u64 v[216:217], v[218:219], 0, s[10:11]
	s_addc_u32 s57, s57, 0
	s_add_i32 s58, s87, s60
	global_load_lds_dwordx4 v[216:217], off
	v_lshl_add_u64 v[216:217], s[56:57], 0, v[130:131]
	s_mov_b32 m0, s58
	s_nop 0
	global_load_lds_dwordx4 v[216:217], off
	v_lshl_add_u64 v[216:217], s[56:57], 0, v[134:135]
	s_add_i32 m0, s58, 0x2000
	s_nop 0
	global_load_lds_dwordx4 v[216:217], off
	v_lshl_add_u64 v[216:217], v[220:221], 0, s[10:11]
	s_mov_b32 m0, s70
	s_nop 0
	global_load_lds_dwordx4 v[216:217], off
	v_lshl_add_u64 v[216:217], v[222:223], 0, s[10:11]
	s_mov_b32 m0, s71
	s_nop 0
	global_load_lds_dwordx4 v[216:217], off
	s_waitcnt vmcnt(8)
	s_waitcnt lgkmcnt(0)
	s_barrier
	s_setprio 1
	v_mfma_f32_16x16x32_bf16 v[60:63], v[152:155], v[184:187], v[60:63]
	v_mfma_f32_16x16x32_bf16 v[56:59], v[160:163], v[184:187], v[56:59]
	v_mfma_f32_16x16x32_bf16 v[52:55], v[152:155], v[192:195], v[52:55]
	v_mfma_f32_16x16x32_bf16 v[48:51], v[160:163], v[192:195], v[48:51]
	v_mfma_f32_16x16x32_bf16 v[36:39], v[152:155], v[200:203], v[36:39]
	v_mfma_f32_16x16x32_bf16 v[32:35], v[160:163], v[200:203], v[32:35]
	v_mfma_f32_16x16x32_bf16 v[20:23], v[152:155], v[208:211], v[20:23]
	v_mfma_f32_16x16x32_bf16 v[16:19], v[160:163], v[208:211], v[16:19]
	v_mfma_f32_16x16x32_bf16 v[60:63], v[156:159], v[188:191], v[60:63]
	v_mfma_f32_16x16x32_bf16 v[56:59], v[164:167], v[188:191], v[56:59]
	v_mfma_f32_16x16x32_bf16 v[52:55], v[156:159], v[196:199], v[52:55]
	v_mfma_f32_16x16x32_bf16 v[48:51], v[164:167], v[196:199], v[48:51]
	v_mfma_f32_16x16x32_bf16 v[36:39], v[156:159], v[204:207], v[36:39]
	v_mfma_f32_16x16x32_bf16 v[32:35], v[164:167], v[204:207], v[32:35]
	v_mfma_f32_16x16x32_bf16 v[20:23], v[156:159], v[212:215], v[20:23]
	v_mfma_f32_16x16x32_bf16 v[16:19], v[164:167], v[212:215], v[16:19]
	s_setprio 0
	s_setprio 1
	v_mfma_f32_16x16x32_bf16 v[44:47], v[168:171], v[184:187], v[44:47]
	v_mfma_f32_16x16x32_bf16 v[40:43], v[176:179], v[184:187], v[40:43]
	v_mfma_f32_16x16x32_bf16 v[28:31], v[168:171], v[192:195], v[28:31]
	v_mfma_f32_16x16x32_bf16 v[24:27], v[176:179], v[192:195], v[24:27]
	v_mfma_f32_16x16x32_bf16 v[12:15], v[168:171], v[200:203], v[12:15]
	v_mfma_f32_16x16x32_bf16 v[8:11], v[176:179], v[200:203], v[8:11]
	v_mfma_f32_16x16x32_bf16 v[4:7], v[168:171], v[208:211], v[4:7]
	v_mfma_f32_16x16x32_bf16 v[0:3], v[176:179], v[208:211], v[0:3]
	v_mfma_f32_16x16x32_bf16 v[44:47], v[172:175], v[188:191], v[44:47]
	v_mfma_f32_16x16x32_bf16 v[40:43], v[180:183], v[188:191], v[40:43]
	v_mfma_f32_16x16x32_bf16 v[28:31], v[172:175], v[196:199], v[28:31]
	v_mfma_f32_16x16x32_bf16 v[24:27], v[180:183], v[196:199], v[24:27]
	v_mfma_f32_16x16x32_bf16 v[12:15], v[172:175], v[204:207], v[12:15]
	v_mfma_f32_16x16x32_bf16 v[8:11], v[180:183], v[204:207], v[8:11]
	v_mfma_f32_16x16x32_bf16 v[4:7], v[172:175], v[212:215], v[4:7]
	v_mfma_f32_16x16x32_bf16 v[0:3], v[180:183], v[212:215], v[0:3]
	s_setprio 0
	s_barrier
	s_add_i32 s85, s85, 2
	s_add_u32 s54, s54, 0x100
	s_addc_u32 s55, s55, 0
	s_add_u32 s83, s83, 0x100
	s_addc_u32 s84, s84, 0
	s_cmp_gt_u32 s85, 13
	s_cbranch_scc0 .LBB0_1460
	s_nop 0
	s_and_b64 vcc, exec, s[12:13]
	s_cbranch_vccz .LBB0_1463
	s_barrier

; #define PG8_STAGE(bufoff, gbase, voff) do { _Pragma("unroll") for (int _i = 0; _i < 2; ++_i) \
;         __builtin_amdgcn_global_load_lds((const unsigned*)((const char*)(gbase) + (voff)[_i]), (PG8_LAS unsigned*)(lds + (bufoff) + ldsw + _i * 8192), 16, 0, 0); } while (0)
; #define PG8_LDA(dst, b, h) do { _Pragma("unroll") for (int m = 0; m < 4; ++m) _Pragma("unroll") for (int k = 0; k < 2; ++k) dst[m][k] = *(const PG8_LAS bf16x8*)(lds + PG8_SA(b, h) + aoff + m * 2048 + k * 1024); } while (0)
; #define PG8_LDB(dst, b, h) do { _Pragma("unroll") for (int n = 0; n < 2; ++n) _Pragma("unroll") for (int k = 0; k < 2; ++k) dst[n][k] = *(const PG8_LAS bf16x8*)(lds + PG8_SB(b, h) + boff + n * 2048 + k * 1024); } while (0)
; #define PG8_MMA(ai, bj, At, Bt) do { __builtin_amdgcn_s_setprio(1); _Pragma("unroll") for (int m = 0; m < 4; ++m) _Pragma("unroll") for (int n = 0; n < 2; ++n) _Pragma("unroll") for (int k = 0; k < 2; ++k) \
;         acc[ai][bj][m][n] = __builtin_amdgcn_mfma_f32_16x16x32_bf16(Bt[n][k], At[m][k], acc[ai][bj][m][n], 0, 0, 0); __builtin_amdgcn_s_setprio(0); } while (0)
; #define PG8_WAIT_V(n) asm volatile("s_waitcnt vmcnt(" #n ")" ::: "memory")
; #define PG8_WAIT_L(n) asm volatile("s_waitcnt lgkmcnt(" #n ")" ::: "memory")
; #define PG8_BAR __builtin_amdgcn_s_barrier()
; template <class Epi, class Sched, bool ALIGN_EPI = false, bool SP2 = false>
; __device__ __forceinline__ void gemm_phase(PG8_LAS unsigned char* lds, const Gemm g, const Sched& S, const Epi& E) {
;     ...
;         const bool has_next = S.next(ui + 1, nxt);
;         const char* nA = has_next ? (const char*)g.A + (size_t)nxt.pm * tstep : cA; const char* nB = has_next ? (const char*)g.Bt + (size_t)nxt.pn * tstep : cB;
;         for (int t = 0; t < nt; t += 2) {
;             const bool last = (t == nt - 2);
;             const char* a1 = cA + (size_t)(t + 1) * kstep;
;             const char* a2 = last ? nA : cA + (size_t)(t + 2) * kstep; const char* b2 = last ? nB : cB + (size_t)(t + 2) * kstep;
;             const char* a3 = a2 + kstep; const char* b3 = b2 + kstep;
;             if (last && has_next) S.a_ready(nxt);
;             if constexpr (SP2) {
;             PG8_LDB(B0, 0, 0); PG8_LDB(B1, 0, 1); PG8_SCHED; PG8_LDA(At, 0, 0); PG8_STAGE(PG8_SA(1, 1), a1 + hstep, voffA);
;             PG8_WAIT_V(8); PG8_WAIT_L(0); PG8_BAR; PG8_MMA(0, 0, At, B0); PG8_MMA(0, 1, At, B1); PG8_BAR; PG8_SCHED;
.LBB0_1534:
	s_ashr_i32 s23, s22, 31
	s_lshl_b64 s[36:37], s[22:23], 19
	s_add_u32 s36, s3, s36
	s_addc_u32 s37, s33, s37
	s_and_b64 s[38:39], s[4:5], exec
	s_cselect_b32 s23, s37, s43
	s_cselect_b32 s66, s36, s42
	s_ashr_i32 s19, s18, 31
	s_lshl_b64 s[38:39], s[18:19], 19
	s_add_u32 s38, s48, s38
	s_addc_u32 s39, s49, s39
	s_and_b64 s[46:47], s[4:5], exec
	s_cselect_b32 s19, s39, s45
	s_cselect_b32 s67, s38, s44
	s_add_u32 s42, s42, 0x40080
	s_addc_u32 s43, s43, 0
	s_add_u32 s68, s44, 0x100
	s_addc_u32 s69, s45, 0
	s_mov_b32 s70, -2
	s_nop 0
	ds_read_b128 v[146:149], v153
	ds_read_b128 v[156:159], v153 offset:1024
	ds_read_b128 v[160:163], v153 offset:2048
	ds_read_b128 v[164:167], v153 offset:3072
	ds_read_b128 v[168:171], v154
	ds_read_b128 v[172:175], v154 offset:1024
	ds_read_b128 v[176:179], v154 offset:2048
	ds_read_b128 v[180:183], v154 offset:3072
	s_add_u32 s44, s42, 0xfffc0080
	s_addc_u32 s45, s43, -1
	s_cmp_eq_u32 s70, 12
	s_cselect_b32 s47, s23, s45
	s_cselect_b32 s46, s66, s44
	s_cselect_b32 s45, s19, s69
	s_cselect_b32 s44, s67, s68
	v_lshl_add_u64 v[216:217], s[42:43], 0, v[136:137]
	s_add_i32 m0, s41, 0xc000
	ds_read_b128 v[184:187], v155
	ds_read_b128 v[188:191], v155 offset:1024
	ds_read_b128 v[192:195], v155 offset:2048
	ds_read_b128 v[196:199], v155 offset:3072
	ds_read_b128 v[200:203], v155 offset:4096
	ds_read_b128 v[204:207], v155 offset:5120
	ds_read_b128 v[208:211], v155 offset:6144
	ds_read_b128 v[212:215], v155 offset:7168
	global_load_lds_dwordx4 v[216:217], off
	v_lshl_add_u64 v[216:217], s[42:43], 0, v[138:139]
	s_add_i32 m0, s41, 0xe000
	s_nop 0
	global_load_lds_dwordx4 v[216:217], off
	s_waitcnt vmcnt(8)
	s_waitcnt lgkmcnt(0)
	s_barrier
	s_setprio 1
	v_mfma_f32_16x16x32_bf16 v[124:127], v[146:149], v[184:187], 0
	v_mfma_f32_16x16x32_bf16 v[120:123], v[160:163], v[184:187], 0
	v_mfma_f32_16x16x32_bf16 v[108:111], v[146:149], v[192:195], 0
	v_mfma_f32_16x16x32_bf16 v[104:107], v[160:163], v[192:195], 0
	v_mfma_f32_16x16x32_bf16 v[92:95], v[146:149], v[200:203], 0
	v_mfma_f32_16x16x32_bf16 v[88:91], v[160:163], v[200:203], 0
	v_mfma_f32_16x16x32_bf16 v[76:79], v[146:149], v[208:211], 0
	v_mfma_f32_16x16x32_bf16 v[72:75], v[160:163], v[208:211], 0
	v_mfma_f32_16x16x32_bf16 v[124:127], v[156:159], v[188:191], v[124:127]
	v_mfma_f32_16x16x32_bf16 v[120:123], v[164:167], v[188:191], v[120:123]
	v_mfma_f32_16x16x32_bf16 v[108:111], v[156:159], v[196:199], v[108:111]
	v_mfma_f32_16x16x32_bf16 v[104:107], v[164:167], v[196:199], v[104:107]
	v_mfma_f32_16x16x32_bf16 v[92:95], v[156:159], v[204:207], v[92:95]
	v_mfma_f32_16x16x32_bf16 v[88:91], v[164:167], v[204:207], v[88:91]
	v_mfma_f32_16x16x32_bf16 v[76:79], v[156:159], v[212:215], v[76:79]
	v_mfma_f32_16x16x32_bf16 v[72:75], v[164:167], v[212:215], v[72:75]
	s_setprio 0
	s_setprio 1
	v_mfma_f32_16x16x32_bf16 v[116:119], v[168:171], v[184:187], 0
	v_mfma_f32_16x16x32_bf16 v[112:115], v[176:179], v[184:187], 0
	v_mfma_f32_16x16x32_bf16 v[100:103], v[168:171], v[192:195], 0
	v_mfma_f32_16x16x32_bf16 v[96:99], v[176:179], v[192:195], 0
	v_mfma_f32_16x16x32_bf16 v[84:87], v[168:171], v[200:203], 0
	v_mfma_f32_16x16x32_bf16 v[80:83], v[176:179], v[200:203], 0
	v_mfma_f32_16x16x32_bf16 v[68:71], v[168:171], v[208:211], 0
	v_mfma_f32_16x16x32_bf16 v[64:67], v[176:179], v[208:211], 0
	v_mfma_f32_16x16x32_bf16 v[116:119], v[172:175], v[188:191], v[116:119]
	v_mfma_f32_16x16x32_bf16 v[112:115], v[180:183], v[188:191], v[112:115]
	v_mfma_f32_16x16x32_bf16 v[100:103], v[172:175], v[196:199], v[100:103]
	v_mfma_f32_16x16x32_bf16 v[96:99], v[180:183], v[196:199], v[96:99]
	v_mfma_f32_16x16x32_bf16 v[84:87], v[172:175], v[204:207], v[84:87]
	v_mfma_f32_16x16x32_bf16 v[80:83], v[180:183], v[204:207], v[80:83]
	v_mfma_f32_16x16x32_bf16 v[68:71], v[172:175], v[212:215], v[68:71]
	v_mfma_f32_16x16x32_bf16 v[64:67], v[180:183], v[212:215], v[64:67]
	s_setprio 0
	s_barrier
	s_add_i32 s71, s62, s50
	v_lshl_add_u64 v[216:217], s[44:45], 0, v[130:131]
	s_mov_b32 m0, s71
	ds_read_b128 v[184:187], v155 offset:16384
	ds_read_b128 v[188:191], v155 offset:17408
	ds_read_b128 v[192:195], v155 offset:18432
	ds_read_b128 v[196:199], v155 offset:19456
	ds_read_b128 v[200:203], v155 offset:20480
	ds_read_b128 v[204:207], v155 offset:21504
	ds_read_b128 v[208:211], v155 offset:22528
	ds_read_b128 v[212:215], v155 offset:23552
	global_load_lds_dwordx4 v[216:217], off
	s_add_i32 m0, s71, 0x2000
	s_add_u32 s72, s44, 0x40000
	v_lshl_add_u64 v[218:219], s[44:45], 0, v[134:135]
	s_addc_u32 s73, s45, 0
	s_add_i32 s71, s63, s50
	global_load_lds_dwordx4 v[218:219], off
	v_lshl_add_u64 v[220:221], s[72:73], 0, v[130:131]
	s_mov_b32 m0, s71
	v_lshl_add_u64 v[222:223], s[46:47], 0, v[132:133]
	global_load_lds_dwordx4 v[220:221], off
	v_lshl_add_u64 v[220:221], s[72:73], 0, v[134:135]
	s_add_i32 m0, s71, 0x2000
	s_nop 0
	global_load_lds_dwordx4 v[220:221], off
	v_lshl_add_u64 v[220:221], s[46:47], 0, v[128:129]
	s_mov_b32 m0, s41
	s_nop 0
	global_load_lds_dwordx4 v[220:221], off
	s_mov_b32 m0, s52
	s_nop 0
	global_load_lds_dwordx4 v[222:223], off
	s_waitcnt vmcnt(8)
	s_waitcnt lgkmcnt(0)
	s_barrier
; #define PG8_STAGE(bufoff, gbase, voff) do { _Pragma("unroll") for (int _i = 0; _i < 2; ++_i) \
;         __builtin_amdgcn_global_load_lds((const unsigned*)((const char*)(gbase) + (voff)[_i]), (PG8_LAS unsigned*)(lds + (bufoff) + ldsw + _i * 8192), 16, 0, 0); } while (0)
; #define PG8_LDA(dst, b, h) do { _Pragma("unroll") for (int m = 0; m < 4; ++m) _Pragma("unroll") for (int k = 0; k < 2; ++k) dst[m][k] = *(const PG8_LAS bf16x8*)(lds + PG8_SA(b, h) + aoff + m * 2048 + k * 1024); } while (0)
; #define PG8_LDB(dst, b, h) do { _Pragma("unroll") for (int n = 0; n < 2; ++n) _Pragma("unroll") for (int k = 0; k < 2; ++k) dst[n][k] = *(const PG8_LAS bf16x8*)(lds + PG8_SB(b, h) + boff + n * 2048 + k * 1024); } while (0)
; #define PG8_MMA(ai, bj, At, Bt) do { __builtin_amdgcn_s_setprio(1); _Pragma("unroll") for (int m = 0; m < 4; ++m) _Pragma("unroll") for (int n = 0; n < 2; ++n) _Pragma("unroll") for (int k = 0; k < 2; ++k) \
;         acc[ai][bj][m][n] = __builtin_amdgcn_mfma_f32_16x16x32_bf16(Bt[n][k], At[m][k], acc[ai][bj][m][n], 0, 0, 0); __builtin_amdgcn_s_setprio(0); } while (0)
; #define PG8_WAIT_V(n) asm volatile("s_waitcnt vmcnt(" #n ")" ::: "memory")
; #define PG8_WAIT_L(n) asm volatile("s_waitcnt lgkmcnt(" #n ")" ::: "memory")
; #define PG8_BAR __builtin_amdgcn_s_barrier()
; #define PG8_SCHED __builtin_amdgcn_sched_barrier(0)
; template <class Epi, class Sched, bool ALIGN_EPI = false, bool SP2 = false>
; __device__ __forceinline__ void gemm_phase(PG8_LAS unsigned char* lds, const Gemm g, const Sched& S, const Epi& E) {
;     ...
;             PG8_WAIT_V(8); PG8_WAIT_L(0); PG8_BAR; PG8_MMA(1, 0, At, B0); PG8_MMA(1, 1, At, B1); PG8_BAR; PG8_SCHED;
;             PG8_LDB(B0, 1, 0); PG8_LDB(B1, 1, 1); PG8_SCHED; PG8_LDA(At, 1, 0); PG8_STAGE(PG8_SA(0, 1), a2 + hstep, voffA);
;             PG8_WAIT_V(8); PG8_WAIT_L(0); PG8_BAR; PG8_MMA(0, 0, At, B0); PG8_MMA(0, 1, At, B1); PG8_BAR; PG8_SCHED;
	s_setprio 1
	v_mfma_f32_16x16x32_bf16 v[60:63], v[146:149], v[184:187], 0
	v_mfma_f32_16x16x32_bf16 v[56:59], v[160:163], v[184:187], 0
	v_mfma_f32_16x16x32_bf16 v[44:47], v[146:149], v[192:195], 0
	v_mfma_f32_16x16x32_bf16 v[40:43], v[160:163], v[192:195], 0
	v_mfma_f32_16x16x32_bf16 v[28:31], v[146:149], v[200:203], 0
	v_mfma_f32_16x16x32_bf16 v[24:27], v[160:163], v[200:203], 0
	v_mfma_f32_16x16x32_bf16 v[12:15], v[146:149], v[208:211], 0
	v_mfma_f32_16x16x32_bf16 v[8:11], v[160:163], v[208:211], 0
	v_mfma_f32_16x16x32_bf16 v[60:63], v[156:159], v[188:191], v[60:63]
	v_mfma_f32_16x16x32_bf16 v[56:59], v[164:167], v[188:191], v[56:59]
	v_mfma_f32_16x16x32_bf16 v[44:47], v[156:159], v[196:199], v[44:47]
	v_mfma_f32_16x16x32_bf16 v[40:43], v[164:167], v[196:199], v[40:43]
	v_mfma_f32_16x16x32_bf16 v[28:31], v[156:159], v[204:207], v[28:31]
	v_mfma_f32_16x16x32_bf16 v[24:27], v[164:167], v[204:207], v[24:27]
	v_mfma_f32_16x16x32_bf16 v[12:15], v[156:159], v[212:215], v[12:15]
	v_mfma_f32_16x16x32_bf16 v[8:11], v[164:167], v[212:215], v[8:11]
	s_setprio 0
	s_setprio 1
	v_mfma_f32_16x16x32_bf16 v[52:55], v[168:171], v[184:187], 0
	v_mfma_f32_16x16x32_bf16 v[48:51], v[176:179], v[184:187], 0
	v_mfma_f32_16x16x32_bf16 v[36:39], v[168:171], v[192:195], 0
	v_mfma_f32_16x16x32_bf16 v[32:35], v[176:179], v[192:195], 0
	v_mfma_f32_16x16x32_bf16 v[20:23], v[168:171], v[200:203], 0
	v_mfma_f32_16x16x32_bf16 v[16:19], v[176:179], v[200:203], 0
	v_mfma_f32_16x16x32_bf16 v[4:7], v[168:171], v[208:211], 0
	v_mfma_f32_16x16x32_bf16 v[0:3], v[176:179], v[208:211], 0
	v_mfma_f32_16x16x32_bf16 v[52:55], v[172:175], v[188:191], v[52:55]
	v_mfma_f32_16x16x32_bf16 v[48:51], v[180:183], v[188:191], v[48:51]
	v_mfma_f32_16x16x32_bf16 v[36:39], v[172:175], v[196:199], v[36:39]
	v_mfma_f32_16x16x32_bf16 v[32:35], v[180:183], v[196:199], v[32:35]
	v_mfma_f32_16x16x32_bf16 v[20:23], v[172:175], v[204:207], v[20:23]
	v_mfma_f32_16x16x32_bf16 v[16:19], v[180:183], v[204:207], v[16:19]
	v_mfma_f32_16x16x32_bf16 v[4:7], v[172:175], v[212:215], v[4:7]
	v_mfma_f32_16x16x32_bf16 v[0:3], v[180:183], v[212:215], v[0:3]
	s_setprio 0
	s_barrier
	s_add_i32 s71, 0, 0x18000
	s_add_i32 s72, 0, 0x1c000
	v_add_u32_e32 v164, s71, v152
	v_add_u32_e32 v180, s72, v152
	ds_read_b128 v[146:149], v164
	ds_read_b128 v[156:159], v164 offset:1024
	ds_read_b128 v[160:163], v164 offset:2048
	ds_read_b128 v[164:167], v164 offset:3072
	ds_read_b128 v[168:171], v180
	ds_read_b128 v[172:175], v180 offset:1024
	ds_read_b128 v[176:179], v180 offset:2048
	ds_read_b128 v[180:183], v180 offset:3072
	s_add_u32 s46, s46, 0x40000
	s_addc_u32 s47, s47, 0
	s_mov_b32 m0, s53
	v_lshl_add_u64 v[224:225], s[46:47], 0, v[128:129]
	ds_read_b128 v[184:187], v155 offset:32768
	ds_read_b128 v[188:191], v155 offset:33792
	ds_read_b128 v[192:195], v155 offset:34816
	ds_read_b128 v[196:199], v155 offset:35840
	ds_read_b128 v[200:203], v155 offset:36864
	ds_read_b128 v[204:207], v155 offset:37888
	ds_read_b128 v[208:211], v155 offset:38912
	ds_read_b128 v[212:215], v155 offset:39936
	global_load_lds_dwordx4 v[224:225], off
	v_lshl_add_u64 v[224:225], s[46:47], 0, v[132:133]
	s_mov_b32 m0, s54
	s_nop 0
	global_load_lds_dwordx4 v[224:225], off
	s_waitcnt vmcnt(8)
	s_waitcnt lgkmcnt(0)
	s_barrier
	s_setprio 1
	v_mfma_f32_16x16x32_bf16 v[124:127], v[146:149], v[184:187], v[124:127]
	v_mfma_f32_16x16x32_bf16 v[120:123], v[160:163], v[184:187], v[120:123]
	v_mfma_f32_16x16x32_bf16 v[108:111], v[146:149], v[192:195], v[108:111]
	v_mfma_f32_16x16x32_bf16 v[104:107], v[160:163], v[192:195], v[104:107]
	v_mfma_f32_16x16x32_bf16 v[92:95], v[146:149], v[200:203], v[92:95]
	v_mfma_f32_16x16x32_bf16 v[88:91], v[160:163], v[200:203], v[88:91]
	v_mfma_f32_16x16x32_bf16 v[76:79], v[146:149], v[208:211], v[76:79]
	v_mfma_f32_16x16x32_bf16 v[72:75], v[160:163], v[208:211], v[72:75]
	v_mfma_f32_16x16x32_bf16 v[124:127], v[156:159], v[188:191], v[124:127]
	v_mfma_f32_16x16x32_bf16 v[120:123], v[164:167], v[188:191], v[120:123]
	v_mfma_f32_16x16x32_bf16 v[108:111], v[156:159], v[196:199], v[108:111]
	v_mfma_f32_16x16x32_bf16 v[104:107], v[164:167], v[196:199], v[104:107]
	v_mfma_f32_16x16x32_bf16 v[92:95], v[156:159], v[204:207], v[92:95]
	v_mfma_f32_16x16x32_bf16 v[88:91], v[164:167], v[204:207], v[88:91]
	v_mfma_f32_16x16x32_bf16 v[76:79], v[156:159], v[212:215], v[76:79]
	v_mfma_f32_16x16x32_bf16 v[72:75], v[164:167], v[212:215], v[72:75]
	s_setprio 0
	s_setprio 1
	v_mfma_f32_16x16x32_bf16 v[116:119], v[168:171], v[184:187], v[116:119]
	v_mfma_f32_16x16x32_bf16 v[112:115], v[176:179], v[184:187], v[112:115]
	v_mfma_f32_16x16x32_bf16 v[100:103], v[168:171], v[192:195], v[100:103]
	v_mfma_f32_16x16x32_bf16 v[96:99], v[176:179], v[192:195], v[96:99]
	v_mfma_f32_16x16x32_bf16 v[84:87], v[168:171], v[200:203], v[84:87]
	v_mfma_f32_16x16x32_bf16 v[80:83], v[176:179], v[200:203], v[80:83]
	v_mfma_f32_16x16x32_bf16 v[68:71], v[168:171], v[208:211], v[68:71]
	v_mfma_f32_16x16x32_bf16 v[64:67], v[176:179], v[208:211], v[64:67]
	v_mfma_f32_16x16x32_bf16 v[116:119], v[172:175], v[188:191], v[116:119]
	v_mfma_f32_16x16x32_bf16 v[112:115], v[180:183], v[188:191], v[112:115]
	v_mfma_f32_16x16x32_bf16 v[100:103], v[172:175], v[196:199], v[100:103]
	v_mfma_f32_16x16x32_bf16 v[96:99], v[180:183], v[196:199], v[96:99]
	v_mfma_f32_16x16x32_bf16 v[84:87], v[172:175], v[204:207], v[84:87]
	v_mfma_f32_16x16x32_bf16 v[80:83], v[180:183], v[204:207], v[80:83]
	v_mfma_f32_16x16x32_bf16 v[68:71], v[172:175], v[212:215], v[68:71]
	v_mfma_f32_16x16x32_bf16 v[64:67], v[180:183], v[212:215], v[64:67]
	s_setprio 0
	s_barrier
; #define PG8_STAGE(bufoff, gbase, voff) do { _Pragma("unroll") for (int _i = 0; _i < 2; ++_i) \
;         __builtin_amdgcn_global_load_lds((const unsigned*)((const char*)(gbase) + (voff)[_i]), (PG8_LAS unsigned*)(lds + (bufoff) + ldsw + _i * 8192), 16, 0, 0); } while (0)
; #define PG8_LDA(dst, b, h) do { _Pragma("unroll") for (int m = 0; m < 4; ++m) _Pragma("unroll") for (int k = 0; k < 2; ++k) dst[m][k] = *(const PG8_LAS bf16x8*)(lds + PG8_SA(b, h) + aoff + m * 2048 + k * 1024); } while (0)
; #define PG8_LDB(dst, b, h) do { _Pragma("unroll") for (int n = 0; n < 2; ++n) _Pragma("unroll") for (int k = 0; k < 2; ++k) dst[n][k] = *(const PG8_LAS bf16x8*)(lds + PG8_SB(b, h) + boff + n * 2048 + k * 1024); } while (0)
; #define PG8_MMA(ai, bj, At, Bt) do { __builtin_amdgcn_s_setprio(1); _Pragma("unroll") for (int m = 0; m < 4; ++m) _Pragma("unroll") for (int n = 0; n < 2; ++n) _Pragma("unroll") for (int k = 0; k < 2; ++k) \
;         acc[ai][bj][m][n] = __builtin_amdgcn_mfma_f32_16x16x32_bf16(Bt[n][k], At[m][k], acc[ai][bj][m][n], 0, 0, 0); __builtin_amdgcn_s_setprio(0); } while (0)
; #define PG8_WAIT_V(n) asm volatile("s_waitcnt vmcnt(" #n ")" ::: "memory")
; #define PG8_WAIT_L(n) asm volatile("s_waitcnt lgkmcnt(" #n ")" ::: "memory")
; #define PG8_BAR __builtin_amdgcn_s_barrier()
; #define PG8_SCHED __builtin_amdgcn_sched_barrier(0)
; template <class Epi, class Sched, bool ALIGN_EPI = false, bool SP2 = false>
; __device__ __forceinline__ void gemm_phase(PG8_LAS unsigned char* lds, const Gemm g, const Sched& S, const Epi& E) {
;     ...
;             PG8_LDB(B0, 0, 0); PG8_LDB(B1, 0, 1); PG8_SCHED; PG8_LDA(At, 0, 0); PG8_STAGE(PG8_SA(1, 1), a1 + hstep, voffA);
;             PG8_WAIT_V(8); PG8_WAIT_L(0); PG8_BAR; PG8_MMA(0, 0, At, B0); PG8_MMA(0, 1, At, B1); PG8_BAR; PG8_SCHED;
;     ...
;             PG8_LDA(At, 1, 1); PG8_STAGE(PG8_SB(1, 0), b3, voffB); PG8_STAGE(PG8_SB(1, 1), b3 + hstep, voffB); PG8_STAGE(PG8_SA(1, 0), a3, voffA);
;             PG8_WAIT_V(8); PG8_WAIT_L(0); PG8_BAR; PG8_MMA(1, 0, At, B0); PG8_MMA(1, 1, At, B1); PG8_BAR; PG8_SCHED;
	s_add_i32 s46, s71, s50
	v_lshl_add_u64 v[216:217], v[216:217], 0, s[12:13]
	s_mov_b32 m0, s46
	ds_read_b128 v[184:187], v155 offset:49152
	ds_read_b128 v[188:191], v155 offset:50176
	ds_read_b128 v[192:195], v155 offset:51200
	ds_read_b128 v[196:199], v155 offset:52224
	ds_read_b128 v[200:203], v155 offset:53248
	ds_read_b128 v[204:207], v155 offset:54272
	ds_read_b128 v[208:211], v155 offset:55296
	ds_read_b128 v[212:215], v155 offset:56320
	global_load_lds_dwordx4 v[216:217], off
	s_add_i32 m0, s46, 0x2000
	s_add_u32 s44, s44, 0x40080
	v_lshl_add_u64 v[216:217], v[218:219], 0, s[12:13]
	s_addc_u32 s45, s45, 0
	s_add_i32 s46, s72, s50
	global_load_lds_dwordx4 v[216:217], off
	v_lshl_add_u64 v[216:217], s[44:45], 0, v[130:131]
	s_mov_b32 m0, s46
	s_nop 0
	global_load_lds_dwordx4 v[216:217], off
	v_lshl_add_u64 v[216:217], s[44:45], 0, v[134:135]
	s_add_i32 m0, s46, 0x2000
	s_nop 0
	global_load_lds_dwordx4 v[216:217], off
	v_lshl_add_u64 v[216:217], v[220:221], 0, s[12:13]
	s_mov_b32 m0, s59
	s_nop 0
	global_load_lds_dwordx4 v[216:217], off
	v_lshl_add_u64 v[216:217], v[222:223], 0, s[12:13]
	s_mov_b32 m0, s60
	s_nop 0
	global_load_lds_dwordx4 v[216:217], off
	s_waitcnt vmcnt(8)
	s_waitcnt lgkmcnt(0)
	s_barrier
	s_setprio 1
	v_mfma_f32_16x16x32_bf16 v[60:63], v[146:149], v[184:187], v[60:63]
	v_mfma_f32_16x16x32_bf16 v[56:59], v[160:163], v[184:187], v[56:59]
	v_mfma_f32_16x16x32_bf16 v[44:47], v[146:149], v[192:195], v[44:47]
	v_mfma_f32_16x16x32_bf16 v[40:43], v[160:163], v[192:195], v[40:43]
	v_mfma_f32_16x16x32_bf16 v[28:31], v[146:149], v[200:203], v[28:31]
	v_mfma_f32_16x16x32_bf16 v[24:27], v[160:163], v[200:203], v[24:27]
	v_mfma_f32_16x16x32_bf16 v[12:15], v[146:149], v[208:211], v[12:15]
	v_mfma_f32_16x16x32_bf16 v[8:11], v[160:163], v[208:211], v[8:11]
	v_mfma_f32_16x16x32_bf16 v[60:63], v[156:159], v[188:191], v[60:63]
	v_mfma_f32_16x16x32_bf16 v[56:59], v[164:167], v[188:191], v[56:59]
	v_mfma_f32_16x16x32_bf16 v[44:47], v[156:159], v[196:199], v[44:47]
	v_mfma_f32_16x16x32_bf16 v[40:43], v[164:167], v[196:199], v[40:43]
	v_mfma_f32_16x16x32_bf16 v[28:31], v[156:159], v[204:207], v[28:31]
	v_mfma_f32_16x16x32_bf16 v[24:27], v[164:167], v[204:207], v[24:27]
	v_mfma_f32_16x16x32_bf16 v[12:15], v[156:159], v[212:215], v[12:15]
	v_mfma_f32_16x16x32_bf16 v[8:11], v[164:167], v[212:215], v[8:11]
	s_setprio 0
	s_setprio 1
	v_mfma_f32_16x16x32_bf16 v[52:55], v[168:171], v[184:187], v[52:55]
	v_mfma_f32_16x16x32_bf16 v[48:51], v[176:179], v[184:187], v[48:51]
	v_mfma_f32_16x16x32_bf16 v[36:39], v[168:171], v[192:195], v[36:39]
	v_mfma_f32_16x16x32_bf16 v[32:35], v[176:179], v[192:195], v[32:35]
	v_mfma_f32_16x16x32_bf16 v[20:23], v[168:171], v[200:203], v[20:23]
	v_mfma_f32_16x16x32_bf16 v[16:19], v[176:179], v[200:203], v[16:19]
	v_mfma_f32_16x16x32_bf16 v[4:7], v[168:171], v[208:211], v[4:7]
	v_mfma_f32_16x16x32_bf16 v[0:3], v[176:179], v[208:211], v[0:3]
	v_mfma_f32_16x16x32_bf16 v[52:55], v[172:175], v[188:191], v[52:55]
	v_mfma_f32_16x16x32_bf16 v[48:51], v[180:183], v[188:191], v[48:51]
	v_mfma_f32_16x16x32_bf16 v[36:39], v[172:175], v[196:199], v[36:39]
	v_mfma_f32_16x16x32_bf16 v[32:35], v[180:183], v[196:199], v[32:35]
	v_mfma_f32_16x16x32_bf16 v[20:23], v[172:175], v[204:207], v[20:23]
	v_mfma_f32_16x16x32_bf16 v[16:19], v[180:183], v[204:207], v[16:19]
	v_mfma_f32_16x16x32_bf16 v[4:7], v[172:175], v[212:215], v[4:7]
	v_mfma_f32_16x16x32_bf16 v[0:3], v[180:183], v[212:215], v[0:3]
	s_setprio 0
	s_barrier
	s_add_i32 s70, s70, 2
	s_add_u32 s42, s42, 0x100
	s_addc_u32 s43, s43, 0
	s_add_u32 s68, s68, 0x100
	s_addc_u32 s69, s69, 0
	s_cmp_gt_u32 s70, 13
.LBB0_1535:
	ds_read_b128 v[146:149], v153
	ds_read_b128 v[156:159], v153 offset:1024
	ds_read_b128 v[160:163], v153 offset:2048
	ds_read_b128 v[164:167], v153 offset:3072
	ds_read_b128 v[168:171], v154
	ds_read_b128 v[172:175], v154 offset:1024
	ds_read_b128 v[176:179], v154 offset:2048
	ds_read_b128 v[180:183], v154 offset:3072
	s_add_u32 s44, s42, 0xfffc0080
	s_addc_u32 s45, s43, -1
	s_cmp_eq_u32 s70, 12
	s_cselect_b32 s47, s23, s45
	s_cselect_b32 s46, s66, s44
	s_cselect_b32 s45, s19, s69
	s_cselect_b32 s44, s67, s68
	v_lshl_add_u64 v[216:217], s[42:43], 0, v[136:137]
	s_add_i32 m0, s41, 0xc000
	ds_read_b128 v[184:187], v155
	ds_read_b128 v[188:191], v155 offset:1024
	ds_read_b128 v[192:195], v155 offset:2048
	ds_read_b128 v[196:199], v155 offset:3072
	ds_read_b128 v[200:203], v155 offset:4096
	ds_read_b128 v[204:207], v155 offset:5120
	ds_read_b128 v[208:211], v155 offset:6144
	ds_read_b128 v[212:215], v155 offset:7168
	global_load_lds_dwordx4 v[216:217], off
	v_lshl_add_u64 v[216:217], s[42:43], 0, v[138:139]
	s_add_i32 m0, s41, 0xe000
	s_nop 0
	global_load_lds_dwordx4 v[216:217], off
	s_waitcnt vmcnt(8)
	s_waitcnt lgkmcnt(0)
	s_barrier
; #define PG8_STAGE(bufoff, gbase, voff) do { _Pragma("unroll") for (int _i = 0; _i < 2; ++_i) \
;         __builtin_amdgcn_global_load_lds((const unsigned*)((const char*)(gbase) + (voff)[_i]), (PG8_LAS unsigned*)(lds + (bufoff) + ldsw + _i * 8192), 16, 0, 0); } while (0)
; #define PG8_LDA(dst, b, h) do { _Pragma("unroll") for (int m = 0; m < 4; ++m) _Pragma("unroll") for (int k = 0; k < 2; ++k) dst[m][k] = *(const PG8_LAS bf16x8*)(lds + PG8_SA(b, h) + aoff + m * 2048 + k * 1024); } while (0)
; #define PG8_LDB(dst, b, h) do { _Pragma("unroll") for (int n = 0; n < 2; ++n) _Pragma("unroll") for (int k = 0; k < 2; ++k) dst[n][k] = *(const PG8_LAS bf16x8*)(lds + PG8_SB(b, h) + boff + n * 2048 + k * 1024); } while (0)
; #define PG8_MMA(ai, bj, At, Bt) do { __builtin_amdgcn_s_setprio(1); _Pragma("unroll") for (int m = 0; m < 4; ++m) _Pragma("unroll") for (int n = 0; n < 2; ++n) _Pragma("unroll") for (int k = 0; k < 2; ++k) \
;         acc[ai][bj][m][n] = __builtin_amdgcn_mfma_f32_16x16x32_bf16(Bt[n][k], At[m][k], acc[ai][bj][m][n], 0, 0, 0); __builtin_amdgcn_s_setprio(0); } while (0)
; #define PG8_WAIT_V(n) asm volatile("s_waitcnt vmcnt(" #n ")" ::: "memory")
; #define PG8_WAIT_L(n) asm volatile("s_waitcnt lgkmcnt(" #n ")" ::: "memory")
; #define PG8_BAR __builtin_amdgcn_s_barrier()
; #define PG8_SCHED __builtin_amdgcn_sched_barrier(0)
; template <class Epi, class Sched, bool ALIGN_EPI = false, bool SP2 = false>
; __device__ __forceinline__ void gemm_phase(PG8_LAS unsigned char* lds, const Gemm g, const Sched& S, const Epi& E) {
;     ...
;             PG8_LDB(B0, 0, 0); PG8_LDB(B1, 0, 1); PG8_SCHED; PG8_LDA(At, 0, 0); PG8_STAGE(PG8_SA(1, 1), a1 + hstep, voffA);
;             PG8_WAIT_V(8); PG8_WAIT_L(0); PG8_BAR; PG8_MMA(0, 0, At, B0); PG8_MMA(0, 1, At, B1); PG8_BAR; PG8_SCHED;
;             PG8_LDA(At, 0, 1); PG8_STAGE(PG8_SB(0, 0), b2, voffB); PG8_STAGE(PG8_SB(0, 1), b2 + hstep, voffB); PG8_STAGE(PG8_SA(0, 0), a2, voffA);
;             PG8_WAIT_V(8); PG8_WAIT_L(0); PG8_BAR; PG8_MMA(1, 0, At, B0); PG8_MMA(1, 1, At, B1); PG8_BAR; PG8_SCHED;
	s_setprio 1
	v_mfma_f32_16x16x32_bf16 v[124:127], v[146:149], v[184:187], v[124:127]
	v_mfma_f32_16x16x32_bf16 v[120:123], v[160:163], v[184:187], v[120:123]
	v_mfma_f32_16x16x32_bf16 v[108:111], v[146:149], v[192:195], v[108:111]
	v_mfma_f32_16x16x32_bf16 v[104:107], v[160:163], v[192:195], v[104:107]
	v_mfma_f32_16x16x32_bf16 v[92:95], v[146:149], v[200:203], v[92:95]
	v_mfma_f32_16x16x32_bf16 v[88:91], v[160:163], v[200:203], v[88:91]
	v_mfma_f32_16x16x32_bf16 v[76:79], v[146:149], v[208:211], v[76:79]
	v_mfma_f32_16x16x32_bf16 v[72:75], v[160:163], v[208:211], v[72:75]
	v_mfma_f32_16x16x32_bf16 v[124:127], v[156:159], v[188:191], v[124:127]
	v_mfma_f32_16x16x32_bf16 v[120:123], v[164:167], v[188:191], v[120:123]
	v_mfma_f32_16x16x32_bf16 v[108:111], v[156:159], v[196:199], v[108:111]
	v_mfma_f32_16x16x32_bf16 v[104:107], v[164:167], v[196:199], v[104:107]
	v_mfma_f32_16x16x32_bf16 v[92:95], v[156:159], v[204:207], v[92:95]
	v_mfma_f32_16x16x32_bf16 v[88:91], v[164:167], v[204:207], v[88:91]
	v_mfma_f32_16x16x32_bf16 v[76:79], v[156:159], v[212:215], v[76:79]
	v_mfma_f32_16x16x32_bf16 v[72:75], v[164:167], v[212:215], v[72:75]
	s_setprio 0
	s_setprio 1
	v_mfma_f32_16x16x32_bf16 v[116:119], v[168:171], v[184:187], v[116:119]
	v_mfma_f32_16x16x32_bf16 v[112:115], v[176:179], v[184:187], v[112:115]
	v_mfma_f32_16x16x32_bf16 v[100:103], v[168:171], v[192:195], v[100:103]
	v_mfma_f32_16x16x32_bf16 v[96:99], v[176:179], v[192:195], v[96:99]
	v_mfma_f32_16x16x32_bf16 v[84:87], v[168:171], v[200:203], v[84:87]
	v_mfma_f32_16x16x32_bf16 v[80:83], v[176:179], v[200:203], v[80:83]
	v_mfma_f32_16x16x32_bf16 v[68:71], v[168:171], v[208:211], v[68:71]
	v_mfma_f32_16x16x32_bf16 v[64:67], v[176:179], v[208:211], v[64:67]
	v_mfma_f32_16x16x32_bf16 v[116:119], v[172:175], v[188:191], v[116:119]
	v_mfma_f32_16x16x32_bf16 v[112:115], v[180:183], v[188:191], v[112:115]
	v_mfma_f32_16x16x32_bf16 v[100:103], v[172:175], v[196:199], v[100:103]
	v_mfma_f32_16x16x32_bf16 v[96:99], v[180:183], v[196:199], v[96:99]
	v_mfma_f32_16x16x32_bf16 v[84:87], v[172:175], v[204:207], v[84:87]
	v_mfma_f32_16x16x32_bf16 v[80:83], v[180:183], v[204:207], v[80:83]
	v_mfma_f32_16x16x32_bf16 v[68:71], v[172:175], v[212:215], v[68:71]
	v_mfma_f32_16x16x32_bf16 v[64:67], v[180:183], v[212:215], v[64:67]
	s_setprio 0
	s_barrier
	s_add_i32 s71, s62, s50
	v_lshl_add_u64 v[216:217], s[44:45], 0, v[130:131]
	s_mov_b32 m0, s71
	ds_read_b128 v[184:187], v155 offset:16384
	ds_read_b128 v[188:191], v155 offset:17408
	ds_read_b128 v[192:195], v155 offset:18432
	ds_read_b128 v[196:199], v155 offset:19456
	ds_read_b128 v[200:203], v155 offset:20480
	ds_read_b128 v[204:207], v155 offset:21504
	ds_read_b128 v[208:211], v155 offset:22528
	ds_read_b128 v[212:215], v155 offset:23552
	global_load_lds_dwordx4 v[216:217], off
	s_add_i32 m0, s71, 0x2000
	s_add_u32 s72, s44, 0x40000
	v_lshl_add_u64 v[218:219], s[44:45], 0, v[134:135]
	s_addc_u32 s73, s45, 0
	s_add_i32 s71, s63, s50
	global_load_lds_dwordx4 v[218:219], off
	v_lshl_add_u64 v[220:221], s[72:73], 0, v[130:131]
	s_mov_b32 m0, s71
	v_lshl_add_u64 v[222:223], s[46:47], 0, v[132:133]
	global_load_lds_dwordx4 v[220:221], off
	v_lshl_add_u64 v[220:221], s[72:73], 0, v[134:135]
	s_add_i32 m0, s71, 0x2000
	s_nop 0
	global_load_lds_dwordx4 v[220:221], off
	v_lshl_add_u64 v[220:221], s[46:47], 0, v[128:129]
	s_mov_b32 m0, s41
	s_nop 0
	global_load_lds_dwordx4 v[220:221], off
	s_mov_b32 m0, s52
	s_nop 0
	global_load_lds_dwordx4 v[222:223], off
	s_waitcnt vmcnt(8)
	s_waitcnt lgkmcnt(0)
	s_barrier
	s_setprio 1
	v_mfma_f32_16x16x32_bf16 v[60:63], v[146:149], v[184:187], v[60:63]
	v_mfma_f32_16x16x32_bf16 v[56:59], v[160:163], v[184:187], v[56:59]
	v_mfma_f32_16x16x32_bf16 v[44:47], v[146:149], v[192:195], v[44:47]
	v_mfma_f32_16x16x32_bf16 v[40:43], v[160:163], v[192:195], v[40:43]
	v_mfma_f32_16x16x32_bf16 v[28:31], v[146:149], v[200:203], v[28:31]
	v_mfma_f32_16x16x32_bf16 v[24:27], v[160:163], v[200:203], v[24:27]
	v_mfma_f32_16x16x32_bf16 v[12:15], v[146:149], v[208:211], v[12:15]
	v_mfma_f32_16x16x32_bf16 v[8:11], v[160:163], v[208:211], v[8:11]
	v_mfma_f32_16x16x32_bf16 v[60:63], v[156:159], v[188:191], v[60:63]
	v_mfma_f32_16x16x32_bf16 v[56:59], v[164:167], v[188:191], v[56:59]
	v_mfma_f32_16x16x32_bf16 v[44:47], v[156:159], v[196:199], v[44:47]
	v_mfma_f32_16x16x32_bf16 v[40:43], v[164:167], v[196:199], v[40:43]
	v_mfma_f32_16x16x32_bf16 v[28:31], v[156:159], v[204:207], v[28:31]
	v_mfma_f32_16x16x32_bf16 v[24:27], v[164:167], v[204:207], v[24:27]
	v_mfma_f32_16x16x32_bf16 v[12:15], v[156:159], v[212:215], v[12:15]
	v_mfma_f32_16x16x32_bf16 v[8:11], v[164:167], v[212:215], v[8:11]
	s_setprio 0
	s_setprio 1
	v_mfma_f32_16x16x32_bf16 v[52:55], v[168:171], v[184:187], v[52:55]
	v_mfma_f32_16x16x32_bf16 v[48:51], v[176:179], v[184:187], v[48:51]
	v_mfma_f32_16x16x32_bf16 v[36:39], v[168:171], v[192:195], v[36:39]
	v_mfma_f32_16x16x32_bf16 v[32:35], v[176:179], v[192:195], v[32:35]
	v_mfma_f32_16x16x32_bf16 v[20:23], v[168:171], v[200:203], v[20:23]
	v_mfma_f32_16x16x32_bf16 v[16:19], v[176:179], v[200:203], v[16:19]
	v_mfma_f32_16x16x32_bf16 v[4:7], v[168:171], v[208:211], v[4:7]
	v_mfma_f32_16x16x32_bf16 v[0:3], v[176:179], v[208:211], v[0:3]
	v_mfma_f32_16x16x32_bf16 v[52:55], v[172:175], v[188:191], v[52:55]
	v_mfma_f32_16x16x32_bf16 v[48:51], v[180:183], v[188:191], v[48:51]
	v_mfma_f32_16x16x32_bf16 v[36:39], v[172:175], v[196:199], v[36:39]
	v_mfma_f32_16x16x32_bf16 v[32:35], v[180:183], v[196:199], v[32:35]
	v_mfma_f32_16x16x32_bf16 v[20:23], v[172:175], v[204:207], v[20:23]
	v_mfma_f32_16x16x32_bf16 v[16:19], v[180:183], v[204:207], v[16:19]
	v_mfma_f32_16x16x32_bf16 v[4:7], v[172:175], v[212:215], v[4:7]
	v_mfma_f32_16x16x32_bf16 v[0:3], v[180:183], v[212:215], v[0:3]
	s_setprio 0
	s_barrier
; #define PG8_STAGE(bufoff, gbase, voff) do { _Pragma("unroll") for (int _i = 0; _i < 2; ++_i) \
;         __builtin_amdgcn_global_load_lds((const unsigned*)((const char*)(gbase) + (voff)[_i]), (PG8_LAS unsigned*)(lds + (bufoff) + ldsw + _i * 8192), 16, 0, 0); } while (0)
; #define PG8_LDA(dst, b, h) do { _Pragma("unroll") for (int m = 0; m < 4; ++m) _Pragma("unroll") for (int k = 0; k < 2; ++k) dst[m][k] = *(const PG8_LAS bf16x8*)(lds + PG8_SA(b, h) + aoff + m * 2048 + k * 1024); } while (0)
; #define PG8_LDB(dst, b, h) do { _Pragma("unroll") for (int n = 0; n < 2; ++n) _Pragma("unroll") for (int k = 0; k < 2; ++k) dst[n][k] = *(const PG8_LAS bf16x8*)(lds + PG8_SB(b, h) + boff + n * 2048 + k * 1024); } while (0)
; #define PG8_MMA(ai, bj, At, Bt) do { __builtin_amdgcn_s_setprio(1); _Pragma("unroll") for (int m = 0; m < 4; ++m) _Pragma("unroll") for (int n = 0; n < 2; ++n) _Pragma("unroll") for (int k = 0; k < 2; ++k) \
;         acc[ai][bj][m][n] = __builtin_amdgcn_mfma_f32_16x16x32_bf16(Bt[n][k], At[m][k], acc[ai][bj][m][n], 0, 0, 0); __builtin_amdgcn_s_setprio(0); } while (0)
; #define PG8_WAIT_V(n) asm volatile("s_waitcnt vmcnt(" #n ")" ::: "memory")
; #define PG8_WAIT_L(n) asm volatile("s_waitcnt lgkmcnt(" #n ")" ::: "memory")
; #define PG8_BAR __builtin_amdgcn_s_barrier()
; #define PG8_SCHED __builtin_amdgcn_sched_barrier(0)
; template <class Epi, class Sched, bool ALIGN_EPI = false, bool SP2 = false>
; __device__ __forceinline__ void gemm_phase(PG8_LAS unsigned char* lds, const Gemm g, const Sched& S, const Epi& E) {
;     ...
;             PG8_LDB(B0, 1, 0); PG8_LDB(B1, 1, 1); PG8_SCHED; PG8_LDA(At, 1, 0); PG8_STAGE(PG8_SA(0, 1), a2 + hstep, voffA);
;             PG8_WAIT_V(8); PG8_WAIT_L(0); PG8_BAR; PG8_MMA(0, 0, At, B0); PG8_MMA(0, 1, At, B1); PG8_BAR; PG8_SCHED;
	s_add_i32 s71, 0, 0x18000
	s_add_i32 s72, 0, 0x1c000
	v_add_u32_e32 v164, s71, v152
	v_add_u32_e32 v180, s72, v152
	ds_read_b128 v[146:149], v164
	ds_read_b128 v[156:159], v164 offset:1024
	ds_read_b128 v[160:163], v164 offset:2048
	ds_read_b128 v[164:167], v164 offset:3072
	ds_read_b128 v[168:171], v180
	ds_read_b128 v[172:175], v180 offset:1024
	ds_read_b128 v[176:179], v180 offset:2048
	ds_read_b128 v[180:183], v180 offset:3072
	s_add_u32 s46, s46, 0x40000
	s_addc_u32 s47, s47, 0
	s_mov_b32 m0, s53
	v_lshl_add_u64 v[224:225], s[46:47], 0, v[128:129]
	ds_read_b128 v[184:187], v155 offset:32768
	ds_read_b128 v[188:191], v155 offset:33792
	ds_read_b128 v[192:195], v155 offset:34816
	ds_read_b128 v[196:199], v155 offset:35840
	ds_read_b128 v[200:203], v155 offset:36864
	ds_read_b128 v[204:207], v155 offset:37888
	ds_read_b128 v[208:211], v155 offset:38912
	ds_read_b128 v[212:215], v155 offset:39936
	global_load_lds_dwordx4 v[224:225], off
	v_lshl_add_u64 v[224:225], s[46:47], 0, v[132:133]
	s_mov_b32 m0, s54
	s_nop 0
	global_load_lds_dwordx4 v[224:225], off
	s_waitcnt vmcnt(8)
	s_waitcnt lgkmcnt(0)
	s_barrier
	s_setprio 1
	v_mfma_f32_16x16x32_bf16 v[124:127], v[146:149], v[184:187], v[124:127]
	v_mfma_f32_16x16x32_bf16 v[120:123], v[160:163], v[184:187], v[120:123]
	v_mfma_f32_16x16x32_bf16 v[108:111], v[146:149], v[192:195], v[108:111]
	v_mfma_f32_16x16x32_bf16 v[104:107], v[160:163], v[192:195], v[104:107]
	v_mfma_f32_16x16x32_bf16 v[92:95], v[146:149], v[200:203], v[92:95]
	v_mfma_f32_16x16x32_bf16 v[88:91], v[160:163], v[200:203], v[88:91]
	v_mfma_f32_16x16x32_bf16 v[76:79], v[146:149], v[208:211], v[76:79]
	v_mfma_f32_16x16x32_bf16 v[72:75], v[160:163], v[208:211], v[72:75]
	v_mfma_f32_16x16x32_bf16 v[124:127], v[156:159], v[188:191], v[124:127]
	v_mfma_f32_16x16x32_bf16 v[120:123], v[164:167], v[188:191], v[120:123]
	v_mfma_f32_16x16x32_bf16 v[108:111], v[156:159], v[196:199], v[108:111]
	v_mfma_f32_16x16x32_bf16 v[104:107], v[164:167], v[196:199], v[104:107]
	v_mfma_f32_16x16x32_bf16 v[92:95], v[156:159], v[204:207], v[92:95]
	v_mfma_f32_16x16x32_bf16 v[88:91], v[164:167], v[204:207], v[88:91]
	v_mfma_f32_16x16x32_bf16 v[76:79], v[156:159], v[212:215], v[76:79]
	v_mfma_f32_16x16x32_bf16 v[72:75], v[164:167], v[212:215], v[72:75]
	s_setprio 0
	s_setprio 1
	v_mfma_f32_16x16x32_bf16 v[116:119], v[168:171], v[184:187], v[116:119]
	v_mfma_f32_16x16x32_bf16 v[112:115], v[176:179], v[184:187], v[112:115]
	v_mfma_f32_16x16x32_bf16 v[100:103], v[168:171], v[192:195], v[100:103]
	v_mfma_f32_16x16x32_bf16 v[96:99], v[176:179], v[192:195], v[96:99]
	v_mfma_f32_16x16x32_bf16 v[84:87], v[168:171], v[200:203], v[84:87]
	v_mfma_f32_16x16x32_bf16 v[80:83], v[176:179], v[200:203], v[80:83]
	v_mfma_f32_16x16x32_bf16 v[68:71], v[168:171], v[208:211], v[68:71]
	v_mfma_f32_16x16x32_bf16 v[64:67], v[176:179], v[208:211], v[64:67]
	v_mfma_f32_16x16x32_bf16 v[116:119], v[172:175], v[188:191], v[116:119]
	v_mfma_f32_16x16x32_bf16 v[112:115], v[180:183], v[188:191], v[112:115]
	v_mfma_f32_16x16x32_bf16 v[100:103], v[172:175], v[196:199], v[100:103]
	v_mfma_f32_16x16x32_bf16 v[96:99], v[180:183], v[196:199], v[96:99]
	v_mfma_f32_16x16x32_bf16 v[84:87], v[172:175], v[204:207], v[84:87]
	v_mfma_f32_16x16x32_bf16 v[80:83], v[180:183], v[204:207], v[80:83]
	v_mfma_f32_16x16x32_bf16 v[68:71], v[172:175], v[212:215], v[68:71]
	v_mfma_f32_16x16x32_bf16 v[64:67], v[180:183], v[212:215], v[64:67]
	s_setprio 0
	s_barrier
; #define PG8_STAGE(bufoff, gbase, voff) do { _Pragma("unroll") for (int _i = 0; _i < 2; ++_i) \
;         __builtin_amdgcn_global_load_lds((const unsigned*)((const char*)(gbase) + (voff)[_i]), (PG8_LAS unsigned*)(lds + (bufoff) + ldsw + _i * 8192), 16, 0, 0); } while (0)
; #define PG8_LDA(dst, b, h) do { _Pragma("unroll") for (int m = 0; m < 4; ++m) _Pragma("unroll") for (int k = 0; k < 2; ++k) dst[m][k] = *(const PG8_LAS bf16x8*)(lds + PG8_SA(b, h) + aoff + m * 2048 + k * 1024); } while (0)
; #define PG8_MMA(ai, bj, At, Bt) do { __builtin_amdgcn_s_setprio(1); _Pragma("unroll") for (int m = 0; m < 4; ++m) _Pragma("unroll") for (int n = 0; n < 2; ++n) _Pragma("unroll") for (int k = 0; k < 2; ++k) \
;         acc[ai][bj][m][n] = __builtin_amdgcn_mfma_f32_16x16x32_bf16(Bt[n][k], At[m][k], acc[ai][bj][m][n], 0, 0, 0); __builtin_amdgcn_s_setprio(0); } while (0)
; #define PG8_WAIT_V(n) asm volatile("s_waitcnt vmcnt(" #n ")" ::: "memory")
; #define PG8_WAIT_L(n) asm volatile("s_waitcnt lgkmcnt(" #n ")" ::: "memory")
; #define PG8_BAR __builtin_amdgcn_s_barrier()
; #define PG8_SCHED __builtin_amdgcn_sched_barrier(0)
; template <class Epi, class Sched, bool ALIGN_EPI = false, bool SP2 = false>
; __device__ __forceinline__ void gemm_phase(PG8_LAS unsigned char* lds, const Gemm g, const Sched& S, const Epi& E) {
;     ...
;             PG8_LDA(At, 1, 1); PG8_STAGE(PG8_SB(1, 0), b3, voffB); PG8_STAGE(PG8_SB(1, 1), b3 + hstep, voffB); PG8_STAGE(PG8_SA(1, 0), a3, voffA);
;             PG8_WAIT_V(8); PG8_WAIT_L(0); PG8_BAR; PG8_MMA(1, 0, At, B0); PG8_MMA(1, 1, At, B1); PG8_BAR; PG8_SCHED;
;     ...
;         if constexpr (ALIGN_EPI) { if (wr == 0) PG8_BAR; }
	s_add_i32 s46, s71, s50
	v_lshl_add_u64 v[216:217], v[216:217], 0, s[12:13]
	s_mov_b32 m0, s46
	ds_read_b128 v[184:187], v155 offset:49152
	ds_read_b128 v[188:191], v155 offset:50176
	ds_read_b128 v[192:195], v155 offset:51200
	ds_read_b128 v[196:199], v155 offset:52224
	ds_read_b128 v[200:203], v155 offset:53248
	ds_read_b128 v[204:207], v155 offset:54272
	ds_read_b128 v[208:211], v155 offset:55296
	ds_read_b128 v[212:215], v155 offset:56320
	global_load_lds_dwordx4 v[216:217], off
	s_add_i32 m0, s46, 0x2000
	s_add_u32 s44, s44, 0x40080
	v_lshl_add_u64 v[216:217], v[218:219], 0, s[12:13]
	s_addc_u32 s45, s45, 0
	s_add_i32 s46, s72, s50
	global_load_lds_dwordx4 v[216:217], off
	v_lshl_add_u64 v[216:217], s[44:45], 0, v[130:131]
	s_mov_b32 m0, s46
	s_nop 0
	global_load_lds_dwordx4 v[216:217], off
	v_lshl_add_u64 v[216:217], s[44:45], 0, v[134:135]
	s_add_i32 m0, s46, 0x2000
	s_nop 0
	global_load_lds_dwordx4 v[216:217], off
	v_lshl_add_u64 v[216:217], v[220:221], 0, s[12:13]
	s_mov_b32 m0, s59
	s_nop 0
	global_load_lds_dwordx4 v[216:217], off
	v_lshl_add_u64 v[216:217], v[222:223], 0, s[12:13]
	s_mov_b32 m0, s60
	s_nop 0
	global_load_lds_dwordx4 v[216:217], off
	s_waitcnt vmcnt(8)
	s_waitcnt lgkmcnt(0)
	s_barrier
	s_setprio 1
	v_mfma_f32_16x16x32_bf16 v[60:63], v[146:149], v[184:187], v[60:63]
	v_mfma_f32_16x16x32_bf16 v[56:59], v[160:163], v[184:187], v[56:59]
	v_mfma_f32_16x16x32_bf16 v[44:47], v[146:149], v[192:195], v[44:47]
	v_mfma_f32_16x16x32_bf16 v[40:43], v[160:163], v[192:195], v[40:43]
	v_mfma_f32_16x16x32_bf16 v[28:31], v[146:149], v[200:203], v[28:31]
	v_mfma_f32_16x16x32_bf16 v[24:27], v[160:163], v[200:203], v[24:27]
	v_mfma_f32_16x16x32_bf16 v[12:15], v[146:149], v[208:211], v[12:15]
	v_mfma_f32_16x16x32_bf16 v[8:11], v[160:163], v[208:211], v[8:11]
	v_mfma_f32_16x16x32_bf16 v[60:63], v[156:159], v[188:191], v[60:63]
	v_mfma_f32_16x16x32_bf16 v[56:59], v[164:167], v[188:191], v[56:59]
	v_mfma_f32_16x16x32_bf16 v[44:47], v[156:159], v[196:199], v[44:47]
	v_mfma_f32_16x16x32_bf16 v[40:43], v[164:167], v[196:199], v[40:43]
	v_mfma_f32_16x16x32_bf16 v[28:31], v[156:159], v[204:207], v[28:31]
	v_mfma_f32_16x16x32_bf16 v[24:27], v[164:167], v[204:207], v[24:27]
	v_mfma_f32_16x16x32_bf16 v[12:15], v[156:159], v[212:215], v[12:15]
	v_mfma_f32_16x16x32_bf16 v[8:11], v[164:167], v[212:215], v[8:11]
	s_setprio 0
	s_setprio 1
	v_mfma_f32_16x16x32_bf16 v[52:55], v[168:171], v[184:187], v[52:55]
	v_mfma_f32_16x16x32_bf16 v[48:51], v[176:179], v[184:187], v[48:51]
	v_mfma_f32_16x16x32_bf16 v[36:39], v[168:171], v[192:195], v[36:39]
	v_mfma_f32_16x16x32_bf16 v[32:35], v[176:179], v[192:195], v[32:35]
	v_mfma_f32_16x16x32_bf16 v[20:23], v[168:171], v[200:203], v[20:23]
	v_mfma_f32_16x16x32_bf16 v[16:19], v[176:179], v[200:203], v[16:19]
	v_mfma_f32_16x16x32_bf16 v[4:7], v[168:171], v[208:211], v[4:7]
	v_mfma_f32_16x16x32_bf16 v[0:3], v[176:179], v[208:211], v[0:3]
	v_mfma_f32_16x16x32_bf16 v[52:55], v[172:175], v[188:191], v[52:55]
	v_mfma_f32_16x16x32_bf16 v[48:51], v[180:183], v[188:191], v[48:51]
	v_mfma_f32_16x16x32_bf16 v[36:39], v[172:175], v[196:199], v[36:39]
	v_mfma_f32_16x16x32_bf16 v[32:35], v[180:183], v[196:199], v[32:35]
	v_mfma_f32_16x16x32_bf16 v[20:23], v[172:175], v[204:207], v[20:23]
	v_mfma_f32_16x16x32_bf16 v[16:19], v[180:183], v[204:207], v[16:19]
	v_mfma_f32_16x16x32_bf16 v[4:7], v[172:175], v[212:215], v[4:7]
	v_mfma_f32_16x16x32_bf16 v[0:3], v[180:183], v[212:215], v[0:3]
	s_setprio 0
	s_barrier
	s_add_i32 s70, s70, 2
	s_add_u32 s42, s42, 0x100
	s_addc_u32 s43, s43, 0
	s_add_u32 s68, s68, 0x100
	s_addc_u32 s69, s69, 0
	s_cmp_gt_u32 s70, 13
	s_cbranch_scc0 .LBB0_1535
	s_nop 0
	s_and_b64 vcc, exec, s[14:15]
	s_cbranch_vccz .LBB0_1538
	s_barrier

; #define PG8_STAGE(bufoff, gbase, voff) do { _Pragma("unroll") for (int _i = 0; _i < 2; ++_i) \
;         __builtin_amdgcn_global_load_lds((const unsigned*)((const char*)(gbase) + (voff)[_i]), (PG8_LAS unsigned*)(lds + (bufoff) + ldsw + _i * 8192), 16, 0, 0); } while (0)
; #define PG8_LDA(dst, b, h) do { _Pragma("unroll") for (int m = 0; m < 4; ++m) _Pragma("unroll") for (int k = 0; k < 2; ++k) dst[m][k] = *(const PG8_LAS bf16x8*)(lds + PG8_SA(b, h) + aoff + m * 2048 + k * 1024); } while (0)
; #define PG8_LDB(dst, b, h) do { _Pragma("unroll") for (int n = 0; n < 2; ++n) _Pragma("unroll") for (int k = 0; k < 2; ++k) dst[n][k] = *(const PG8_LAS bf16x8*)(lds + PG8_SB(b, h) + boff + n * 2048 + k * 1024); } while (0)
; #define PG8_WAIT_V(n) asm volatile("s_waitcnt vmcnt(" #n ")" ::: "memory")
; #define PG8_WAIT_L(n) asm volatile("s_waitcnt lgkmcnt(" #n ")" ::: "memory")
; #define PG8_BAR __builtin_amdgcn_s_barrier()
; #define PG8_SCHED __builtin_amdgcn_sched_barrier(0)
; template <class Epi, class Sched, bool ALIGN_EPI = false, bool SP2 = false>
; __device__ __forceinline__ void gemm_phase(PG8_LAS unsigned char* lds, const Gemm g, const Sched& S, const Epi& E) {
;     ...
;         const bool has_next = S.next(ui + 1, nxt);
;         const char* nA = has_next ? (const char*)g.A + (size_t)nxt.pm * tstep : cA; const char* nB = has_next ? (const char*)g.Bt + (size_t)nxt.pn * tstep : cB;
;         for (int t = 0; t < nt; t += 2) {
;             const bool last = (t == nt - 2);
;             const char* a1 = cA + (size_t)(t + 1) * kstep;
;             const char* a2 = last ? nA : cA + (size_t)(t + 2) * kstep; const char* b2 = last ? nB : cB + (size_t)(t + 2) * kstep;
;             const char* a3 = a2 + kstep; const char* b3 = b2 + kstep;
;             if (last && has_next) S.a_ready(nxt);
;             if constexpr (SP2) {
;             PG8_LDB(B0, 0, 0); PG8_LDB(B1, 0, 1); PG8_SCHED; PG8_LDA(At, 0, 0); PG8_STAGE(PG8_SA(1, 1), a1 + hstep, voffA);
;             PG8_WAIT_V(8); PG8_WAIT_L(0); PG8_BAR; PG8_MMA(0, 0, At, B0); PG8_MMA(0, 1, At, B1); PG8_BAR; PG8_SCHED;
;             PG8_LDA(At, 0, 1); PG8_STAGE(PG8_SB(0, 0), b2, voffB); PG8_STAGE(PG8_SB(0, 1), b2 + hstep, voffB); PG8_STAGE(PG8_SA(0, 0), a2, voffA);
;             PG8_WAIT_V(8); PG8_WAIT_L(0); PG8_BAR; PG8_MMA(1, 0, At, B0); PG8_MMA(1, 1, At, B1); PG8_BAR; PG8_SCHED;
;     ...
;         cur = nxt; cA = nA; cB = nB; ++ui;
.LBB0_1611:
	s_ashr_i32 s23, s22, 31
	s_lshl_b64 s[36:37], s[22:23], 20
	s_add_u32 s36, s3, s36
	s_addc_u32 s37, s33, s37
	s_and_b64 s[38:39], s[4:5], exec
	s_cselect_b32 s23, s37, s43
	s_cselect_b32 s41, s36, s42
	s_ashr_i32 s19, s18, 31
	s_lshl_b64 s[38:39], s[18:19], 20
	s_add_u32 s38, s48, s38
	s_addc_u32 s39, s49, s39
	s_and_b64 s[46:47], s[4:5], exec
	s_cselect_b32 s19, s39, s45
	s_cselect_b32 s66, s38, s44
	s_add_u32 s42, s42, 0x80080
	s_addc_u32 s43, s43, 0
	s_add_u32 s67, s44, 0x100
	s_addc_u32 s68, s45, 0
	s_mov_b32 s69, -2
	s_waitcnt lgkmcnt(0)
	s_nop 0
	ds_read_b128 v[146:149], v153
	ds_read_b128 v[158:161], v153 offset:1024
	ds_read_b128 v[162:165], v153 offset:2048
	ds_read_b128 v[166:169], v153 offset:3072
	ds_read_b128 v[170:173], v154
	ds_read_b128 v[174:177], v154 offset:1024
	ds_read_b128 v[178:181], v154 offset:2048
	ds_read_b128 v[182:185], v154 offset:3072
	s_add_u32 s44, s42, 0xfff80080
	s_addc_u32 s45, s43, -1
	s_cmp_eq_u32 s69, 28
	s_cselect_b32 s47, s23, s45
	s_cselect_b32 s46, s41, s44
	s_cselect_b32 s45, s19, s68
	s_cselect_b32 s44, s66, s67
	v_lshl_add_u64 v[218:219], s[42:43], 0, v[136:137]
	s_add_i32 m0, s51, 0xc000
	ds_read_b128 v[186:189], v155
	ds_read_b128 v[190:193], v155 offset:1024
	ds_read_b128 v[194:197], v155 offset:2048
	ds_read_b128 v[198:201], v155 offset:3072
	ds_read_b128 v[202:205], v155 offset:4096
	ds_read_b128 v[206:209], v155 offset:5120
	ds_read_b128 v[210:213], v155 offset:6144
	ds_read_b128 v[214:217], v155 offset:7168
	global_load_lds_dwordx4 v[218:219], off
	v_lshl_add_u64 v[218:219], s[42:43], 0, v[138:139]
	s_add_i32 m0, s51, 0xe000
	s_nop 0
	global_load_lds_dwordx4 v[218:219], off
	s_waitcnt vmcnt(8)
	s_waitcnt lgkmcnt(0)
	s_barrier
	s_setprio 1
	v_mfma_f32_16x16x32_bf16 v[124:127], v[146:149], v[186:189], 0
	v_mfma_f32_16x16x32_bf16 v[120:123], v[162:165], v[186:189], 0
	v_mfma_f32_16x16x32_bf16 v[108:111], v[146:149], v[194:197], 0
	v_mfma_f32_16x16x32_bf16 v[104:107], v[162:165], v[194:197], 0
	v_mfma_f32_16x16x32_bf16 v[92:95], v[146:149], v[202:205], 0
	v_mfma_f32_16x16x32_bf16 v[88:91], v[162:165], v[202:205], 0
	v_mfma_f32_16x16x32_bf16 v[76:79], v[146:149], v[210:213], 0
	v_mfma_f32_16x16x32_bf16 v[72:75], v[162:165], v[210:213], 0
	v_mfma_f32_16x16x32_bf16 v[124:127], v[158:161], v[190:193], v[124:127]
	v_mfma_f32_16x16x32_bf16 v[120:123], v[166:169], v[190:193], v[120:123]
	v_mfma_f32_16x16x32_bf16 v[108:111], v[158:161], v[198:201], v[108:111]
	v_mfma_f32_16x16x32_bf16 v[104:107], v[166:169], v[198:201], v[104:107]
	v_mfma_f32_16x16x32_bf16 v[92:95], v[158:161], v[206:209], v[92:95]
	v_mfma_f32_16x16x32_bf16 v[88:91], v[166:169], v[206:209], v[88:91]
	v_mfma_f32_16x16x32_bf16 v[76:79], v[158:161], v[214:217], v[76:79]
	v_mfma_f32_16x16x32_bf16 v[72:75], v[166:169], v[214:217], v[72:75]
	s_setprio 0
	s_setprio 1
	v_mfma_f32_16x16x32_bf16 v[116:119], v[170:173], v[186:189], 0
	v_mfma_f32_16x16x32_bf16 v[112:115], v[178:181], v[186:189], 0
	v_mfma_f32_16x16x32_bf16 v[100:103], v[170:173], v[194:197], 0
	v_mfma_f32_16x16x32_bf16 v[96:99], v[178:181], v[194:197], 0
	v_mfma_f32_16x16x32_bf16 v[84:87], v[170:173], v[202:205], 0
	v_mfma_f32_16x16x32_bf16 v[80:83], v[178:181], v[202:205], 0
	v_mfma_f32_16x16x32_bf16 v[68:71], v[170:173], v[210:213], 0
	v_mfma_f32_16x16x32_bf16 v[64:67], v[178:181], v[210:213], 0
	v_mfma_f32_16x16x32_bf16 v[116:119], v[174:177], v[190:193], v[116:119]
	v_mfma_f32_16x16x32_bf16 v[112:115], v[182:185], v[190:193], v[112:115]
	v_mfma_f32_16x16x32_bf16 v[100:103], v[174:177], v[198:201], v[100:103]
	v_mfma_f32_16x16x32_bf16 v[96:99], v[182:185], v[198:201], v[96:99]
	v_mfma_f32_16x16x32_bf16 v[84:87], v[174:177], v[206:209], v[84:87]
	v_mfma_f32_16x16x32_bf16 v[80:83], v[182:185], v[206:209], v[80:83]
	v_mfma_f32_16x16x32_bf16 v[68:71], v[174:177], v[214:217], v[68:71]
	v_mfma_f32_16x16x32_bf16 v[64:67], v[182:185], v[214:217], v[64:67]
	s_setprio 0
	s_barrier
	s_add_i32 s70, s63, s50
	v_lshl_add_u64 v[218:219], s[44:45], 0, v[130:131]
	s_mov_b32 m0, s70
	ds_read_b128 v[186:189], v155 offset:16384
	ds_read_b128 v[190:193], v155 offset:17408
	ds_read_b128 v[194:197], v155 offset:18432
	ds_read_b128 v[198:201], v155 offset:19456
	ds_read_b128 v[202:205], v155 offset:20480
	ds_read_b128 v[206:209], v155 offset:21504
	ds_read_b128 v[210:213], v155 offset:22528
	ds_read_b128 v[214:217], v155 offset:23552
	global_load_lds_dwordx4 v[218:219], off
	s_add_i32 m0, s70, 0x2000
	s_add_u32 s70, s44, 0x80000
	v_lshl_add_u64 v[220:221], s[44:45], 0, v[134:135]
	s_addc_u32 s71, s45, 0
	s_add_i32 s72, s64, s50
	global_load_lds_dwordx4 v[220:221], off
	v_lshl_add_u64 v[222:223], s[70:71], 0, v[130:131]
	s_mov_b32 m0, s72
	v_lshl_add_u64 v[224:225], s[46:47], 0, v[132:133]
	global_load_lds_dwordx4 v[222:223], off
	v_lshl_add_u64 v[222:223], s[70:71], 0, v[134:135]
	s_add_i32 m0, s72, 0x2000
	s_nop 0
	global_load_lds_dwordx4 v[222:223], off
	v_lshl_add_u64 v[222:223], s[46:47], 0, v[128:129]
	s_mov_b32 m0, s51
	s_nop 0
	global_load_lds_dwordx4 v[222:223], off
	s_mov_b32 m0, s52
	s_nop 0
	global_load_lds_dwordx4 v[224:225], off
	s_waitcnt vmcnt(8)
	s_waitcnt lgkmcnt(0)
	s_barrier
; #define PG8_STAGE(bufoff, gbase, voff) do { _Pragma("unroll") for (int _i = 0; _i < 2; ++_i) \
;         __builtin_amdgcn_global_load_lds((const unsigned*)((const char*)(gbase) + (voff)[_i]), (PG8_LAS unsigned*)(lds + (bufoff) + ldsw + _i * 8192), 16, 0, 0); } while (0)
; #define PG8_LDA(dst, b, h) do { _Pragma("unroll") for (int m = 0; m < 4; ++m) _Pragma("unroll") for (int k = 0; k < 2; ++k) dst[m][k] = *(const PG8_LAS bf16x8*)(lds + PG8_SA(b, h) + aoff + m * 2048 + k * 1024); } while (0)
; #define PG8_LDB(dst, b, h) do { _Pragma("unroll") for (int n = 0; n < 2; ++n) _Pragma("unroll") for (int k = 0; k < 2; ++k) dst[n][k] = *(const PG8_LAS bf16x8*)(lds + PG8_SB(b, h) + boff + n * 2048 + k * 1024); } while (0)
; #define PG8_MMA(ai, bj, At, Bt) do { __builtin_amdgcn_s_setprio(1); _Pragma("unroll") for (int m = 0; m < 4; ++m) _Pragma("unroll") for (int n = 0; n < 2; ++n) _Pragma("unroll") for (int k = 0; k < 2; ++k) \
;         acc[ai][bj][m][n] = __builtin_amdgcn_mfma_f32_16x16x32_bf16(Bt[n][k], At[m][k], acc[ai][bj][m][n], 0, 0, 0); __builtin_amdgcn_s_setprio(0); } while (0)
; #define PG8_WAIT_V(n) asm volatile("s_waitcnt vmcnt(" #n ")" ::: "memory")
; #define PG8_WAIT_L(n) asm volatile("s_waitcnt lgkmcnt(" #n ")" ::: "memory")
; #define PG8_BAR __builtin_amdgcn_s_barrier()
; #define PG8_SCHED __builtin_amdgcn_sched_barrier(0)
; template <class Epi, class Sched, bool ALIGN_EPI = false, bool SP2 = false>
; __device__ __forceinline__ void gemm_phase(PG8_LAS unsigned char* lds, const Gemm g, const Sched& S, const Epi& E) {
;     ...
;             PG8_WAIT_V(8); PG8_WAIT_L(0); PG8_BAR; PG8_MMA(1, 0, At, B0); PG8_MMA(1, 1, At, B1); PG8_BAR; PG8_SCHED;
;             PG8_LDB(B0, 1, 0); PG8_LDB(B1, 1, 1); PG8_SCHED; PG8_LDA(At, 1, 0); PG8_STAGE(PG8_SA(0, 1), a2 + hstep, voffA);
;             PG8_WAIT_V(8); PG8_WAIT_L(0); PG8_BAR; PG8_MMA(0, 0, At, B0); PG8_MMA(0, 1, At, B1); PG8_BAR; PG8_SCHED;
	s_setprio 1
	v_mfma_f32_16x16x32_bf16 v[60:63], v[146:149], v[186:189], 0
	v_mfma_f32_16x16x32_bf16 v[56:59], v[162:165], v[186:189], 0
	v_mfma_f32_16x16x32_bf16 v[44:47], v[146:149], v[194:197], 0
	v_mfma_f32_16x16x32_bf16 v[40:43], v[162:165], v[194:197], 0
	v_mfma_f32_16x16x32_bf16 v[28:31], v[146:149], v[202:205], 0
	v_mfma_f32_16x16x32_bf16 v[24:27], v[162:165], v[202:205], 0
	v_mfma_f32_16x16x32_bf16 v[12:15], v[146:149], v[210:213], 0
	v_mfma_f32_16x16x32_bf16 v[8:11], v[162:165], v[210:213], 0
	v_mfma_f32_16x16x32_bf16 v[60:63], v[158:161], v[190:193], v[60:63]
	v_mfma_f32_16x16x32_bf16 v[56:59], v[166:169], v[190:193], v[56:59]
	v_mfma_f32_16x16x32_bf16 v[44:47], v[158:161], v[198:201], v[44:47]
	v_mfma_f32_16x16x32_bf16 v[40:43], v[166:169], v[198:201], v[40:43]
	v_mfma_f32_16x16x32_bf16 v[28:31], v[158:161], v[206:209], v[28:31]
	v_mfma_f32_16x16x32_bf16 v[24:27], v[166:169], v[206:209], v[24:27]
	v_mfma_f32_16x16x32_bf16 v[12:15], v[158:161], v[214:217], v[12:15]
	v_mfma_f32_16x16x32_bf16 v[8:11], v[166:169], v[214:217], v[8:11]
	s_setprio 0
	s_setprio 1
	v_mfma_f32_16x16x32_bf16 v[52:55], v[170:173], v[186:189], 0
	v_mfma_f32_16x16x32_bf16 v[48:51], v[178:181], v[186:189], 0
	v_mfma_f32_16x16x32_bf16 v[36:39], v[170:173], v[194:197], 0
	v_mfma_f32_16x16x32_bf16 v[32:35], v[178:181], v[194:197], 0
	v_mfma_f32_16x16x32_bf16 v[20:23], v[170:173], v[202:205], 0
	v_mfma_f32_16x16x32_bf16 v[16:19], v[178:181], v[202:205], 0
	v_mfma_f32_16x16x32_bf16 v[4:7], v[170:173], v[210:213], 0
	v_mfma_f32_16x16x32_bf16 v[0:3], v[178:181], v[210:213], 0
	v_mfma_f32_16x16x32_bf16 v[52:55], v[174:177], v[190:193], v[52:55]
	v_mfma_f32_16x16x32_bf16 v[48:51], v[182:185], v[190:193], v[48:51]
	v_mfma_f32_16x16x32_bf16 v[36:39], v[174:177], v[198:201], v[36:39]
	v_mfma_f32_16x16x32_bf16 v[32:35], v[182:185], v[198:201], v[32:35]
	v_mfma_f32_16x16x32_bf16 v[20:23], v[174:177], v[206:209], v[20:23]
	v_mfma_f32_16x16x32_bf16 v[16:19], v[182:185], v[206:209], v[16:19]
	v_mfma_f32_16x16x32_bf16 v[4:7], v[174:177], v[214:217], v[4:7]
	v_mfma_f32_16x16x32_bf16 v[0:3], v[182:185], v[214:217], v[0:3]
	s_setprio 0
	s_barrier
	s_add_i32 s70, 0, 0x18000
	v_add_u32_e32 v157, s70, v152
	s_add_i32 s71, 0, 0x1c000
	ds_read_b128 v[146:149], v157
	ds_read_b128 v[158:161], v157 offset:1024
	ds_read_b128 v[162:165], v157 offset:2048
	ds_read_b128 v[166:169], v157 offset:3072
	v_add_u32_e32 v157, s71, v152
	ds_read_b128 v[170:173], v157
	ds_read_b128 v[174:177], v157 offset:1024
	ds_read_b128 v[178:181], v157 offset:2048
	ds_read_b128 v[182:185], v157 offset:3072
	s_add_u32 s46, s46, 0x80000
	s_addc_u32 s47, s47, 0
	s_mov_b32 m0, s53
	v_lshl_add_u64 v[226:227], s[46:47], 0, v[128:129]
	ds_read_b128 v[186:189], v155 offset:32768
	ds_read_b128 v[190:193], v155 offset:33792
	ds_read_b128 v[194:197], v155 offset:34816
	ds_read_b128 v[198:201], v155 offset:35840
	ds_read_b128 v[202:205], v155 offset:36864
	ds_read_b128 v[206:209], v155 offset:37888
	ds_read_b128 v[210:213], v155 offset:38912
	ds_read_b128 v[214:217], v155 offset:39936
	global_load_lds_dwordx4 v[226:227], off
	v_lshl_add_u64 v[226:227], s[46:47], 0, v[132:133]
	s_mov_b32 m0, s54
	s_nop 0
	global_load_lds_dwordx4 v[226:227], off
	s_waitcnt vmcnt(8)
	s_waitcnt lgkmcnt(0)
	s_barrier
	s_setprio 1
	v_mfma_f32_16x16x32_bf16 v[124:127], v[146:149], v[186:189], v[124:127]
	v_mfma_f32_16x16x32_bf16 v[120:123], v[162:165], v[186:189], v[120:123]
	v_mfma_f32_16x16x32_bf16 v[108:111], v[146:149], v[194:197], v[108:111]
	v_mfma_f32_16x16x32_bf16 v[104:107], v[162:165], v[194:197], v[104:107]
	v_mfma_f32_16x16x32_bf16 v[92:95], v[146:149], v[202:205], v[92:95]
	v_mfma_f32_16x16x32_bf16 v[88:91], v[162:165], v[202:205], v[88:91]
	v_mfma_f32_16x16x32_bf16 v[76:79], v[146:149], v[210:213], v[76:79]
	v_mfma_f32_16x16x32_bf16 v[72:75], v[162:165], v[210:213], v[72:75]
	v_mfma_f32_16x16x32_bf16 v[124:127], v[158:161], v[190:193], v[124:127]
	v_mfma_f32_16x16x32_bf16 v[120:123], v[166:169], v[190:193], v[120:123]
	v_mfma_f32_16x16x32_bf16 v[108:111], v[158:161], v[198:201], v[108:111]
	v_mfma_f32_16x16x32_bf16 v[104:107], v[166:169], v[198:201], v[104:107]
	v_mfma_f32_16x16x32_bf16 v[92:95], v[158:161], v[206:209], v[92:95]
	v_mfma_f32_16x16x32_bf16 v[88:91], v[166:169], v[206:209], v[88:91]
	v_mfma_f32_16x16x32_bf16 v[76:79], v[158:161], v[214:217], v[76:79]
	v_mfma_f32_16x16x32_bf16 v[72:75], v[166:169], v[214:217], v[72:75]
	s_setprio 0
	s_setprio 1
	v_mfma_f32_16x16x32_bf16 v[116:119], v[170:173], v[186:189], v[116:119]
	v_mfma_f32_16x16x32_bf16 v[112:115], v[178:181], v[186:189], v[112:115]
	v_mfma_f32_16x16x32_bf16 v[100:103], v[170:173], v[194:197], v[100:103]
	v_mfma_f32_16x16x32_bf16 v[96:99], v[178:181], v[194:197], v[96:99]
	v_mfma_f32_16x16x32_bf16 v[84:87], v[170:173], v[202:205], v[84:87]
	v_mfma_f32_16x16x32_bf16 v[80:83], v[178:181], v[202:205], v[80:83]
	v_mfma_f32_16x16x32_bf16 v[68:71], v[170:173], v[210:213], v[68:71]
	v_mfma_f32_16x16x32_bf16 v[64:67], v[178:181], v[210:213], v[64:67]
	v_mfma_f32_16x16x32_bf16 v[116:119], v[174:177], v[190:193], v[116:119]
	v_mfma_f32_16x16x32_bf16 v[112:115], v[182:185], v[190:193], v[112:115]
	v_mfma_f32_16x16x32_bf16 v[100:103], v[174:177], v[198:201], v[100:103]
	v_mfma_f32_16x16x32_bf16 v[96:99], v[182:185], v[198:201], v[96:99]
	v_mfma_f32_16x16x32_bf16 v[84:87], v[174:177], v[206:209], v[84:87]
	v_mfma_f32_16x16x32_bf16 v[80:83], v[182:185], v[206:209], v[80:83]
	v_mfma_f32_16x16x32_bf16 v[68:71], v[174:177], v[214:217], v[68:71]
	v_mfma_f32_16x16x32_bf16 v[64:67], v[182:185], v[214:217], v[64:67]
	s_setprio 0
	s_barrier
; #define PG8_STAGE(bufoff, gbase, voff) do { _Pragma("unroll") for (int _i = 0; _i < 2; ++_i) \
;         __builtin_amdgcn_global_load_lds((const unsigned*)((const char*)(gbase) + (voff)[_i]), (PG8_LAS unsigned*)(lds + (bufoff) + ldsw + _i * 8192), 16, 0, 0); } while (0)
; #define PG8_LDA(dst, b, h) do { _Pragma("unroll") for (int m = 0; m < 4; ++m) _Pragma("unroll") for (int k = 0; k < 2; ++k) dst[m][k] = *(const PG8_LAS bf16x8*)(lds + PG8_SA(b, h) + aoff + m * 2048 + k * 1024); } while (0)
; #define PG8_LDB(dst, b, h) do { _Pragma("unroll") for (int n = 0; n < 2; ++n) _Pragma("unroll") for (int k = 0; k < 2; ++k) dst[n][k] = *(const PG8_LAS bf16x8*)(lds + PG8_SB(b, h) + boff + n * 2048 + k * 1024); } while (0)
; #define PG8_MMA(ai, bj, At, Bt) do { __builtin_amdgcn_s_setprio(1); _Pragma("unroll") for (int m = 0; m < 4; ++m) _Pragma("unroll") for (int n = 0; n < 2; ++n) _Pragma("unroll") for (int k = 0; k < 2; ++k) \
;         acc[ai][bj][m][n] = __builtin_amdgcn_mfma_f32_16x16x32_bf16(Bt[n][k], At[m][k], acc[ai][bj][m][n], 0, 0, 0); __builtin_amdgcn_s_setprio(0); } while (0)
; #define PG8_WAIT_V(n) asm volatile("s_waitcnt vmcnt(" #n ")" ::: "memory")
; #define PG8_WAIT_L(n) asm volatile("s_waitcnt lgkmcnt(" #n ")" ::: "memory")
; #define PG8_BAR __builtin_amdgcn_s_barrier()
; #define PG8_SCHED __builtin_amdgcn_sched_barrier(0)
; template <class Epi, class Sched, bool ALIGN_EPI = false, bool SP2 = false>
; __device__ __forceinline__ void gemm_phase(PG8_LAS unsigned char* lds, const Gemm g, const Sched& S, const Epi& E) {
;     ...
;             PG8_LDB(B0, 0, 0); PG8_LDB(B1, 0, 1); PG8_SCHED; PG8_LDA(At, 0, 0); PG8_STAGE(PG8_SA(1, 1), a1 + hstep, voffA);
;             PG8_WAIT_V(8); PG8_WAIT_L(0); PG8_BAR; PG8_MMA(0, 0, At, B0); PG8_MMA(0, 1, At, B1); PG8_BAR; PG8_SCHED;
;     ...
;             PG8_LDA(At, 1, 1); PG8_STAGE(PG8_SB(1, 0), b3, voffB); PG8_STAGE(PG8_SB(1, 1), b3 + hstep, voffB); PG8_STAGE(PG8_SA(1, 0), a3, voffA);
;             PG8_WAIT_V(8); PG8_WAIT_L(0); PG8_BAR; PG8_MMA(1, 0, At, B0); PG8_MMA(1, 1, At, B1); PG8_BAR; PG8_SCHED;
	s_add_i32 s46, s70, s50
	v_lshl_add_u64 v[218:219], v[218:219], 0, s[14:15]
	s_mov_b32 m0, s46
	ds_read_b128 v[186:189], v155 offset:49152
	ds_read_b128 v[190:193], v155 offset:50176
	ds_read_b128 v[194:197], v155 offset:51200
	ds_read_b128 v[198:201], v155 offset:52224
	ds_read_b128 v[202:205], v155 offset:53248
	ds_read_b128 v[206:209], v155 offset:54272
	ds_read_b128 v[210:213], v155 offset:55296
	ds_read_b128 v[214:217], v155 offset:56320
	global_load_lds_dwordx4 v[218:219], off
	s_add_i32 m0, s46, 0x2000
	s_add_u32 s44, s44, 0x80080
	v_lshl_add_u64 v[218:219], v[220:221], 0, s[14:15]
	s_addc_u32 s45, s45, 0
	s_add_i32 s46, s71, s50
	global_load_lds_dwordx4 v[218:219], off
	v_lshl_add_u64 v[218:219], s[44:45], 0, v[130:131]
	s_mov_b32 m0, s46
	s_nop 0
	global_load_lds_dwordx4 v[218:219], off
	v_lshl_add_u64 v[218:219], s[44:45], 0, v[134:135]
	s_add_i32 m0, s46, 0x2000
	s_nop 0
	global_load_lds_dwordx4 v[218:219], off
	v_lshl_add_u64 v[218:219], v[222:223], 0, s[14:15]
	s_mov_b32 m0, s60
	s_nop 0
	global_load_lds_dwordx4 v[218:219], off
	v_lshl_add_u64 v[218:219], v[224:225], 0, s[14:15]
	s_mov_b32 m0, s61
	s_nop 0
	global_load_lds_dwordx4 v[218:219], off
	s_waitcnt vmcnt(8)
	s_waitcnt lgkmcnt(0)
	s_barrier
	s_setprio 1
	v_mfma_f32_16x16x32_bf16 v[60:63], v[146:149], v[186:189], v[60:63]
	v_mfma_f32_16x16x32_bf16 v[56:59], v[162:165], v[186:189], v[56:59]
	v_mfma_f32_16x16x32_bf16 v[44:47], v[146:149], v[194:197], v[44:47]
	v_mfma_f32_16x16x32_bf16 v[40:43], v[162:165], v[194:197], v[40:43]
	v_mfma_f32_16x16x32_bf16 v[28:31], v[146:149], v[202:205], v[28:31]
	v_mfma_f32_16x16x32_bf16 v[24:27], v[162:165], v[202:205], v[24:27]
	v_mfma_f32_16x16x32_bf16 v[12:15], v[146:149], v[210:213], v[12:15]
	v_mfma_f32_16x16x32_bf16 v[8:11], v[162:165], v[210:213], v[8:11]
	v_mfma_f32_16x16x32_bf16 v[60:63], v[158:161], v[190:193], v[60:63]
	v_mfma_f32_16x16x32_bf16 v[56:59], v[166:169], v[190:193], v[56:59]
	v_mfma_f32_16x16x32_bf16 v[44:47], v[158:161], v[198:201], v[44:47]
	v_mfma_f32_16x16x32_bf16 v[40:43], v[166:169], v[198:201], v[40:43]
	v_mfma_f32_16x16x32_bf16 v[28:31], v[158:161], v[206:209], v[28:31]
	v_mfma_f32_16x16x32_bf16 v[24:27], v[166:169], v[206:209], v[24:27]
	v_mfma_f32_16x16x32_bf16 v[12:15], v[158:161], v[214:217], v[12:15]
	v_mfma_f32_16x16x32_bf16 v[8:11], v[166:169], v[214:217], v[8:11]
	s_setprio 0
	s_setprio 1
	v_mfma_f32_16x16x32_bf16 v[52:55], v[170:173], v[186:189], v[52:55]
	v_mfma_f32_16x16x32_bf16 v[48:51], v[178:181], v[186:189], v[48:51]
	v_mfma_f32_16x16x32_bf16 v[36:39], v[170:173], v[194:197], v[36:39]
	v_mfma_f32_16x16x32_bf16 v[32:35], v[178:181], v[194:197], v[32:35]
	v_mfma_f32_16x16x32_bf16 v[20:23], v[170:173], v[202:205], v[20:23]
	v_mfma_f32_16x16x32_bf16 v[16:19], v[178:181], v[202:205], v[16:19]
	v_mfma_f32_16x16x32_bf16 v[4:7], v[170:173], v[210:213], v[4:7]
	v_mfma_f32_16x16x32_bf16 v[0:3], v[178:181], v[210:213], v[0:3]
	v_mfma_f32_16x16x32_bf16 v[52:55], v[174:177], v[190:193], v[52:55]
	v_mfma_f32_16x16x32_bf16 v[48:51], v[182:185], v[190:193], v[48:51]
	v_mfma_f32_16x16x32_bf16 v[36:39], v[174:177], v[198:201], v[36:39]
	v_mfma_f32_16x16x32_bf16 v[32:35], v[182:185], v[198:201], v[32:35]
	v_mfma_f32_16x16x32_bf16 v[20:23], v[174:177], v[206:209], v[20:23]
	v_mfma_f32_16x16x32_bf16 v[16:19], v[182:185], v[206:209], v[16:19]
	v_mfma_f32_16x16x32_bf16 v[4:7], v[174:177], v[214:217], v[4:7]
	v_mfma_f32_16x16x32_bf16 v[0:3], v[182:185], v[214:217], v[0:3]
	s_setprio 0
	s_barrier
	s_add_i32 s69, s69, 2
	s_add_u32 s42, s42, 0x100
	s_addc_u32 s43, s43, 0
	s_add_u32 s67, s67, 0x100
	s_addc_u32 s68, s68, 0
	s_cmp_gt_u32 s69, 29
.LBB0_1612:
	ds_read_b128 v[146:149], v153
	ds_read_b128 v[158:161], v153 offset:1024
	ds_read_b128 v[162:165], v153 offset:2048
	ds_read_b128 v[166:169], v153 offset:3072
	ds_read_b128 v[170:173], v154
	ds_read_b128 v[174:177], v154 offset:1024
	ds_read_b128 v[178:181], v154 offset:2048
	ds_read_b128 v[182:185], v154 offset:3072
	s_add_u32 s44, s42, 0xfff80080
	s_addc_u32 s45, s43, -1
	s_cmp_eq_u32 s69, 28
	s_cselect_b32 s47, s23, s45
	s_cselect_b32 s46, s41, s44
	s_cselect_b32 s45, s19, s68
	s_cselect_b32 s44, s66, s67
	v_lshl_add_u64 v[218:219], s[42:43], 0, v[136:137]
	s_add_i32 m0, s51, 0xc000
	ds_read_b128 v[186:189], v155
	ds_read_b128 v[190:193], v155 offset:1024
	ds_read_b128 v[194:197], v155 offset:2048
	ds_read_b128 v[198:201], v155 offset:3072
	ds_read_b128 v[202:205], v155 offset:4096
	ds_read_b128 v[206:209], v155 offset:5120
	ds_read_b128 v[210:213], v155 offset:6144
	ds_read_b128 v[214:217], v155 offset:7168
	global_load_lds_dwordx4 v[218:219], off
	v_lshl_add_u64 v[218:219], s[42:43], 0, v[138:139]
	s_add_i32 m0, s51, 0xe000
	s_nop 0
	global_load_lds_dwordx4 v[218:219], off
	s_waitcnt vmcnt(8)
	s_waitcnt lgkmcnt(0)
	s_barrier
; #define PG8_STAGE(bufoff, gbase, voff) do { _Pragma("unroll") for (int _i = 0; _i < 2; ++_i) \
;         __builtin_amdgcn_global_load_lds((const unsigned*)((const char*)(gbase) + (voff)[_i]), (PG8_LAS unsigned*)(lds + (bufoff) + ldsw + _i * 8192), 16, 0, 0); } while (0)
; #define PG8_LDA(dst, b, h) do { _Pragma("unroll") for (int m = 0; m < 4; ++m) _Pragma("unroll") for (int k = 0; k < 2; ++k) dst[m][k] = *(const PG8_LAS bf16x8*)(lds + PG8_SA(b, h) + aoff + m * 2048 + k * 1024); } while (0)
; #define PG8_MMA(ai, bj, At, Bt) do { __builtin_amdgcn_s_setprio(1); _Pragma("unroll") for (int m = 0; m < 4; ++m) _Pragma("unroll") for (int n = 0; n < 2; ++n) _Pragma("unroll") for (int k = 0; k < 2; ++k) \
;         acc[ai][bj][m][n] = __builtin_amdgcn_mfma_f32_16x16x32_bf16(Bt[n][k], At[m][k], acc[ai][bj][m][n], 0, 0, 0); __builtin_amdgcn_s_setprio(0); } while (0)
; #define PG8_WAIT_V(n) asm volatile("s_waitcnt vmcnt(" #n ")" ::: "memory")
; #define PG8_WAIT_L(n) asm volatile("s_waitcnt lgkmcnt(" #n ")" ::: "memory")
; #define PG8_BAR __builtin_amdgcn_s_barrier()
; #define PG8_SCHED __builtin_amdgcn_sched_barrier(0)
; template <class Epi, class Sched, bool ALIGN_EPI = false, bool SP2 = false>
; __device__ __forceinline__ void gemm_phase(PG8_LAS unsigned char* lds, const Gemm g, const Sched& S, const Epi& E) {
;     ...
;             PG8_WAIT_V(8); PG8_WAIT_L(0); PG8_BAR; PG8_MMA(0, 0, At, B0); PG8_MMA(0, 1, At, B1); PG8_BAR; PG8_SCHED;
;             PG8_LDA(At, 0, 1); PG8_STAGE(PG8_SB(0, 0), b2, voffB); PG8_STAGE(PG8_SB(0, 1), b2 + hstep, voffB); PG8_STAGE(PG8_SA(0, 0), a2, voffA);
;             PG8_WAIT_V(8); PG8_WAIT_L(0); PG8_BAR; PG8_MMA(1, 0, At, B0); PG8_MMA(1, 1, At, B1); PG8_BAR; PG8_SCHED;
	s_setprio 1
	v_mfma_f32_16x16x32_bf16 v[124:127], v[146:149], v[186:189], v[124:127]
	v_mfma_f32_16x16x32_bf16 v[120:123], v[162:165], v[186:189], v[120:123]
	v_mfma_f32_16x16x32_bf16 v[108:111], v[146:149], v[194:197], v[108:111]
	v_mfma_f32_16x16x32_bf16 v[104:107], v[162:165], v[194:197], v[104:107]
	v_mfma_f32_16x16x32_bf16 v[92:95], v[146:149], v[202:205], v[92:95]
	v_mfma_f32_16x16x32_bf16 v[88:91], v[162:165], v[202:205], v[88:91]
	v_mfma_f32_16x16x32_bf16 v[76:79], v[146:149], v[210:213], v[76:79]
	v_mfma_f32_16x16x32_bf16 v[72:75], v[162:165], v[210:213], v[72:75]
	v_mfma_f32_16x16x32_bf16 v[124:127], v[158:161], v[190:193], v[124:127]
	v_mfma_f32_16x16x32_bf16 v[120:123], v[166:169], v[190:193], v[120:123]
	v_mfma_f32_16x16x32_bf16 v[108:111], v[158:161], v[198:201], v[108:111]
	v_mfma_f32_16x16x32_bf16 v[104:107], v[166:169], v[198:201], v[104:107]
	v_mfma_f32_16x16x32_bf16 v[92:95], v[158:161], v[206:209], v[92:95]
	v_mfma_f32_16x16x32_bf16 v[88:91], v[166:169], v[206:209], v[88:91]
	v_mfma_f32_16x16x32_bf16 v[76:79], v[158:161], v[214:217], v[76:79]
	v_mfma_f32_16x16x32_bf16 v[72:75], v[166:169], v[214:217], v[72:75]
	s_setprio 0
	s_setprio 1
	v_mfma_f32_16x16x32_bf16 v[116:119], v[170:173], v[186:189], v[116:119]
	v_mfma_f32_16x16x32_bf16 v[112:115], v[178:181], v[186:189], v[112:115]
	v_mfma_f32_16x16x32_bf16 v[100:103], v[170:173], v[194:197], v[100:103]
	v_mfma_f32_16x16x32_bf16 v[96:99], v[178:181], v[194:197], v[96:99]
	v_mfma_f32_16x16x32_bf16 v[84:87], v[170:173], v[202:205], v[84:87]
	v_mfma_f32_16x16x32_bf16 v[80:83], v[178:181], v[202:205], v[80:83]
	v_mfma_f32_16x16x32_bf16 v[68:71], v[170:173], v[210:213], v[68:71]
	v_mfma_f32_16x16x32_bf16 v[64:67], v[178:181], v[210:213], v[64:67]
	v_mfma_f32_16x16x32_bf16 v[116:119], v[174:177], v[190:193], v[116:119]
	v_mfma_f32_16x16x32_bf16 v[112:115], v[182:185], v[190:193], v[112:115]
	v_mfma_f32_16x16x32_bf16 v[100:103], v[174:177], v[198:201], v[100:103]
	v_mfma_f32_16x16x32_bf16 v[96:99], v[182:185], v[198:201], v[96:99]
	v_mfma_f32_16x16x32_bf16 v[84:87], v[174:177], v[206:209], v[84:87]
	v_mfma_f32_16x16x32_bf16 v[80:83], v[182:185], v[206:209], v[80:83]
	v_mfma_f32_16x16x32_bf16 v[68:71], v[174:177], v[214:217], v[68:71]
	v_mfma_f32_16x16x32_bf16 v[64:67], v[182:185], v[214:217], v[64:67]
	s_setprio 0
	s_barrier
	s_add_i32 s70, s63, s50
	v_lshl_add_u64 v[218:219], s[44:45], 0, v[130:131]
	s_mov_b32 m0, s70
	ds_read_b128 v[186:189], v155 offset:16384
	ds_read_b128 v[190:193], v155 offset:17408
	ds_read_b128 v[194:197], v155 offset:18432
	ds_read_b128 v[198:201], v155 offset:19456
	ds_read_b128 v[202:205], v155 offset:20480
	ds_read_b128 v[206:209], v155 offset:21504
	ds_read_b128 v[210:213], v155 offset:22528
	ds_read_b128 v[214:217], v155 offset:23552
	global_load_lds_dwordx4 v[218:219], off
	s_add_i32 m0, s70, 0x2000
	s_add_u32 s70, s44, 0x80000
	v_lshl_add_u64 v[220:221], s[44:45], 0, v[134:135]
	s_addc_u32 s71, s45, 0
	s_add_i32 s72, s64, s50
	global_load_lds_dwordx4 v[220:221], off
	v_lshl_add_u64 v[222:223], s[70:71], 0, v[130:131]
	s_mov_b32 m0, s72
	v_lshl_add_u64 v[224:225], s[46:47], 0, v[132:133]
	global_load_lds_dwordx4 v[222:223], off
	v_lshl_add_u64 v[222:223], s[70:71], 0, v[134:135]
	s_add_i32 m0, s72, 0x2000
	s_nop 0
	global_load_lds_dwordx4 v[222:223], off
	v_lshl_add_u64 v[222:223], s[46:47], 0, v[128:129]
	s_mov_b32 m0, s51
	s_nop 0
	global_load_lds_dwordx4 v[222:223], off
	s_mov_b32 m0, s52
	s_nop 0
	global_load_lds_dwordx4 v[224:225], off
	s_waitcnt vmcnt(8)
	s_waitcnt lgkmcnt(0)
	s_barrier
	s_setprio 1
	v_mfma_f32_16x16x32_bf16 v[60:63], v[146:149], v[186:189], v[60:63]
	v_mfma_f32_16x16x32_bf16 v[56:59], v[162:165], v[186:189], v[56:59]
	v_mfma_f32_16x16x32_bf16 v[44:47], v[146:149], v[194:197], v[44:47]
	v_mfma_f32_16x16x32_bf16 v[40:43], v[162:165], v[194:197], v[40:43]
	v_mfma_f32_16x16x32_bf16 v[28:31], v[146:149], v[202:205], v[28:31]
	v_mfma_f32_16x16x32_bf16 v[24:27], v[162:165], v[202:205], v[24:27]
	v_mfma_f32_16x16x32_bf16 v[12:15], v[146:149], v[210:213], v[12:15]
	v_mfma_f32_16x16x32_bf16 v[8:11], v[162:165], v[210:213], v[8:11]
	v_mfma_f32_16x16x32_bf16 v[60:63], v[158:161], v[190:193], v[60:63]
	v_mfma_f32_16x16x32_bf16 v[56:59], v[166:169], v[190:193], v[56:59]
	v_mfma_f32_16x16x32_bf16 v[44:47], v[158:161], v[198:201], v[44:47]
	v_mfma_f32_16x16x32_bf16 v[40:43], v[166:169], v[198:201], v[40:43]
	v_mfma_f32_16x16x32_bf16 v[28:31], v[158:161], v[206:209], v[28:31]
	v_mfma_f32_16x16x32_bf16 v[24:27], v[166:169], v[206:209], v[24:27]
	v_mfma_f32_16x16x32_bf16 v[12:15], v[158:161], v[214:217], v[12:15]
	v_mfma_f32_16x16x32_bf16 v[8:11], v[166:169], v[214:217], v[8:11]
	s_setprio 0
	s_setprio 1
	v_mfma_f32_16x16x32_bf16 v[52:55], v[170:173], v[186:189], v[52:55]
	v_mfma_f32_16x16x32_bf16 v[48:51], v[178:181], v[186:189], v[48:51]
	v_mfma_f32_16x16x32_bf16 v[36:39], v[170:173], v[194:197], v[36:39]
	v_mfma_f32_16x16x32_bf16 v[32:35], v[178:181], v[194:197], v[32:35]
	v_mfma_f32_16x16x32_bf16 v[20:23], v[170:173], v[202:205], v[20:23]
	v_mfma_f32_16x16x32_bf16 v[16:19], v[178:181], v[202:205], v[16:19]
	v_mfma_f32_16x16x32_bf16 v[4:7], v[170:173], v[210:213], v[4:7]
	v_mfma_f32_16x16x32_bf16 v[0:3], v[178:181], v[210:213], v[0:3]
	v_mfma_f32_16x16x32_bf16 v[52:55], v[174:177], v[190:193], v[52:55]
	v_mfma_f32_16x16x32_bf16 v[48:51], v[182:185], v[190:193], v[48:51]
	v_mfma_f32_16x16x32_bf16 v[36:39], v[174:177], v[198:201], v[36:39]
	v_mfma_f32_16x16x32_bf16 v[32:35], v[182:185], v[198:201], v[32:35]
	v_mfma_f32_16x16x32_bf16 v[20:23], v[174:177], v[206:209], v[20:23]
	v_mfma_f32_16x16x32_bf16 v[16:19], v[182:185], v[206:209], v[16:19]
	v_mfma_f32_16x16x32_bf16 v[4:7], v[174:177], v[214:217], v[4:7]
	v_mfma_f32_16x16x32_bf16 v[0:3], v[182:185], v[214:217], v[0:3]
	s_setprio 0
	s_barrier
; #define PG8_STAGE(bufoff, gbase, voff) do { _Pragma("unroll") for (int _i = 0; _i < 2; ++_i) \
;         __builtin_amdgcn_global_load_lds((const unsigned*)((const char*)(gbase) + (voff)[_i]), (PG8_LAS unsigned*)(lds + (bufoff) + ldsw + _i * 8192), 16, 0, 0); } while (0)
; #define PG8_LDA(dst, b, h) do { _Pragma("unroll") for (int m = 0; m < 4; ++m) _Pragma("unroll") for (int k = 0; k < 2; ++k) dst[m][k] = *(const PG8_LAS bf16x8*)(lds + PG8_SA(b, h) + aoff + m * 2048 + k * 1024); } while (0)
; #define PG8_LDB(dst, b, h) do { _Pragma("unroll") for (int n = 0; n < 2; ++n) _Pragma("unroll") for (int k = 0; k < 2; ++k) dst[n][k] = *(const PG8_LAS bf16x8*)(lds + PG8_SB(b, h) + boff + n * 2048 + k * 1024); } while (0)
; #define PG8_MMA(ai, bj, At, Bt) do { __builtin_amdgcn_s_setprio(1); _Pragma("unroll") for (int m = 0; m < 4; ++m) _Pragma("unroll") for (int n = 0; n < 2; ++n) _Pragma("unroll") for (int k = 0; k < 2; ++k) \
;         acc[ai][bj][m][n] = __builtin_amdgcn_mfma_f32_16x16x32_bf16(Bt[n][k], At[m][k], acc[ai][bj][m][n], 0, 0, 0); __builtin_amdgcn_s_setprio(0); } while (0)
; #define PG8_WAIT_V(n) asm volatile("s_waitcnt vmcnt(" #n ")" ::: "memory")
; #define PG8_WAIT_L(n) asm volatile("s_waitcnt lgkmcnt(" #n ")" ::: "memory")
; #define PG8_BAR __builtin_amdgcn_s_barrier()
; #define PG8_SCHED __builtin_amdgcn_sched_barrier(0)
; template <class Epi, class Sched, bool ALIGN_EPI = false, bool SP2 = false>
; __device__ __forceinline__ void gemm_phase(PG8_LAS unsigned char* lds, const Gemm g, const Sched& S, const Epi& E) {
;     ...
;             PG8_LDB(B0, 1, 0); PG8_LDB(B1, 1, 1); PG8_SCHED; PG8_LDA(At, 1, 0); PG8_STAGE(PG8_SA(0, 1), a2 + hstep, voffA);
;             PG8_WAIT_V(8); PG8_WAIT_L(0); PG8_BAR; PG8_MMA(0, 0, At, B0); PG8_MMA(0, 1, At, B1); PG8_BAR; PG8_SCHED;
	s_add_i32 s70, 0, 0x18000
	v_add_u32_e32 v157, s70, v152
	s_add_i32 s71, 0, 0x1c000
	ds_read_b128 v[146:149], v157
	ds_read_b128 v[158:161], v157 offset:1024
	ds_read_b128 v[162:165], v157 offset:2048
	ds_read_b128 v[166:169], v157 offset:3072
	v_add_u32_e32 v157, s71, v152
	ds_read_b128 v[170:173], v157
	ds_read_b128 v[174:177], v157 offset:1024
	ds_read_b128 v[178:181], v157 offset:2048
	ds_read_b128 v[182:185], v157 offset:3072
	s_add_u32 s46, s46, 0x80000
	s_addc_u32 s47, s47, 0
	s_mov_b32 m0, s53
	v_lshl_add_u64 v[226:227], s[46:47], 0, v[128:129]
	ds_read_b128 v[186:189], v155 offset:32768
	ds_read_b128 v[190:193], v155 offset:33792
	ds_read_b128 v[194:197], v155 offset:34816
	ds_read_b128 v[198:201], v155 offset:35840
	ds_read_b128 v[202:205], v155 offset:36864
	ds_read_b128 v[206:209], v155 offset:37888
	ds_read_b128 v[210:213], v155 offset:38912
	ds_read_b128 v[214:217], v155 offset:39936
	global_load_lds_dwordx4 v[226:227], off
	v_lshl_add_u64 v[226:227], s[46:47], 0, v[132:133]
	s_mov_b32 m0, s54
	s_nop 0
	global_load_lds_dwordx4 v[226:227], off
	s_waitcnt vmcnt(8)
	s_waitcnt lgkmcnt(0)
	s_barrier
	s_setprio 1
	v_mfma_f32_16x16x32_bf16 v[124:127], v[146:149], v[186:189], v[124:127]
	v_mfma_f32_16x16x32_bf16 v[120:123], v[162:165], v[186:189], v[120:123]
	v_mfma_f32_16x16x32_bf16 v[108:111], v[146:149], v[194:197], v[108:111]
	v_mfma_f32_16x16x32_bf16 v[104:107], v[162:165], v[194:197], v[104:107]
	v_mfma_f32_16x16x32_bf16 v[92:95], v[146:149], v[202:205], v[92:95]
	v_mfma_f32_16x16x32_bf16 v[88:91], v[162:165], v[202:205], v[88:91]
	v_mfma_f32_16x16x32_bf16 v[76:79], v[146:149], v[210:213], v[76:79]
	v_mfma_f32_16x16x32_bf16 v[72:75], v[162:165], v[210:213], v[72:75]
	v_mfma_f32_16x16x32_bf16 v[124:127], v[158:161], v[190:193], v[124:127]
	v_mfma_f32_16x16x32_bf16 v[120:123], v[166:169], v[190:193], v[120:123]
	v_mfma_f32_16x16x32_bf16 v[108:111], v[158:161], v[198:201], v[108:111]
	v_mfma_f32_16x16x32_bf16 v[104:107], v[166:169], v[198:201], v[104:107]
	v_mfma_f32_16x16x32_bf16 v[92:95], v[158:161], v[206:209], v[92:95]
	v_mfma_f32_16x16x32_bf16 v[88:91], v[166:169], v[206:209], v[88:91]
	v_mfma_f32_16x16x32_bf16 v[76:79], v[158:161], v[214:217], v[76:79]
	v_mfma_f32_16x16x32_bf16 v[72:75], v[166:169], v[214:217], v[72:75]
	s_setprio 0
	s_setprio 1
	v_mfma_f32_16x16x32_bf16 v[116:119], v[170:173], v[186:189], v[116:119]
	v_mfma_f32_16x16x32_bf16 v[112:115], v[178:181], v[186:189], v[112:115]
	v_mfma_f32_16x16x32_bf16 v[100:103], v[170:173], v[194:197], v[100:103]
	v_mfma_f32_16x16x32_bf16 v[96:99], v[178:181], v[194:197], v[96:99]
	v_mfma_f32_16x16x32_bf16 v[84:87], v[170:173], v[202:205], v[84:87]
	v_mfma_f32_16x16x32_bf16 v[80:83], v[178:181], v[202:205], v[80:83]
	v_mfma_f32_16x16x32_bf16 v[68:71], v[170:173], v[210:213], v[68:71]
	v_mfma_f32_16x16x32_bf16 v[64:67], v[178:181], v[210:213], v[64:67]
	v_mfma_f32_16x16x32_bf16 v[116:119], v[174:177], v[190:193], v[116:119]
	v_mfma_f32_16x16x32_bf16 v[112:115], v[182:185], v[190:193], v[112:115]
	v_mfma_f32_16x16x32_bf16 v[100:103], v[174:177], v[198:201], v[100:103]
	v_mfma_f32_16x16x32_bf16 v[96:99], v[182:185], v[198:201], v[96:99]
	v_mfma_f32_16x16x32_bf16 v[84:87], v[174:177], v[206:209], v[84:87]
	v_mfma_f32_16x16x32_bf16 v[80:83], v[182:185], v[206:209], v[80:83]
	v_mfma_f32_16x16x32_bf16 v[68:71], v[174:177], v[214:217], v[68:71]
	v_mfma_f32_16x16x32_bf16 v[64:67], v[182:185], v[214:217], v[64:67]
	s_setprio 0
	s_barrier
; #define PG8_STAGE(bufoff, gbase, voff) do { _Pragma("unroll") for (int _i = 0; _i < 2; ++_i) \
;         __builtin_amdgcn_global_load_lds((const unsigned*)((const char*)(gbase) + (voff)[_i]), (PG8_LAS unsigned*)(lds + (bufoff) + ldsw + _i * 8192), 16, 0, 0); } while (0)
; #define PG8_LDA(dst, b, h) do { _Pragma("unroll") for (int m = 0; m < 4; ++m) _Pragma("unroll") for (int k = 0; k < 2; ++k) dst[m][k] = *(const PG8_LAS bf16x8*)(lds + PG8_SA(b, h) + aoff + m * 2048 + k * 1024); } while (0)
; #define PG8_MMA(ai, bj, At, Bt) do { __builtin_amdgcn_s_setprio(1); _Pragma("unroll") for (int m = 0; m < 4; ++m) _Pragma("unroll") for (int n = 0; n < 2; ++n) _Pragma("unroll") for (int k = 0; k < 2; ++k) \
;         acc[ai][bj][m][n] = __builtin_amdgcn_mfma_f32_16x16x32_bf16(Bt[n][k], At[m][k], acc[ai][bj][m][n], 0, 0, 0); __builtin_amdgcn_s_setprio(0); } while (0)
; #define PG8_WAIT_V(n) asm volatile("s_waitcnt vmcnt(" #n ")" ::: "memory")
; #define PG8_WAIT_L(n) asm volatile("s_waitcnt lgkmcnt(" #n ")" ::: "memory")
; #define PG8_BAR __builtin_amdgcn_s_barrier()
; #define PG8_SCHED __builtin_amdgcn_sched_barrier(0)
; template <class Epi, class Sched, bool ALIGN_EPI = false, bool SP2 = false>
; __device__ __forceinline__ void gemm_phase(PG8_LAS unsigned char* lds, const Gemm g, const Sched& S, const Epi& E) {
;     ...
;             PG8_LDA(At, 1, 1); PG8_STAGE(PG8_SB(1, 0), b3, voffB); PG8_STAGE(PG8_SB(1, 1), b3 + hstep, voffB); PG8_STAGE(PG8_SA(1, 0), a3, voffA);
;             PG8_WAIT_V(8); PG8_WAIT_L(0); PG8_BAR; PG8_MMA(1, 0, At, B0); PG8_MMA(1, 1, At, B1); PG8_BAR; PG8_SCHED;
;     ...
;         if constexpr (ALIGN_EPI) { if (wr == 0) PG8_BAR; }
	s_add_i32 s46, s70, s50
	v_lshl_add_u64 v[218:219], v[218:219], 0, s[14:15]
	s_mov_b32 m0, s46
	ds_read_b128 v[186:189], v155 offset:49152
	ds_read_b128 v[190:193], v155 offset:50176
	ds_read_b128 v[194:197], v155 offset:51200
	ds_read_b128 v[198:201], v155 offset:52224
	ds_read_b128 v[202:205], v155 offset:53248
	ds_read_b128 v[206:209], v155 offset:54272
	ds_read_b128 v[210:213], v155 offset:55296
	ds_read_b128 v[214:217], v155 offset:56320
	global_load_lds_dwordx4 v[218:219], off
	s_add_i32 m0, s46, 0x2000
	s_add_u32 s44, s44, 0x80080
	v_lshl_add_u64 v[218:219], v[220:221], 0, s[14:15]
	s_addc_u32 s45, s45, 0
	s_add_i32 s46, s71, s50
	global_load_lds_dwordx4 v[218:219], off
	v_lshl_add_u64 v[218:219], s[44:45], 0, v[130:131]
	s_mov_b32 m0, s46
	s_nop 0
	global_load_lds_dwordx4 v[218:219], off
	v_lshl_add_u64 v[218:219], s[44:45], 0, v[134:135]
	s_add_i32 m0, s46, 0x2000
	s_nop 0
	global_load_lds_dwordx4 v[218:219], off
	v_lshl_add_u64 v[218:219], v[222:223], 0, s[14:15]
	s_mov_b32 m0, s60
	s_nop 0
	global_load_lds_dwordx4 v[218:219], off
	v_lshl_add_u64 v[218:219], v[224:225], 0, s[14:15]
	s_mov_b32 m0, s61
	s_nop 0
	global_load_lds_dwordx4 v[218:219], off
	s_waitcnt vmcnt(8)
	s_waitcnt lgkmcnt(0)
	s_barrier
	s_setprio 1
	v_mfma_f32_16x16x32_bf16 v[60:63], v[146:149], v[186:189], v[60:63]
	v_mfma_f32_16x16x32_bf16 v[56:59], v[162:165], v[186:189], v[56:59]
	v_mfma_f32_16x16x32_bf16 v[44:47], v[146:149], v[194:197], v[44:47]
	v_mfma_f32_16x16x32_bf16 v[40:43], v[162:165], v[194:197], v[40:43]
	v_mfma_f32_16x16x32_bf16 v[28:31], v[146:149], v[202:205], v[28:31]
	v_mfma_f32_16x16x32_bf16 v[24:27], v[162:165], v[202:205], v[24:27]
	v_mfma_f32_16x16x32_bf16 v[12:15], v[146:149], v[210:213], v[12:15]
	v_mfma_f32_16x16x32_bf16 v[8:11], v[162:165], v[210:213], v[8:11]
	v_mfma_f32_16x16x32_bf16 v[60:63], v[158:161], v[190:193], v[60:63]
	v_mfma_f32_16x16x32_bf16 v[56:59], v[166:169], v[190:193], v[56:59]
	v_mfma_f32_16x16x32_bf16 v[44:47], v[158:161], v[198:201], v[44:47]
	v_mfma_f32_16x16x32_bf16 v[40:43], v[166:169], v[198:201], v[40:43]
	v_mfma_f32_16x16x32_bf16 v[28:31], v[158:161], v[206:209], v[28:31]
	v_mfma_f32_16x16x32_bf16 v[24:27], v[166:169], v[206:209], v[24:27]
	v_mfma_f32_16x16x32_bf16 v[12:15], v[158:161], v[214:217], v[12:15]
	v_mfma_f32_16x16x32_bf16 v[8:11], v[166:169], v[214:217], v[8:11]
	s_setprio 0
	s_setprio 1
	v_mfma_f32_16x16x32_bf16 v[52:55], v[170:173], v[186:189], v[52:55]
	v_mfma_f32_16x16x32_bf16 v[48:51], v[178:181], v[186:189], v[48:51]
	v_mfma_f32_16x16x32_bf16 v[36:39], v[170:173], v[194:197], v[36:39]
	v_mfma_f32_16x16x32_bf16 v[32:35], v[178:181], v[194:197], v[32:35]
	v_mfma_f32_16x16x32_bf16 v[20:23], v[170:173], v[202:205], v[20:23]
	v_mfma_f32_16x16x32_bf16 v[16:19], v[178:181], v[202:205], v[16:19]
	v_mfma_f32_16x16x32_bf16 v[4:7], v[170:173], v[210:213], v[4:7]
	v_mfma_f32_16x16x32_bf16 v[0:3], v[178:181], v[210:213], v[0:3]
	v_mfma_f32_16x16x32_bf16 v[52:55], v[174:177], v[190:193], v[52:55]
	v_mfma_f32_16x16x32_bf16 v[48:51], v[182:185], v[190:193], v[48:51]
	v_mfma_f32_16x16x32_bf16 v[36:39], v[174:177], v[198:201], v[36:39]
	v_mfma_f32_16x16x32_bf16 v[32:35], v[182:185], v[198:201], v[32:35]
	v_mfma_f32_16x16x32_bf16 v[20:23], v[174:177], v[206:209], v[20:23]
	v_mfma_f32_16x16x32_bf16 v[16:19], v[182:185], v[206:209], v[16:19]
	v_mfma_f32_16x16x32_bf16 v[4:7], v[174:177], v[214:217], v[4:7]
	v_mfma_f32_16x16x32_bf16 v[0:3], v[182:185], v[214:217], v[0:3]
	s_setprio 0
	s_barrier
	s_add_i32 s69, s69, 2
	s_add_u32 s42, s42, 0x100
	s_addc_u32 s43, s43, 0
	s_add_u32 s67, s67, 0x100
	s_addc_u32 s68, s68, 0
	s_cmp_gt_u32 s69, 29
	s_cbranch_scc0 .LBB0_1612
	s_nop 0
	s_and_b64 vcc, exec, s[16:17]
	s_cbranch_vccz .LBB0_1615
	s_barrier

; #define PG8_STAGE(bufoff, gbase, voff) do { _Pragma("unroll") for (int _i = 0; _i < 2; ++_i) \
;         __builtin_amdgcn_global_load_lds((const unsigned*)((const char*)(gbase) + (voff)[_i]), (PG8_LAS unsigned*)(lds + (bufoff) + ldsw + _i * 8192), 16, 0, 0); } while (0)
; #define PG8_LDA(dst, b, h) do { _Pragma("unroll") for (int m = 0; m < 4; ++m) _Pragma("unroll") for (int k = 0; k < 2; ++k) dst[m][k] = *(const PG8_LAS bf16x8*)(lds + PG8_SA(b, h) + aoff + m * 2048 + k * 1024); } while (0)
; #define PG8_LDB(dst, b, h) do { _Pragma("unroll") for (int n = 0; n < 2; ++n) _Pragma("unroll") for (int k = 0; k < 2; ++k) dst[n][k] = *(const PG8_LAS bf16x8*)(lds + PG8_SB(b, h) + boff + n * 2048 + k * 1024); } while (0)
; #define PG8_WAIT_V(n) asm volatile("s_waitcnt vmcnt(" #n ")" ::: "memory")
; #define PG8_WAIT_L(n) asm volatile("s_waitcnt lgkmcnt(" #n ")" ::: "memory")
; #define PG8_BAR __builtin_amdgcn_s_barrier()
; #define PG8_SCHED __builtin_amdgcn_sched_barrier(0)
; template <class Epi, class Sched, bool ALIGN_EPI = false, bool SP2 = false>
; __device__ __forceinline__ void gemm_phase(PG8_LAS unsigned char* lds, const Gemm g, const Sched& S, const Epi& E) {
;     ...
;         const bool has_next = S.next(ui + 1, nxt);
;         const char* nA = has_next ? (const char*)g.A + (size_t)nxt.pm * tstep : cA; const char* nB = has_next ? (const char*)g.Bt + (size_t)nxt.pn * tstep : cB;
;         for (int t = 0; t < nt; t += 2) {
;             const bool last = (t == nt - 2);
;             const char* a1 = cA + (size_t)(t + 1) * kstep;
;             const char* a2 = last ? nA : cA + (size_t)(t + 2) * kstep; const char* b2 = last ? nB : cB + (size_t)(t + 2) * kstep;
;             const char* a3 = a2 + kstep; const char* b3 = b2 + kstep;
;             if (last && has_next) S.a_ready(nxt);
;             if constexpr (SP2) {
;             PG8_LDB(B0, 0, 0); PG8_LDB(B1, 0, 1); PG8_SCHED; PG8_LDA(At, 0, 0); PG8_STAGE(PG8_SA(1, 1), a1 + hstep, voffA);
;             PG8_WAIT_V(8); PG8_WAIT_L(0); PG8_BAR; PG8_MMA(0, 0, At, B0); PG8_MMA(0, 1, At, B1); PG8_BAR; PG8_SCHED;
;             PG8_LDA(At, 0, 1); PG8_STAGE(PG8_SB(0, 0), b2, voffB); PG8_STAGE(PG8_SB(0, 1), b2 + hstep, voffB); PG8_STAGE(PG8_SA(0, 0), a2, voffA);
;             PG8_WAIT_V(8); PG8_WAIT_L(0); PG8_BAR; PG8_MMA(1, 0, At, B0); PG8_MMA(1, 1, At, B1); PG8_BAR; PG8_SCHED;
.LBB0_1923:
	s_add_u32 s22, s22, 0x160080
	s_addc_u32 s23, s23, 0
	s_add_u32 s61, s36, 0x100
	s_addc_u32 s62, s37, 0
	s_mov_b32 s63, -2
	s_waitcnt lgkmcnt(0)
	s_nop 0
	ds_read_b128 v[146:149], v153
	ds_read_b128 v[158:161], v153 offset:1024
	ds_read_b128 v[162:165], v153 offset:2048
	ds_read_b128 v[166:169], v153 offset:3072
	ds_read_b128 v[170:173], v154
	ds_read_b128 v[174:177], v154 offset:1024
	ds_read_b128 v[178:181], v154 offset:2048
	ds_read_b128 v[182:185], v154 offset:3072
	s_add_u32 s36, s22, 0xffea0080
	s_addc_u32 s37, s23, -1
	s_cmpk_eq_i32 s63, 0x54
	s_cselect_b32 s39, s5, s37
	s_cselect_b32 s38, s4, s36
	s_cselect_b32 s37, s21, s62
	s_cselect_b32 s36, s20, s61
	v_lshl_add_u64 v[218:219], s[22:23], 0, v[136:137]
	s_add_i32 m0, s43, 0xc000
	ds_read_b128 v[186:189], v155
	ds_read_b128 v[190:193], v155 offset:1024
	ds_read_b128 v[194:197], v155 offset:2048
	ds_read_b128 v[198:201], v155 offset:3072
	ds_read_b128 v[202:205], v155 offset:4096
	ds_read_b128 v[206:209], v155 offset:5120
	ds_read_b128 v[210:213], v155 offset:6144
	ds_read_b128 v[214:217], v155 offset:7168
	global_load_lds_dwordx4 v[218:219], off
	v_lshl_add_u64 v[218:219], s[22:23], 0, v[138:139]
	s_add_i32 m0, s43, 0xe000
	s_nop 0
	global_load_lds_dwordx4 v[218:219], off
	s_waitcnt vmcnt(8)
	s_waitcnt lgkmcnt(0)
	s_barrier
	s_setprio 1
	v_mfma_f32_16x16x32_bf16 v[124:127], v[146:149], v[186:189], 0
	v_mfma_f32_16x16x32_bf16 v[120:123], v[162:165], v[186:189], 0
	v_mfma_f32_16x16x32_bf16 v[108:111], v[146:149], v[194:197], 0
	v_mfma_f32_16x16x32_bf16 v[104:107], v[162:165], v[194:197], 0
	v_mfma_f32_16x16x32_bf16 v[92:95], v[146:149], v[202:205], 0
	v_mfma_f32_16x16x32_bf16 v[88:91], v[162:165], v[202:205], 0
	v_mfma_f32_16x16x32_bf16 v[76:79], v[146:149], v[210:213], 0
	v_mfma_f32_16x16x32_bf16 v[72:75], v[162:165], v[210:213], 0
	v_mfma_f32_16x16x32_bf16 v[124:127], v[158:161], v[190:193], v[124:127]
	v_mfma_f32_16x16x32_bf16 v[120:123], v[166:169], v[190:193], v[120:123]
	v_mfma_f32_16x16x32_bf16 v[108:111], v[158:161], v[198:201], v[108:111]
	v_mfma_f32_16x16x32_bf16 v[104:107], v[166:169], v[198:201], v[104:107]
	v_mfma_f32_16x16x32_bf16 v[92:95], v[158:161], v[206:209], v[92:95]
	v_mfma_f32_16x16x32_bf16 v[88:91], v[166:169], v[206:209], v[88:91]
	v_mfma_f32_16x16x32_bf16 v[76:79], v[158:161], v[214:217], v[76:79]
	v_mfma_f32_16x16x32_bf16 v[72:75], v[166:169], v[214:217], v[72:75]
	s_setprio 0
	s_setprio 1
	v_mfma_f32_16x16x32_bf16 v[116:119], v[170:173], v[186:189], 0
	v_mfma_f32_16x16x32_bf16 v[112:115], v[178:181], v[186:189], 0
	v_mfma_f32_16x16x32_bf16 v[100:103], v[170:173], v[194:197], 0
	v_mfma_f32_16x16x32_bf16 v[96:99], v[178:181], v[194:197], 0
	v_mfma_f32_16x16x32_bf16 v[84:87], v[170:173], v[202:205], 0
	v_mfma_f32_16x16x32_bf16 v[80:83], v[178:181], v[202:205], 0
	v_mfma_f32_16x16x32_bf16 v[68:71], v[170:173], v[210:213], 0
	v_mfma_f32_16x16x32_bf16 v[64:67], v[178:181], v[210:213], 0
	v_mfma_f32_16x16x32_bf16 v[116:119], v[174:177], v[190:193], v[116:119]
	v_mfma_f32_16x16x32_bf16 v[112:115], v[182:185], v[190:193], v[112:115]
	v_mfma_f32_16x16x32_bf16 v[100:103], v[174:177], v[198:201], v[100:103]
	v_mfma_f32_16x16x32_bf16 v[96:99], v[182:185], v[198:201], v[96:99]
	v_mfma_f32_16x16x32_bf16 v[84:87], v[174:177], v[206:209], v[84:87]
	v_mfma_f32_16x16x32_bf16 v[80:83], v[182:185], v[206:209], v[80:83]
	v_mfma_f32_16x16x32_bf16 v[68:71], v[174:177], v[214:217], v[68:71]
	v_mfma_f32_16x16x32_bf16 v[64:67], v[182:185], v[214:217], v[64:67]
	s_setprio 0
	s_barrier
	s_add_i32 s64, s55, s42
	v_lshl_add_u64 v[218:219], s[36:37], 0, v[130:131]
	s_mov_b32 m0, s64
	ds_read_b128 v[186:189], v155 offset:16384
	ds_read_b128 v[190:193], v155 offset:17408
	ds_read_b128 v[194:197], v155 offset:18432
	ds_read_b128 v[198:201], v155 offset:19456
	ds_read_b128 v[202:205], v155 offset:20480
	ds_read_b128 v[206:209], v155 offset:21504
	ds_read_b128 v[210:213], v155 offset:22528
	ds_read_b128 v[214:217], v155 offset:23552
	global_load_lds_dwordx4 v[218:219], off
	s_add_i32 m0, s64, 0x2000
	s_add_u32 s64, s36, 0x160000
	v_lshl_add_u64 v[220:221], s[36:37], 0, v[134:135]
	s_addc_u32 s65, s37, 0
	s_add_i32 s66, s56, s42
	global_load_lds_dwordx4 v[220:221], off
	v_lshl_add_u64 v[222:223], s[64:65], 0, v[130:131]
	s_mov_b32 m0, s66
	v_lshl_add_u64 v[224:225], s[38:39], 0, v[132:133]
	global_load_lds_dwordx4 v[222:223], off
	v_lshl_add_u64 v[222:223], s[64:65], 0, v[134:135]
	s_add_i32 m0, s66, 0x2000
	s_nop 0
	global_load_lds_dwordx4 v[222:223], off
	v_lshl_add_u64 v[222:223], s[38:39], 0, v[128:129]
	s_mov_b32 m0, s43
	s_nop 0
	global_load_lds_dwordx4 v[222:223], off
	s_mov_b32 m0, s44
	s_nop 0
	global_load_lds_dwordx4 v[224:225], off
	s_waitcnt vmcnt(8)
	s_waitcnt lgkmcnt(0)
	s_barrier
; #define PG8_STAGE(bufoff, gbase, voff) do { _Pragma("unroll") for (int _i = 0; _i < 2; ++_i) \
;         __builtin_amdgcn_global_load_lds((const unsigned*)((const char*)(gbase) + (voff)[_i]), (PG8_LAS unsigned*)(lds + (bufoff) + ldsw + _i * 8192), 16, 0, 0); } while (0)
; #define PG8_LDA(dst, b, h) do { _Pragma("unroll") for (int m = 0; m < 4; ++m) _Pragma("unroll") for (int k = 0; k < 2; ++k) dst[m][k] = *(const PG8_LAS bf16x8*)(lds + PG8_SA(b, h) + aoff + m * 2048 + k * 1024); } while (0)
; #define PG8_LDB(dst, b, h) do { _Pragma("unroll") for (int n = 0; n < 2; ++n) _Pragma("unroll") for (int k = 0; k < 2; ++k) dst[n][k] = *(const PG8_LAS bf16x8*)(lds + PG8_SB(b, h) + boff + n * 2048 + k * 1024); } while (0)
; #define PG8_MMA(ai, bj, At, Bt) do { __builtin_amdgcn_s_setprio(1); _Pragma("unroll") for (int m = 0; m < 4; ++m) _Pragma("unroll") for (int n = 0; n < 2; ++n) _Pragma("unroll") for (int k = 0; k < 2; ++k) \
;         acc[ai][bj][m][n] = __builtin_amdgcn_mfma_f32_16x16x32_bf16(Bt[n][k], At[m][k], acc[ai][bj][m][n], 0, 0, 0); __builtin_amdgcn_s_setprio(0); } while (0)
; #define PG8_WAIT_V(n) asm volatile("s_waitcnt vmcnt(" #n ")" ::: "memory")
; #define PG8_WAIT_L(n) asm volatile("s_waitcnt lgkmcnt(" #n ")" ::: "memory")
; #define PG8_BAR __builtin_amdgcn_s_barrier()
; #define PG8_SCHED __builtin_amdgcn_sched_barrier(0)
; template <class Epi, class Sched, bool ALIGN_EPI = false, bool SP2 = false>
; __device__ __forceinline__ void gemm_phase(PG8_LAS unsigned char* lds, const Gemm g, const Sched& S, const Epi& E) {
;     ...
;             PG8_WAIT_V(8); PG8_WAIT_L(0); PG8_BAR; PG8_MMA(1, 0, At, B0); PG8_MMA(1, 1, At, B1); PG8_BAR; PG8_SCHED;
;             PG8_LDB(B0, 1, 0); PG8_LDB(B1, 1, 1); PG8_SCHED; PG8_LDA(At, 1, 0); PG8_STAGE(PG8_SA(0, 1), a2 + hstep, voffA);
;             PG8_WAIT_V(8); PG8_WAIT_L(0); PG8_BAR; PG8_MMA(0, 0, At, B0); PG8_MMA(0, 1, At, B1); PG8_BAR; PG8_SCHED;
	s_setprio 1
	v_mfma_f32_16x16x32_bf16 v[60:63], v[146:149], v[186:189], 0
	v_mfma_f32_16x16x32_bf16 v[56:59], v[162:165], v[186:189], 0
	v_mfma_f32_16x16x32_bf16 v[44:47], v[146:149], v[194:197], 0
	v_mfma_f32_16x16x32_bf16 v[40:43], v[162:165], v[194:197], 0
	v_mfma_f32_16x16x32_bf16 v[28:31], v[146:149], v[202:205], 0
	v_mfma_f32_16x16x32_bf16 v[24:27], v[162:165], v[202:205], 0
	v_mfma_f32_16x16x32_bf16 v[12:15], v[146:149], v[210:213], 0
	v_mfma_f32_16x16x32_bf16 v[8:11], v[162:165], v[210:213], 0
	v_mfma_f32_16x16x32_bf16 v[60:63], v[158:161], v[190:193], v[60:63]
	v_mfma_f32_16x16x32_bf16 v[56:59], v[166:169], v[190:193], v[56:59]
	v_mfma_f32_16x16x32_bf16 v[44:47], v[158:161], v[198:201], v[44:47]
	v_mfma_f32_16x16x32_bf16 v[40:43], v[166:169], v[198:201], v[40:43]
	v_mfma_f32_16x16x32_bf16 v[28:31], v[158:161], v[206:209], v[28:31]
	v_mfma_f32_16x16x32_bf16 v[24:27], v[166:169], v[206:209], v[24:27]
	v_mfma_f32_16x16x32_bf16 v[12:15], v[158:161], v[214:217], v[12:15]
	v_mfma_f32_16x16x32_bf16 v[8:11], v[166:169], v[214:217], v[8:11]
	s_setprio 0
	s_setprio 1
	v_mfma_f32_16x16x32_bf16 v[52:55], v[170:173], v[186:189], 0
	v_mfma_f32_16x16x32_bf16 v[48:51], v[178:181], v[186:189], 0
	v_mfma_f32_16x16x32_bf16 v[36:39], v[170:173], v[194:197], 0
	v_mfma_f32_16x16x32_bf16 v[32:35], v[178:181], v[194:197], 0
	v_mfma_f32_16x16x32_bf16 v[20:23], v[170:173], v[202:205], 0
	v_mfma_f32_16x16x32_bf16 v[16:19], v[178:181], v[202:205], 0
	v_mfma_f32_16x16x32_bf16 v[4:7], v[170:173], v[210:213], 0
	v_mfma_f32_16x16x32_bf16 v[0:3], v[178:181], v[210:213], 0
	v_mfma_f32_16x16x32_bf16 v[52:55], v[174:177], v[190:193], v[52:55]
	v_mfma_f32_16x16x32_bf16 v[48:51], v[182:185], v[190:193], v[48:51]
	v_mfma_f32_16x16x32_bf16 v[36:39], v[174:177], v[198:201], v[36:39]
	v_mfma_f32_16x16x32_bf16 v[32:35], v[182:185], v[198:201], v[32:35]
	v_mfma_f32_16x16x32_bf16 v[20:23], v[174:177], v[206:209], v[20:23]
	v_mfma_f32_16x16x32_bf16 v[16:19], v[182:185], v[206:209], v[16:19]
	v_mfma_f32_16x16x32_bf16 v[4:7], v[174:177], v[214:217], v[4:7]
	v_mfma_f32_16x16x32_bf16 v[0:3], v[182:185], v[214:217], v[0:3]
	s_setprio 0
	s_barrier
	s_add_i32 s64, 0, 0x18000
	v_add_u32_e32 v157, s64, v152
	s_add_i32 s65, 0, 0x1c000
	ds_read_b128 v[146:149], v157
	ds_read_b128 v[158:161], v157 offset:1024
	ds_read_b128 v[162:165], v157 offset:2048
	ds_read_b128 v[166:169], v157 offset:3072
	v_add_u32_e32 v157, s65, v152
	ds_read_b128 v[170:173], v157
	ds_read_b128 v[174:177], v157 offset:1024
	ds_read_b128 v[178:181], v157 offset:2048
	ds_read_b128 v[182:185], v157 offset:3072
	s_add_u32 s38, s38, 0x160000
	s_addc_u32 s39, s39, 0
	s_mov_b32 m0, s45
	v_lshl_add_u64 v[226:227], s[38:39], 0, v[128:129]
	ds_read_b128 v[186:189], v155 offset:32768
	ds_read_b128 v[190:193], v155 offset:33792
	ds_read_b128 v[194:197], v155 offset:34816
	ds_read_b128 v[198:201], v155 offset:35840
	ds_read_b128 v[202:205], v155 offset:36864
	ds_read_b128 v[206:209], v155 offset:37888
	ds_read_b128 v[210:213], v155 offset:38912
	ds_read_b128 v[214:217], v155 offset:39936
	global_load_lds_dwordx4 v[226:227], off
	v_lshl_add_u64 v[226:227], s[38:39], 0, v[132:133]
	s_mov_b32 m0, s46
	s_nop 0
	global_load_lds_dwordx4 v[226:227], off
	s_waitcnt vmcnt(8)
	s_waitcnt lgkmcnt(0)
	s_barrier
	s_setprio 1
	v_mfma_f32_16x16x32_bf16 v[124:127], v[146:149], v[186:189], v[124:127]
	v_mfma_f32_16x16x32_bf16 v[120:123], v[162:165], v[186:189], v[120:123]
	v_mfma_f32_16x16x32_bf16 v[108:111], v[146:149], v[194:197], v[108:111]
	v_mfma_f32_16x16x32_bf16 v[104:107], v[162:165], v[194:197], v[104:107]
	v_mfma_f32_16x16x32_bf16 v[92:95], v[146:149], v[202:205], v[92:95]
	v_mfma_f32_16x16x32_bf16 v[88:91], v[162:165], v[202:205], v[88:91]
	v_mfma_f32_16x16x32_bf16 v[76:79], v[146:149], v[210:213], v[76:79]
	v_mfma_f32_16x16x32_bf16 v[72:75], v[162:165], v[210:213], v[72:75]
	v_mfma_f32_16x16x32_bf16 v[124:127], v[158:161], v[190:193], v[124:127]
	v_mfma_f32_16x16x32_bf16 v[120:123], v[166:169], v[190:193], v[120:123]
	v_mfma_f32_16x16x32_bf16 v[108:111], v[158:161], v[198:201], v[108:111]
	v_mfma_f32_16x16x32_bf16 v[104:107], v[166:169], v[198:201], v[104:107]
	v_mfma_f32_16x16x32_bf16 v[92:95], v[158:161], v[206:209], v[92:95]
	v_mfma_f32_16x16x32_bf16 v[88:91], v[166:169], v[206:209], v[88:91]
	v_mfma_f32_16x16x32_bf16 v[76:79], v[158:161], v[214:217], v[76:79]
	v_mfma_f32_16x16x32_bf16 v[72:75], v[166:169], v[214:217], v[72:75]
	s_setprio 0
	s_setprio 1
	v_mfma_f32_16x16x32_bf16 v[116:119], v[170:173], v[186:189], v[116:119]
	v_mfma_f32_16x16x32_bf16 v[112:115], v[178:181], v[186:189], v[112:115]
	v_mfma_f32_16x16x32_bf16 v[100:103], v[170:173], v[194:197], v[100:103]
	v_mfma_f32_16x16x32_bf16 v[96:99], v[178:181], v[194:197], v[96:99]
	v_mfma_f32_16x16x32_bf16 v[84:87], v[170:173], v[202:205], v[84:87]
	v_mfma_f32_16x16x32_bf16 v[80:83], v[178:181], v[202:205], v[80:83]
	v_mfma_f32_16x16x32_bf16 v[68:71], v[170:173], v[210:213], v[68:71]
	v_mfma_f32_16x16x32_bf16 v[64:67], v[178:181], v[210:213], v[64:67]
	v_mfma_f32_16x16x32_bf16 v[116:119], v[174:177], v[190:193], v[116:119]
	v_mfma_f32_16x16x32_bf16 v[112:115], v[182:185], v[190:193], v[112:115]
	v_mfma_f32_16x16x32_bf16 v[100:103], v[174:177], v[198:201], v[100:103]
	v_mfma_f32_16x16x32_bf16 v[96:99], v[182:185], v[198:201], v[96:99]
	v_mfma_f32_16x16x32_bf16 v[84:87], v[174:177], v[206:209], v[84:87]
	v_mfma_f32_16x16x32_bf16 v[80:83], v[182:185], v[206:209], v[80:83]
	v_mfma_f32_16x16x32_bf16 v[68:71], v[174:177], v[214:217], v[68:71]
	v_mfma_f32_16x16x32_bf16 v[64:67], v[182:185], v[214:217], v[64:67]
	s_setprio 0
	s_barrier
; #define PG8_STAGE(bufoff, gbase, voff) do { _Pragma("unroll") for (int _i = 0; _i < 2; ++_i) \
;         __builtin_amdgcn_global_load_lds((const unsigned*)((const char*)(gbase) + (voff)[_i]), (PG8_LAS unsigned*)(lds + (bufoff) + ldsw + _i * 8192), 16, 0, 0); } while (0)
; #define PG8_LDA(dst, b, h) do { _Pragma("unroll") for (int m = 0; m < 4; ++m) _Pragma("unroll") for (int k = 0; k < 2; ++k) dst[m][k] = *(const PG8_LAS bf16x8*)(lds + PG8_SA(b, h) + aoff + m * 2048 + k * 1024); } while (0)
; #define PG8_LDB(dst, b, h) do { _Pragma("unroll") for (int n = 0; n < 2; ++n) _Pragma("unroll") for (int k = 0; k < 2; ++k) dst[n][k] = *(const PG8_LAS bf16x8*)(lds + PG8_SB(b, h) + boff + n * 2048 + k * 1024); } while (0)
; #define PG8_MMA(ai, bj, At, Bt) do { __builtin_amdgcn_s_setprio(1); _Pragma("unroll") for (int m = 0; m < 4; ++m) _Pragma("unroll") for (int n = 0; n < 2; ++n) _Pragma("unroll") for (int k = 0; k < 2; ++k) \
;         acc[ai][bj][m][n] = __builtin_amdgcn_mfma_f32_16x16x32_bf16(Bt[n][k], At[m][k], acc[ai][bj][m][n], 0, 0, 0); __builtin_amdgcn_s_setprio(0); } while (0)
; #define PG8_WAIT_V(n) asm volatile("s_waitcnt vmcnt(" #n ")" ::: "memory")
; #define PG8_WAIT_L(n) asm volatile("s_waitcnt lgkmcnt(" #n ")" ::: "memory")
; #define PG8_BAR __builtin_amdgcn_s_barrier()
; #define PG8_SCHED __builtin_amdgcn_sched_barrier(0)
; template <class Epi, class Sched, bool ALIGN_EPI = false, bool SP2 = false>
; __device__ __forceinline__ void gemm_phase(PG8_LAS unsigned char* lds, const Gemm g, const Sched& S, const Epi& E) {
;     ...
;             PG8_LDB(B0, 0, 0); PG8_LDB(B1, 0, 1); PG8_SCHED; PG8_LDA(At, 0, 0); PG8_STAGE(PG8_SA(1, 1), a1 + hstep, voffA);
;             PG8_WAIT_V(8); PG8_WAIT_L(0); PG8_BAR; PG8_MMA(0, 0, At, B0); PG8_MMA(0, 1, At, B1); PG8_BAR; PG8_SCHED;
;     ...
;             PG8_LDA(At, 1, 1); PG8_STAGE(PG8_SB(1, 0), b3, voffB); PG8_STAGE(PG8_SB(1, 1), b3 + hstep, voffB); PG8_STAGE(PG8_SA(1, 0), a3, voffA);
;             PG8_WAIT_V(8); PG8_WAIT_L(0); PG8_BAR; PG8_MMA(1, 0, At, B0); PG8_MMA(1, 1, At, B1); PG8_BAR; PG8_SCHED;
	s_add_i32 s38, s64, s42
	v_lshl_add_u64 v[218:219], v[218:219], 0, s[16:17]
	s_mov_b32 m0, s38
	ds_read_b128 v[186:189], v155 offset:49152
	ds_read_b128 v[190:193], v155 offset:50176
	ds_read_b128 v[194:197], v155 offset:51200
	ds_read_b128 v[198:201], v155 offset:52224
	ds_read_b128 v[202:205], v155 offset:53248
	ds_read_b128 v[206:209], v155 offset:54272
	ds_read_b128 v[210:213], v155 offset:55296
	ds_read_b128 v[214:217], v155 offset:56320
	global_load_lds_dwordx4 v[218:219], off
	s_add_i32 m0, s38, 0x2000
	s_add_u32 s36, s36, 0x160080
	v_lshl_add_u64 v[218:219], v[220:221], 0, s[16:17]
	s_addc_u32 s37, s37, 0
	s_add_i32 s38, s65, s42
	global_load_lds_dwordx4 v[218:219], off
	v_lshl_add_u64 v[218:219], s[36:37], 0, v[130:131]
	s_mov_b32 m0, s38
	s_nop 0
	global_load_lds_dwordx4 v[218:219], off
	v_lshl_add_u64 v[218:219], s[36:37], 0, v[134:135]
	s_add_i32 m0, s38, 0x2000
	s_nop 0
	global_load_lds_dwordx4 v[218:219], off
	v_lshl_add_u64 v[218:219], v[222:223], 0, s[16:17]
	s_mov_b32 m0, s52
	s_nop 0
	global_load_lds_dwordx4 v[218:219], off
	v_lshl_add_u64 v[218:219], v[224:225], 0, s[16:17]
	s_mov_b32 m0, s53
	s_nop 0
	global_load_lds_dwordx4 v[218:219], off
	s_waitcnt vmcnt(8)
	s_waitcnt lgkmcnt(0)
	s_barrier
	s_setprio 1
	v_mfma_f32_16x16x32_bf16 v[60:63], v[146:149], v[186:189], v[60:63]
	v_mfma_f32_16x16x32_bf16 v[56:59], v[162:165], v[186:189], v[56:59]
	v_mfma_f32_16x16x32_bf16 v[44:47], v[146:149], v[194:197], v[44:47]
	v_mfma_f32_16x16x32_bf16 v[40:43], v[162:165], v[194:197], v[40:43]
	v_mfma_f32_16x16x32_bf16 v[28:31], v[146:149], v[202:205], v[28:31]
	v_mfma_f32_16x16x32_bf16 v[24:27], v[162:165], v[202:205], v[24:27]
	v_mfma_f32_16x16x32_bf16 v[12:15], v[146:149], v[210:213], v[12:15]
	v_mfma_f32_16x16x32_bf16 v[8:11], v[162:165], v[210:213], v[8:11]
	v_mfma_f32_16x16x32_bf16 v[60:63], v[158:161], v[190:193], v[60:63]
	v_mfma_f32_16x16x32_bf16 v[56:59], v[166:169], v[190:193], v[56:59]
	v_mfma_f32_16x16x32_bf16 v[44:47], v[158:161], v[198:201], v[44:47]
	v_mfma_f32_16x16x32_bf16 v[40:43], v[166:169], v[198:201], v[40:43]
	v_mfma_f32_16x16x32_bf16 v[28:31], v[158:161], v[206:209], v[28:31]
	v_mfma_f32_16x16x32_bf16 v[24:27], v[166:169], v[206:209], v[24:27]
	v_mfma_f32_16x16x32_bf16 v[12:15], v[158:161], v[214:217], v[12:15]
	v_mfma_f32_16x16x32_bf16 v[8:11], v[166:169], v[214:217], v[8:11]
	s_setprio 0
	s_setprio 1
	v_mfma_f32_16x16x32_bf16 v[52:55], v[170:173], v[186:189], v[52:55]
	v_mfma_f32_16x16x32_bf16 v[48:51], v[178:181], v[186:189], v[48:51]
	v_mfma_f32_16x16x32_bf16 v[36:39], v[170:173], v[194:197], v[36:39]
	v_mfma_f32_16x16x32_bf16 v[32:35], v[178:181], v[194:197], v[32:35]
	v_mfma_f32_16x16x32_bf16 v[20:23], v[170:173], v[202:205], v[20:23]
	v_mfma_f32_16x16x32_bf16 v[16:19], v[178:181], v[202:205], v[16:19]
	v_mfma_f32_16x16x32_bf16 v[4:7], v[170:173], v[210:213], v[4:7]
	v_mfma_f32_16x16x32_bf16 v[0:3], v[178:181], v[210:213], v[0:3]
	v_mfma_f32_16x16x32_bf16 v[52:55], v[174:177], v[190:193], v[52:55]
	v_mfma_f32_16x16x32_bf16 v[48:51], v[182:185], v[190:193], v[48:51]
	v_mfma_f32_16x16x32_bf16 v[36:39], v[174:177], v[198:201], v[36:39]
	v_mfma_f32_16x16x32_bf16 v[32:35], v[182:185], v[198:201], v[32:35]
	v_mfma_f32_16x16x32_bf16 v[20:23], v[174:177], v[206:209], v[20:23]
	v_mfma_f32_16x16x32_bf16 v[16:19], v[182:185], v[206:209], v[16:19]
	v_mfma_f32_16x16x32_bf16 v[4:7], v[174:177], v[214:217], v[4:7]
	v_mfma_f32_16x16x32_bf16 v[0:3], v[182:185], v[214:217], v[0:3]
	s_setprio 0
	s_barrier
	s_add_i32 s63, s63, 2
	s_add_u32 s22, s22, 0x100
	s_addc_u32 s23, s23, 0
	s_add_u32 s61, s61, 0x100
	s_addc_u32 s62, s62, 0
	s_cmpk_gt_u32 s63, 0x55
.LBB0_1924:
	ds_read_b128 v[146:149], v153
	ds_read_b128 v[158:161], v153 offset:1024
	ds_read_b128 v[162:165], v153 offset:2048
	ds_read_b128 v[166:169], v153 offset:3072
	ds_read_b128 v[170:173], v154
	ds_read_b128 v[174:177], v154 offset:1024
	ds_read_b128 v[178:181], v154 offset:2048
	ds_read_b128 v[182:185], v154 offset:3072
	s_add_u32 s36, s22, 0xffea0080
	s_addc_u32 s37, s23, -1
	s_cmpk_eq_i32 s63, 0x54
	s_cselect_b32 s39, s5, s37
	s_cselect_b32 s38, s4, s36
	s_cselect_b32 s37, s21, s62
	s_cselect_b32 s36, s20, s61
	v_lshl_add_u64 v[218:219], s[22:23], 0, v[136:137]
	s_add_i32 m0, s43, 0xc000
	ds_read_b128 v[186:189], v155
	ds_read_b128 v[190:193], v155 offset:1024
	ds_read_b128 v[194:197], v155 offset:2048
	ds_read_b128 v[198:201], v155 offset:3072
	ds_read_b128 v[202:205], v155 offset:4096
	ds_read_b128 v[206:209], v155 offset:5120
	ds_read_b128 v[210:213], v155 offset:6144
	ds_read_b128 v[214:217], v155 offset:7168
	global_load_lds_dwordx4 v[218:219], off
	v_lshl_add_u64 v[218:219], s[22:23], 0, v[138:139]
	s_add_i32 m0, s43, 0xe000
	s_nop 0
	global_load_lds_dwordx4 v[218:219], off
	s_waitcnt vmcnt(8)
	s_waitcnt lgkmcnt(0)
	s_barrier
; #define PG8_STAGE(bufoff, gbase, voff) do { _Pragma("unroll") for (int _i = 0; _i < 2; ++_i) \
;         __builtin_amdgcn_global_load_lds((const unsigned*)((const char*)(gbase) + (voff)[_i]), (PG8_LAS unsigned*)(lds + (bufoff) + ldsw + _i * 8192), 16, 0, 0); } while (0)
; #define PG8_LDA(dst, b, h) do { _Pragma("unroll") for (int m = 0; m < 4; ++m) _Pragma("unroll") for (int k = 0; k < 2; ++k) dst[m][k] = *(const PG8_LAS bf16x8*)(lds + PG8_SA(b, h) + aoff + m * 2048 + k * 1024); } while (0)
; #define PG8_MMA(ai, bj, At, Bt) do { __builtin_amdgcn_s_setprio(1); _Pragma("unroll") for (int m = 0; m < 4; ++m) _Pragma("unroll") for (int n = 0; n < 2; ++n) _Pragma("unroll") for (int k = 0; k < 2; ++k) \
;         acc[ai][bj][m][n] = __builtin_amdgcn_mfma_f32_16x16x32_bf16(Bt[n][k], At[m][k], acc[ai][bj][m][n], 0, 0, 0); __builtin_amdgcn_s_setprio(0); } while (0)
; #define PG8_WAIT_V(n) asm volatile("s_waitcnt vmcnt(" #n ")" ::: "memory")
; #define PG8_WAIT_L(n) asm volatile("s_waitcnt lgkmcnt(" #n ")" ::: "memory")
; #define PG8_BAR __builtin_amdgcn_s_barrier()
; #define PG8_SCHED __builtin_amdgcn_sched_barrier(0)
; template <class Epi, class Sched, bool ALIGN_EPI = false, bool SP2 = false>
; __device__ __forceinline__ void gemm_phase(PG8_LAS unsigned char* lds, const Gemm g, const Sched& S, const Epi& E) {
;     ...
;             PG8_WAIT_V(8); PG8_WAIT_L(0); PG8_BAR; PG8_MMA(0, 0, At, B0); PG8_MMA(0, 1, At, B1); PG8_BAR; PG8_SCHED;
;             PG8_LDA(At, 0, 1); PG8_STAGE(PG8_SB(0, 0), b2, voffB); PG8_STAGE(PG8_SB(0, 1), b2 + hstep, voffB); PG8_STAGE(PG8_SA(0, 0), a2, voffA);
;             PG8_WAIT_V(8); PG8_WAIT_L(0); PG8_BAR; PG8_MMA(1, 0, At, B0); PG8_MMA(1, 1, At, B1); PG8_BAR; PG8_SCHED;
	s_setprio 1
	v_mfma_f32_16x16x32_bf16 v[124:127], v[146:149], v[186:189], v[124:127]
	v_mfma_f32_16x16x32_bf16 v[120:123], v[162:165], v[186:189], v[120:123]
	v_mfma_f32_16x16x32_bf16 v[108:111], v[146:149], v[194:197], v[108:111]
	v_mfma_f32_16x16x32_bf16 v[104:107], v[162:165], v[194:197], v[104:107]
	v_mfma_f32_16x16x32_bf16 v[92:95], v[146:149], v[202:205], v[92:95]
	v_mfma_f32_16x16x32_bf16 v[88:91], v[162:165], v[202:205], v[88:91]
	v_mfma_f32_16x16x32_bf16 v[76:79], v[146:149], v[210:213], v[76:79]
	v_mfma_f32_16x16x32_bf16 v[72:75], v[162:165], v[210:213], v[72:75]
	v_mfma_f32_16x16x32_bf16 v[124:127], v[158:161], v[190:193], v[124:127]
	v_mfma_f32_16x16x32_bf16 v[120:123], v[166:169], v[190:193], v[120:123]
	v_mfma_f32_16x16x32_bf16 v[108:111], v[158:161], v[198:201], v[108:111]
	v_mfma_f32_16x16x32_bf16 v[104:107], v[166:169], v[198:201], v[104:107]
	v_mfma_f32_16x16x32_bf16 v[92:95], v[158:161], v[206:209], v[92:95]
	v_mfma_f32_16x16x32_bf16 v[88:91], v[166:169], v[206:209], v[88:91]
	v_mfma_f32_16x16x32_bf16 v[76:79], v[158:161], v[214:217], v[76:79]
	v_mfma_f32_16x16x32_bf16 v[72:75], v[166:169], v[214:217], v[72:75]
	s_setprio 0
	s_setprio 1
	v_mfma_f32_16x16x32_bf16 v[116:119], v[170:173], v[186:189], v[116:119]
	v_mfma_f32_16x16x32_bf16 v[112:115], v[178:181], v[186:189], v[112:115]
	v_mfma_f32_16x16x32_bf16 v[100:103], v[170:173], v[194:197], v[100:103]
	v_mfma_f32_16x16x32_bf16 v[96:99], v[178:181], v[194:197], v[96:99]
	v_mfma_f32_16x16x32_bf16 v[84:87], v[170:173], v[202:205], v[84:87]
	v_mfma_f32_16x16x32_bf16 v[80:83], v[178:181], v[202:205], v[80:83]
	v_mfma_f32_16x16x32_bf16 v[68:71], v[170:173], v[210:213], v[68:71]
	v_mfma_f32_16x16x32_bf16 v[64:67], v[178:181], v[210:213], v[64:67]
	v_mfma_f32_16x16x32_bf16 v[116:119], v[174:177], v[190:193], v[116:119]
	v_mfma_f32_16x16x32_bf16 v[112:115], v[182:185], v[190:193], v[112:115]
	v_mfma_f32_16x16x32_bf16 v[100:103], v[174:177], v[198:201], v[100:103]
	v_mfma_f32_16x16x32_bf16 v[96:99], v[182:185], v[198:201], v[96:99]
	v_mfma_f32_16x16x32_bf16 v[84:87], v[174:177], v[206:209], v[84:87]
	v_mfma_f32_16x16x32_bf16 v[80:83], v[182:185], v[206:209], v[80:83]
	v_mfma_f32_16x16x32_bf16 v[68:71], v[174:177], v[214:217], v[68:71]
	v_mfma_f32_16x16x32_bf16 v[64:67], v[182:185], v[214:217], v[64:67]
	s_setprio 0
	s_barrier
	s_add_i32 s64, s55, s42
	v_lshl_add_u64 v[218:219], s[36:37], 0, v[130:131]
	s_mov_b32 m0, s64
	ds_read_b128 v[186:189], v155 offset:16384
	ds_read_b128 v[190:193], v155 offset:17408
	ds_read_b128 v[194:197], v155 offset:18432
	ds_read_b128 v[198:201], v155 offset:19456
	ds_read_b128 v[202:205], v155 offset:20480
	ds_read_b128 v[206:209], v155 offset:21504
	ds_read_b128 v[210:213], v155 offset:22528
	ds_read_b128 v[214:217], v155 offset:23552
	global_load_lds_dwordx4 v[218:219], off
	s_add_i32 m0, s64, 0x2000
	s_add_u32 s64, s36, 0x160000
	v_lshl_add_u64 v[220:221], s[36:37], 0, v[134:135]
	s_addc_u32 s65, s37, 0
	s_add_i32 s66, s56, s42
	global_load_lds_dwordx4 v[220:221], off
	v_lshl_add_u64 v[222:223], s[64:65], 0, v[130:131]
	s_mov_b32 m0, s66
	v_lshl_add_u64 v[224:225], s[38:39], 0, v[132:133]
	global_load_lds_dwordx4 v[222:223], off
	v_lshl_add_u64 v[222:223], s[64:65], 0, v[134:135]
	s_add_i32 m0, s66, 0x2000
	s_nop 0
	global_load_lds_dwordx4 v[222:223], off
	v_lshl_add_u64 v[222:223], s[38:39], 0, v[128:129]
	s_mov_b32 m0, s43
	s_nop 0
	global_load_lds_dwordx4 v[222:223], off
	s_mov_b32 m0, s44
	s_nop 0
	global_load_lds_dwordx4 v[224:225], off
	s_waitcnt vmcnt(8)
	s_waitcnt lgkmcnt(0)
	s_barrier
	s_setprio 1
	v_mfma_f32_16x16x32_bf16 v[60:63], v[146:149], v[186:189], v[60:63]
	v_mfma_f32_16x16x32_bf16 v[56:59], v[162:165], v[186:189], v[56:59]
	v_mfma_f32_16x16x32_bf16 v[44:47], v[146:149], v[194:197], v[44:47]
	v_mfma_f32_16x16x32_bf16 v[40:43], v[162:165], v[194:197], v[40:43]
	v_mfma_f32_16x16x32_bf16 v[28:31], v[146:149], v[202:205], v[28:31]
	v_mfma_f32_16x16x32_bf16 v[24:27], v[162:165], v[202:205], v[24:27]
	v_mfma_f32_16x16x32_bf16 v[12:15], v[146:149], v[210:213], v[12:15]
	v_mfma_f32_16x16x32_bf16 v[8:11], v[162:165], v[210:213], v[8:11]
	v_mfma_f32_16x16x32_bf16 v[60:63], v[158:161], v[190:193], v[60:63]
	v_mfma_f32_16x16x32_bf16 v[56:59], v[166:169], v[190:193], v[56:59]
	v_mfma_f32_16x16x32_bf16 v[44:47], v[158:161], v[198:201], v[44:47]
	v_mfma_f32_16x16x32_bf16 v[40:43], v[166:169], v[198:201], v[40:43]
	v_mfma_f32_16x16x32_bf16 v[28:31], v[158:161], v[206:209], v[28:31]
	v_mfma_f32_16x16x32_bf16 v[24:27], v[166:169], v[206:209], v[24:27]
	v_mfma_f32_16x16x32_bf16 v[12:15], v[158:161], v[214:217], v[12:15]
	v_mfma_f32_16x16x32_bf16 v[8:11], v[166:169], v[214:217], v[8:11]
	s_setprio 0
	s_setprio 1
	v_mfma_f32_16x16x32_bf16 v[52:55], v[170:173], v[186:189], v[52:55]
	v_mfma_f32_16x16x32_bf16 v[48:51], v[178:181], v[186:189], v[48:51]
	v_mfma_f32_16x16x32_bf16 v[36:39], v[170:173], v[194:197], v[36:39]
	v_mfma_f32_16x16x32_bf16 v[32:35], v[178:181], v[194:197], v[32:35]
	v_mfma_f32_16x16x32_bf16 v[20:23], v[170:173], v[202:205], v[20:23]
	v_mfma_f32_16x16x32_bf16 v[16:19], v[178:181], v[202:205], v[16:19]
	v_mfma_f32_16x16x32_bf16 v[4:7], v[170:173], v[210:213], v[4:7]
	v_mfma_f32_16x16x32_bf16 v[0:3], v[178:181], v[210:213], v[0:3]
	v_mfma_f32_16x16x32_bf16 v[52:55], v[174:177], v[190:193], v[52:55]
	v_mfma_f32_16x16x32_bf16 v[48:51], v[182:185], v[190:193], v[48:51]
	v_mfma_f32_16x16x32_bf16 v[36:39], v[174:177], v[198:201], v[36:39]
	v_mfma_f32_16x16x32_bf16 v[32:35], v[182:185], v[198:201], v[32:35]
	v_mfma_f32_16x16x32_bf16 v[20:23], v[174:177], v[206:209], v[20:23]
	v_mfma_f32_16x16x32_bf16 v[16:19], v[182:185], v[206:209], v[16:19]
	v_mfma_f32_16x16x32_bf16 v[4:7], v[174:177], v[214:217], v[4:7]
	v_mfma_f32_16x16x32_bf16 v[0:3], v[182:185], v[214:217], v[0:3]
	s_setprio 0
	s_barrier
; #define PG8_STAGE(bufoff, gbase, voff) do { _Pragma("unroll") for (int _i = 0; _i < 2; ++_i) \
;         __builtin_amdgcn_global_load_lds((const unsigned*)((const char*)(gbase) + (voff)[_i]), (PG8_LAS unsigned*)(lds + (bufoff) + ldsw + _i * 8192), 16, 0, 0); } while (0)
; #define PG8_LDA(dst, b, h) do { _Pragma("unroll") for (int m = 0; m < 4; ++m) _Pragma("unroll") for (int k = 0; k < 2; ++k) dst[m][k] = *(const PG8_LAS bf16x8*)(lds + PG8_SA(b, h) + aoff + m * 2048 + k * 1024); } while (0)
; #define PG8_LDB(dst, b, h) do { _Pragma("unroll") for (int n = 0; n < 2; ++n) _Pragma("unroll") for (int k = 0; k < 2; ++k) dst[n][k] = *(const PG8_LAS bf16x8*)(lds + PG8_SB(b, h) + boff + n * 2048 + k * 1024); } while (0)
; #define PG8_MMA(ai, bj, At, Bt) do { __builtin_amdgcn_s_setprio(1); _Pragma("unroll") for (int m = 0; m < 4; ++m) _Pragma("unroll") for (int n = 0; n < 2; ++n) _Pragma("unroll") for (int k = 0; k < 2; ++k) \
;         acc[ai][bj][m][n] = __builtin_amdgcn_mfma_f32_16x16x32_bf16(Bt[n][k], At[m][k], acc[ai][bj][m][n], 0, 0, 0); __builtin_amdgcn_s_setprio(0); } while (0)
; #define PG8_WAIT_V(n) asm volatile("s_waitcnt vmcnt(" #n ")" ::: "memory")
; #define PG8_WAIT_L(n) asm volatile("s_waitcnt lgkmcnt(" #n ")" ::: "memory")
; #define PG8_BAR __builtin_amdgcn_s_barrier()
; #define PG8_SCHED __builtin_amdgcn_sched_barrier(0)
; template <class Epi, class Sched, bool ALIGN_EPI = false, bool SP2 = false>
; __device__ __forceinline__ void gemm_phase(PG8_LAS unsigned char* lds, const Gemm g, const Sched& S, const Epi& E) {
;     ...
;             PG8_LDB(B0, 1, 0); PG8_LDB(B1, 1, 1); PG8_SCHED; PG8_LDA(At, 1, 0); PG8_STAGE(PG8_SA(0, 1), a2 + hstep, voffA);
;             PG8_WAIT_V(8); PG8_WAIT_L(0); PG8_BAR; PG8_MMA(0, 0, At, B0); PG8_MMA(0, 1, At, B1); PG8_BAR; PG8_SCHED;
	s_add_i32 s64, 0, 0x18000
	v_add_u32_e32 v157, s64, v152
	s_add_i32 s65, 0, 0x1c000
	ds_read_b128 v[146:149], v157
	ds_read_b128 v[158:161], v157 offset:1024
	ds_read_b128 v[162:165], v157 offset:2048
	ds_read_b128 v[166:169], v157 offset:3072
	v_add_u32_e32 v157, s65, v152
	ds_read_b128 v[170:173], v157
	ds_read_b128 v[174:177], v157 offset:1024
	ds_read_b128 v[178:181], v157 offset:2048
	ds_read_b128 v[182:185], v157 offset:3072
	s_add_u32 s38, s38, 0x160000
	s_addc_u32 s39, s39, 0
	s_mov_b32 m0, s45
	v_lshl_add_u64 v[226:227], s[38:39], 0, v[128:129]
	ds_read_b128 v[186:189], v155 offset:32768
	ds_read_b128 v[190:193], v155 offset:33792
	ds_read_b128 v[194:197], v155 offset:34816
	ds_read_b128 v[198:201], v155 offset:35840
	ds_read_b128 v[202:205], v155 offset:36864
	ds_read_b128 v[206:209], v155 offset:37888
	ds_read_b128 v[210:213], v155 offset:38912
	ds_read_b128 v[214:217], v155 offset:39936
	global_load_lds_dwordx4 v[226:227], off
	v_lshl_add_u64 v[226:227], s[38:39], 0, v[132:133]
	s_mov_b32 m0, s46
	s_nop 0
	global_load_lds_dwordx4 v[226:227], off
	s_waitcnt vmcnt(8)
	s_waitcnt lgkmcnt(0)
	s_barrier
	s_setprio 1
	v_mfma_f32_16x16x32_bf16 v[124:127], v[146:149], v[186:189], v[124:127]
	v_mfma_f32_16x16x32_bf16 v[120:123], v[162:165], v[186:189], v[120:123]
	v_mfma_f32_16x16x32_bf16 v[108:111], v[146:149], v[194:197], v[108:111]
	v_mfma_f32_16x16x32_bf16 v[104:107], v[162:165], v[194:197], v[104:107]
	v_mfma_f32_16x16x32_bf16 v[92:95], v[146:149], v[202:205], v[92:95]
	v_mfma_f32_16x16x32_bf16 v[88:91], v[162:165], v[202:205], v[88:91]
	v_mfma_f32_16x16x32_bf16 v[76:79], v[146:149], v[210:213], v[76:79]
	v_mfma_f32_16x16x32_bf16 v[72:75], v[162:165], v[210:213], v[72:75]
	v_mfma_f32_16x16x32_bf16 v[124:127], v[158:161], v[190:193], v[124:127]
	v_mfma_f32_16x16x32_bf16 v[120:123], v[166:169], v[190:193], v[120:123]
	v_mfma_f32_16x16x32_bf16 v[108:111], v[158:161], v[198:201], v[108:111]
	v_mfma_f32_16x16x32_bf16 v[104:107], v[166:169], v[198:201], v[104:107]
	v_mfma_f32_16x16x32_bf16 v[92:95], v[158:161], v[206:209], v[92:95]
	v_mfma_f32_16x16x32_bf16 v[88:91], v[166:169], v[206:209], v[88:91]
	v_mfma_f32_16x16x32_bf16 v[76:79], v[158:161], v[214:217], v[76:79]
	v_mfma_f32_16x16x32_bf16 v[72:75], v[166:169], v[214:217], v[72:75]
	s_setprio 0
	s_setprio 1
	v_mfma_f32_16x16x32_bf16 v[116:119], v[170:173], v[186:189], v[116:119]
	v_mfma_f32_16x16x32_bf16 v[112:115], v[178:181], v[186:189], v[112:115]
	v_mfma_f32_16x16x32_bf16 v[100:103], v[170:173], v[194:197], v[100:103]
	v_mfma_f32_16x16x32_bf16 v[96:99], v[178:181], v[194:197], v[96:99]
	v_mfma_f32_16x16x32_bf16 v[84:87], v[170:173], v[202:205], v[84:87]
	v_mfma_f32_16x16x32_bf16 v[80:83], v[178:181], v[202:205], v[80:83]
	v_mfma_f32_16x16x32_bf16 v[68:71], v[170:173], v[210:213], v[68:71]
	v_mfma_f32_16x16x32_bf16 v[64:67], v[178:181], v[210:213], v[64:67]
	v_mfma_f32_16x16x32_bf16 v[116:119], v[174:177], v[190:193], v[116:119]
	v_mfma_f32_16x16x32_bf16 v[112:115], v[182:185], v[190:193], v[112:115]
	v_mfma_f32_16x16x32_bf16 v[100:103], v[174:177], v[198:201], v[100:103]
	v_mfma_f32_16x16x32_bf16 v[96:99], v[182:185], v[198:201], v[96:99]
	v_mfma_f32_16x16x32_bf16 v[84:87], v[174:177], v[206:209], v[84:87]
	v_mfma_f32_16x16x32_bf16 v[80:83], v[182:185], v[206:209], v[80:83]
	v_mfma_f32_16x16x32_bf16 v[68:71], v[174:177], v[214:217], v[68:71]
	v_mfma_f32_16x16x32_bf16 v[64:67], v[182:185], v[214:217], v[64:67]
	s_setprio 0
	s_barrier
; #define PG8_STAGE(bufoff, gbase, voff) do { _Pragma("unroll") for (int _i = 0; _i < 2; ++_i) \
;         __builtin_amdgcn_global_load_lds((const unsigned*)((const char*)(gbase) + (voff)[_i]), (PG8_LAS unsigned*)(lds + (bufoff) + ldsw + _i * 8192), 16, 0, 0); } while (0)
; #define PG8_LDA(dst, b, h) do { _Pragma("unroll") for (int m = 0; m < 4; ++m) _Pragma("unroll") for (int k = 0; k < 2; ++k) dst[m][k] = *(const PG8_LAS bf16x8*)(lds + PG8_SA(b, h) + aoff + m * 2048 + k * 1024); } while (0)
; #define PG8_MMA(ai, bj, At, Bt) do { __builtin_amdgcn_s_setprio(1); _Pragma("unroll") for (int m = 0; m < 4; ++m) _Pragma("unroll") for (int n = 0; n < 2; ++n) _Pragma("unroll") for (int k = 0; k < 2; ++k) \
;         acc[ai][bj][m][n] = __builtin_amdgcn_mfma_f32_16x16x32_bf16(Bt[n][k], At[m][k], acc[ai][bj][m][n], 0, 0, 0); __builtin_amdgcn_s_setprio(0); } while (0)
; #define PG8_WAIT_V(n) asm volatile("s_waitcnt vmcnt(" #n ")" ::: "memory")
; #define PG8_WAIT_L(n) asm volatile("s_waitcnt lgkmcnt(" #n ")" ::: "memory")
; #define PG8_BAR __builtin_amdgcn_s_barrier()
; #define PG8_SCHED __builtin_amdgcn_sched_barrier(0)
; template <class Epi, class Sched, bool ALIGN_EPI = false, bool SP2 = false>
; __device__ __forceinline__ void gemm_phase(PG8_LAS unsigned char* lds, const Gemm g, const Sched& S, const Epi& E) {
;     ...
;             PG8_LDA(At, 1, 1); PG8_STAGE(PG8_SB(1, 0), b3, voffB); PG8_STAGE(PG8_SB(1, 1), b3 + hstep, voffB); PG8_STAGE(PG8_SA(1, 0), a3, voffA);
;             PG8_WAIT_V(8); PG8_WAIT_L(0); PG8_BAR; PG8_MMA(1, 0, At, B0); PG8_MMA(1, 1, At, B1); PG8_BAR; PG8_SCHED;
;     ...
;         if constexpr (ALIGN_EPI) { if (wr == 0) PG8_BAR; }
	s_add_i32 s38, s64, s42
	v_lshl_add_u64 v[218:219], v[218:219], 0, s[16:17]
	s_mov_b32 m0, s38
	ds_read_b128 v[186:189], v155 offset:49152
	ds_read_b128 v[190:193], v155 offset:50176
	ds_read_b128 v[194:197], v155 offset:51200
	ds_read_b128 v[198:201], v155 offset:52224
	ds_read_b128 v[202:205], v155 offset:53248
	ds_read_b128 v[206:209], v155 offset:54272
	ds_read_b128 v[210:213], v155 offset:55296
	ds_read_b128 v[214:217], v155 offset:56320
	global_load_lds_dwordx4 v[218:219], off
	s_add_i32 m0, s38, 0x2000
	s_add_u32 s36, s36, 0x160080
	v_lshl_add_u64 v[218:219], v[220:221], 0, s[16:17]
	s_addc_u32 s37, s37, 0
	s_add_i32 s38, s65, s42
	global_load_lds_dwordx4 v[218:219], off
	v_lshl_add_u64 v[218:219], s[36:37], 0, v[130:131]
	s_mov_b32 m0, s38
	s_nop 0
	global_load_lds_dwordx4 v[218:219], off
	v_lshl_add_u64 v[218:219], s[36:37], 0, v[134:135]
	s_add_i32 m0, s38, 0x2000
	s_nop 0
	global_load_lds_dwordx4 v[218:219], off
	v_lshl_add_u64 v[218:219], v[222:223], 0, s[16:17]
	s_mov_b32 m0, s52
	s_nop 0
	global_load_lds_dwordx4 v[218:219], off
	v_lshl_add_u64 v[218:219], v[224:225], 0, s[16:17]
	s_mov_b32 m0, s53
	s_nop 0
	global_load_lds_dwordx4 v[218:219], off
	s_waitcnt vmcnt(8)
	s_waitcnt lgkmcnt(0)
	s_barrier
	s_setprio 1
	v_mfma_f32_16x16x32_bf16 v[60:63], v[146:149], v[186:189], v[60:63]
	v_mfma_f32_16x16x32_bf16 v[56:59], v[162:165], v[186:189], v[56:59]
	v_mfma_f32_16x16x32_bf16 v[44:47], v[146:149], v[194:197], v[44:47]
	v_mfma_f32_16x16x32_bf16 v[40:43], v[162:165], v[194:197], v[40:43]
	v_mfma_f32_16x16x32_bf16 v[28:31], v[146:149], v[202:205], v[28:31]
	v_mfma_f32_16x16x32_bf16 v[24:27], v[162:165], v[202:205], v[24:27]
	v_mfma_f32_16x16x32_bf16 v[12:15], v[146:149], v[210:213], v[12:15]
	v_mfma_f32_16x16x32_bf16 v[8:11], v[162:165], v[210:213], v[8:11]
	v_mfma_f32_16x16x32_bf16 v[60:63], v[158:161], v[190:193], v[60:63]
	v_mfma_f32_16x16x32_bf16 v[56:59], v[166:169], v[190:193], v[56:59]
	v_mfma_f32_16x16x32_bf16 v[44:47], v[158:161], v[198:201], v[44:47]
	v_mfma_f32_16x16x32_bf16 v[40:43], v[166:169], v[198:201], v[40:43]
	v_mfma_f32_16x16x32_bf16 v[28:31], v[158:161], v[206:209], v[28:31]
	v_mfma_f32_16x16x32_bf16 v[24:27], v[166:169], v[206:209], v[24:27]
	v_mfma_f32_16x16x32_bf16 v[12:15], v[158:161], v[214:217], v[12:15]
	v_mfma_f32_16x16x32_bf16 v[8:11], v[166:169], v[214:217], v[8:11]
	s_setprio 0
	s_setprio 1
	v_mfma_f32_16x16x32_bf16 v[52:55], v[170:173], v[186:189], v[52:55]
	v_mfma_f32_16x16x32_bf16 v[48:51], v[178:181], v[186:189], v[48:51]
	v_mfma_f32_16x16x32_bf16 v[36:39], v[170:173], v[194:197], v[36:39]
	v_mfma_f32_16x16x32_bf16 v[32:35], v[178:181], v[194:197], v[32:35]
	v_mfma_f32_16x16x32_bf16 v[20:23], v[170:173], v[202:205], v[20:23]
	v_mfma_f32_16x16x32_bf16 v[16:19], v[178:181], v[202:205], v[16:19]
	v_mfma_f32_16x16x32_bf16 v[4:7], v[170:173], v[210:213], v[4:7]
	v_mfma_f32_16x16x32_bf16 v[0:3], v[178:181], v[210:213], v[0:3]
	v_mfma_f32_16x16x32_bf16 v[52:55], v[174:177], v[190:193], v[52:55]
	v_mfma_f32_16x16x32_bf16 v[48:51], v[182:185], v[190:193], v[48:51]
	v_mfma_f32_16x16x32_bf16 v[36:39], v[174:177], v[198:201], v[36:39]
	v_mfma_f32_16x16x32_bf16 v[32:35], v[182:185], v[198:201], v[32:35]
	v_mfma_f32_16x16x32_bf16 v[20:23], v[174:177], v[206:209], v[20:23]
	v_mfma_f32_16x16x32_bf16 v[16:19], v[182:185], v[206:209], v[16:19]
	v_mfma_f32_16x16x32_bf16 v[4:7], v[174:177], v[214:217], v[4:7]
	v_mfma_f32_16x16x32_bf16 v[0:3], v[182:185], v[214:217], v[0:3]
	s_setprio 0
	s_barrier
	s_add_i32 s63, s63, 2
	s_add_u32 s22, s22, 0x100
	s_addc_u32 s23, s23, 0
	s_add_u32 s61, s61, 0x100
	s_addc_u32 s62, s62, 0
	s_cmpk_gt_u32 s63, 0x55
	s_cbranch_scc0 .LBB0_1924
	s_nop 0
	s_and_b64 vcc, exec, s[18:19]
	s_cbranch_vccz .LBB0_1927
	s_barrier
